# hot loop heads (GEMM K-loops, PEER expert loop, attnC loop) aligned to 64 bytes (on top of v66)
# baseline (speedup 1.0000x reference)
.LBB0_272:
	s_and_b32 s2, s8, 0xff
	s_mul_i32 s2, s2, 27
	s_lshr_b32 s2, s2, 9
	s_add_i32 s97, s22, s2
	s_lshl_b32 s14, s97, 19
	v_lshl_add_u64 v[2:3], v[84:85], 0, s[14:15]
	v_add_co_u32_e32 v4, vcc, 0x10000, v2
	s_mul_i32 s2, s2, 19
	s_nop 0
	v_addc_co_u32_e32 v5, vcc, 0, v3, vcc
	v_add_co_u32_e32 v12, vcc, 0x20000, v2
	s_sub_i32 s2, s8, s2
	s_nop 0
	v_addc_co_u32_e32 v13, vcc, 0, v3, vcc
	v_add_co_u32_e32 v14, vcc, 0x30000, v2
	s_and_b32 s9, s2, 0xff
	s_nop 0
	v_addc_co_u32_e32 v15, vcc, 0, v3, vcc
	v_add_co_u32_e32 v24, vcc, 0x40000, v2
	global_load_dwordx4 v[48:51], v[2:3], off
	s_nop 0
	v_addc_co_u32_e32 v25, vcc, 0, v3, vcc
	v_add_co_u32_e32 v26, vcc, 0x50000, v2
	s_lshl_b32 s2, s9, 18
	s_mov_b32 s3, s15
	global_load_dwordx4 v[52:55], v[4:5], off
	global_load_dwordx4 v[56:59], v[12:13], off
	v_addc_co_u32_e32 v27, vcc, 0, v3, vcc
	v_lshl_add_u64 v[0:1], v[82:83], 0, s[2:3]
	v_add_co_u32_e32 v32, vcc, 0x60000, v2
	global_load_dwordx4 v[104:107], v[0:1], off
	s_nop 0
	v_addc_co_u32_e32 v33, vcc, 0, v3, vcc
	global_load_dwordx4 v[60:63], v[14:15], off
	global_load_dwordx4 v[64:67], v[24:25], off
	v_add_co_u32_e32 v34, vcc, 0x70000, v2
	global_load_dwordx4 v[68:71], v[26:27], off
	global_load_dwordx4 v[72:75], v[32:33], off
	v_addc_co_u32_e32 v35, vcc, 0, v3, vcc
	v_add_co_u32_e32 v36, vcc, s33, v0
	global_load_dwordx4 v[76:79], v[34:35], off
	s_nop 0
	v_addc_co_u32_e32 v37, vcc, 0, v1, vcc
	v_add_co_u32_e32 v120, vcc, s57, v0
	global_load_dwordx4 v[108:111], v[36:37], off
	s_nop 0
	v_addc_co_u32_e32 v121, vcc, 0, v1, vcc
	global_load_dwordx4 v[112:115], v[120:121], off
	v_add_co_u32_e32 v122, vcc, s69, v0
	s_mov_b32 s6, 0
	s_nop 0
	v_addc_co_u32_e32 v123, vcc, 0, v1, vcc
	global_load_dwordx4 v[116:119], v[122:123], off
	global_load_dwordx4 v[250:253], v[2:3], off offset:128
	s_nop 0
	global_load_dwordx4 v[246:249], v[4:5], off offset:128
	s_nop 0
	global_load_dwordx4 v[218:221], v[0:1], off offset:128
	global_load_dwordx4 v[242:245], v[12:13], off offset:128
	global_load_dwordx4 v[238:241], v[14:15], off offset:128
	s_nop 0
	global_load_dwordx4 v[234:237], v[24:25], off offset:128
	global_load_dwordx4 v[230:233], v[26:27], off offset:128
	s_nop 0
	global_load_dwordx4 v[226:229], v[32:33], off offset:128
	global_load_dwordx4 v[222:225], v[34:35], off offset:128
	s_nop 0
	global_load_dwordx4 v[214:217], v[36:37], off offset:128
	s_nop 0
	global_load_dwordx4 v[210:213], v[120:121], off offset:128
	v_lshl_add_u64 v[2:3], v[102:103], 0, s[14:15]
	v_accvgpr_write_b32 a47, 0
	v_accvgpr_write_b32 a46, 0
	v_accvgpr_write_b32 a45, 0
	v_accvgpr_write_b32 a44, 0
	v_accvgpr_write_b32 a43, 0
	v_accvgpr_write_b32 a42, 0
	v_accvgpr_write_b32 a41, 0
	v_accvgpr_write_b32 a40, 0
	v_accvgpr_write_b32 a39, 0
	v_accvgpr_write_b32 a38, 0
	v_accvgpr_write_b32 a37, 0
	v_accvgpr_write_b32 a36, 0
	v_accvgpr_write_b32 a35, 0
	v_accvgpr_write_b32 a34, 0
	v_accvgpr_write_b32 a33, 0
	v_accvgpr_write_b32 a32, 0
	v_accvgpr_write_b32 a63, 0
	v_accvgpr_write_b32 a62, 0
	v_accvgpr_write_b32 a61, 0
	v_accvgpr_write_b32 a60, 0
	v_accvgpr_write_b32 a59, 0
	v_accvgpr_write_b32 a58, 0
	v_accvgpr_write_b32 a57, 0
	v_accvgpr_write_b32 a56, 0
	v_accvgpr_write_b32 a55, 0
	v_accvgpr_write_b32 a54, 0
	v_accvgpr_write_b32 a53, 0
	s_waitcnt vmcnt(22)
	ds_write_b128 v146, v[48:51]
	s_waitcnt vmcnt(21)
	ds_write_b128 v146, v[52:55] offset:4608
	s_waitcnt vmcnt(19)
	ds_write_b128 v146, v[104:107] offset:36864
	ds_write_b128 v146, v[56:59] offset:9216
	s_waitcnt vmcnt(18)
	ds_write_b128 v146, v[60:63] offset:13824
	s_waitcnt vmcnt(17)
	ds_write_b128 v146, v[64:67] offset:18432
	s_waitcnt vmcnt(16)
	ds_write_b128 v146, v[68:71] offset:23040
	s_waitcnt vmcnt(15)
	ds_write_b128 v146, v[72:75] offset:27648
	s_waitcnt vmcnt(14)
	ds_write_b128 v146, v[76:79] offset:32256
	s_waitcnt vmcnt(13)
	ds_write_b128 v146, v[108:111] offset:41472
	s_waitcnt vmcnt(12)
	ds_write_b128 v146, v[112:115] offset:46080
	global_load_dwordx4 v[206:209], v[122:123], off offset:128
	v_accvgpr_write_b32 a52, 0
	v_accvgpr_write_b32 a51, 0
	v_accvgpr_write_b32 a50, 0
	v_accvgpr_write_b32 a49, 0
	v_accvgpr_write_b32 a48, 0
	v_accvgpr_write_b32 a79, 0
	v_accvgpr_write_b32 a78, 0
	v_accvgpr_write_b32 a77, 0
	v_accvgpr_write_b32 a76, 0
	v_accvgpr_write_b32 a75, 0
	v_accvgpr_write_b32 a74, 0
	v_accvgpr_write_b32 a73, 0
	v_accvgpr_write_b32 a72, 0
	v_accvgpr_write_b32 a71, 0
	v_accvgpr_write_b32 a70, 0
	v_accvgpr_write_b32 a69, 0
	v_accvgpr_write_b32 a68, 0
	v_accvgpr_write_b32 a67, 0
	v_accvgpr_write_b32 a66, 0
	v_accvgpr_write_b32 a65, 0
	v_accvgpr_write_b32 a64, 0
	v_accvgpr_write_b32 a111, 0
	v_accvgpr_write_b32 a110, 0
	v_accvgpr_write_b32 a109, 0
	v_accvgpr_write_b32 a108, 0
	v_accvgpr_write_b32 a107, 0
	v_accvgpr_write_b32 a106, 0
	v_accvgpr_write_b32 a105, 0
	v_accvgpr_write_b32 a104, 0
	v_accvgpr_write_b32 a103, 0
	v_accvgpr_write_b32 a102, 0
	v_accvgpr_write_b32 a101, 0
	v_accvgpr_write_b32 a100, 0
	v_accvgpr_write_b32 a99, 0
	v_accvgpr_write_b32 a98, 0
	v_accvgpr_write_b32 a97, 0
	v_accvgpr_write_b32 a96, 0
	v_accvgpr_write_b32 a95, 0
	v_accvgpr_write_b32 a94, 0
	v_accvgpr_write_b32 a93, 0
	v_accvgpr_write_b32 a92, 0
	v_accvgpr_write_b32 a91, 0
	v_accvgpr_write_b32 a90, 0
	v_accvgpr_write_b32 a89, 0
	v_accvgpr_write_b32 a88, 0
	v_accvgpr_write_b32 a87, 0
	v_accvgpr_write_b32 a86, 0
	v_accvgpr_write_b32 a85, 0
	v_accvgpr_write_b32 a84, 0
	v_accvgpr_write_b32 a83, 0
	v_accvgpr_write_b32 a82, 0
	v_accvgpr_write_b32 a81, 0
	v_accvgpr_write_b32 a80, 0
	v_accvgpr_write_b32 a127, 0
	v_accvgpr_write_b32 a126, 0
	v_accvgpr_write_b32 a125, 0
	v_accvgpr_write_b32 a124, 0
	v_accvgpr_write_b32 a123, 0
	v_accvgpr_write_b32 a122, 0
	v_accvgpr_write_b32 a121, 0
	v_accvgpr_write_b32 a120, 0
	v_accvgpr_write_b32 a119, 0
	v_accvgpr_write_b32 a118, 0
	v_accvgpr_write_b32 a117, 0
	v_accvgpr_write_b32 a116, 0
	v_accvgpr_write_b32 a115, 0
	v_accvgpr_write_b32 a114, 0
	v_accvgpr_write_b32 a113, 0
	v_accvgpr_write_b32 a112, 0
	v_accvgpr_write_b32 a31, 0
	v_accvgpr_write_b32 a30, 0
	v_accvgpr_write_b32 a29, 0
	v_accvgpr_write_b32 a28, 0
	v_accvgpr_write_b32 a27, 0
	v_accvgpr_write_b32 a26, 0
	v_accvgpr_write_b32 a25, 0
	v_accvgpr_write_b32 a24, 0
	v_accvgpr_write_b32 a23, 0
	v_accvgpr_write_b32 a22, 0
	v_accvgpr_write_b32 a21, 0
	v_accvgpr_write_b32 a20, 0
	v_accvgpr_write_b32 a19, 0
	v_accvgpr_write_b32 a18, 0
	v_accvgpr_write_b32 a17, 0
	v_accvgpr_write_b32 a16, 0
	v_accvgpr_write_b32 a15, 0
	v_accvgpr_write_b32 a14, 0
	v_accvgpr_write_b32 a13, 0
	v_accvgpr_write_b32 a12, 0
	v_accvgpr_write_b32 a11, 0
	v_accvgpr_write_b32 a10, 0
	v_accvgpr_write_b32 a9, 0
	v_accvgpr_write_b32 a8, 0
	v_accvgpr_write_b32 a7, 0
	v_accvgpr_write_b32 a6, 0
	v_accvgpr_write_b32 a5, 0
	v_accvgpr_write_b32 a4, 0
	v_accvgpr_write_b32 a3, 0
	v_accvgpr_write_b32 a2, 0
	v_accvgpr_write_b32 a1, 0
	v_accvgpr_write_b32 a0, 0
	s_mov_b64 s[2:3], 0
	s_waitcnt vmcnt(12)
	ds_write_b128 v146, v[116:119] offset:50688
	s_waitcnt lgkmcnt(0)
	s_barrier
	s_waitcnt vmcnt(0)
	v_readfirstlane_b32 s100, v2
	v_readfirstlane_b32 s101, v3
	v_readfirstlane_b32 s98, v0
	v_readfirstlane_b32 s99, v1
	s_nop 1
	v_subrev_u32_e32 v194, s100, v2
	v_subrev_u32_e32 v193, s98, v0
	v_add_u32_e32 v254, 0x126fa000, v194
	v_add_u32_e32 v205, 0x1270a000, v194
	v_add_u32_e32 v204, 0x1271a000, v194
	v_add_u32_e32 v203, 0x1272a000, v194
	v_add_u32_e32 v202, 0x1273a000, v194
	v_add_u32_e32 v201, 0x1274a000, v194
	v_add_u32_e32 v200, 0x1275a000, v194
	v_add_u32_e32 v199, 0x1276a000, v194
	v_mov_b32_e32 v198, v193
	v_add_u32_e32 v197, s33, v193
	v_add_u32_e32 v196, s57, v193
	v_add_u32_e32 v195, s69, v193
	s_add_u32 s100, s100, s2
	s_addc_u32 s101, s101, s3
	s_add_u32 s98, s98, s2
	s_addc_u32 s99, s99, s3
	v_add_u32_e32 v192, v148, v147
	v_add_u32_e32 v191, v148, v150
	v_add_u32_e32 v190, v148, v151
	s_and_b32 s7, s6, 1
	s_mul_i32 s14, s7, 0xd800
	v_add_u32_e32 v189, s14, v192
	v_add_u32_e32 v188, s14, v191
	v_add_u32_e32 v187, s14, v190
	ds_read_b128 v[52:55], v189
	ds_read_b128 v[4:7], v187 offset:36864
	ds_read_b128 v[56:59], v189 offset:4608
	ds_read_b128 v[8:11], v187 offset:41472
	ds_read_b128 v[60:63], v189 offset:9216
	ds_read_b128 v[64:67], v188
	s_getreg_b32 s7, hwreg(HW_REG_HW_ID, 4, 1)
	s_cmp_lg_u32 s7, 0
	s_cbranch_scc1 xg5_varB_1
	.p2align 6
.LBB0_273:
	s_and_b32 s7, s6, 1
	s_mul_i32 s14, s7, 0xd800
	s_xor_b32 s7, s7, 1
	s_mul_i32 s7, s7, 0xd800
	s_add_i32 s6, s6, 1
	v_add_u32_e32 v186, s7, v146
	ds_read_b128 v[12:15], v189 offset:32
	ds_read_b128 v[24:27], v187 offset:36896
	ds_read_b128 v[16:19], v189 offset:4640
	ds_read_b128 v[28:31], v187 offset:41504
	ds_read_b128 v[20:23], v189 offset:9248
	ds_read_b128 v[48:51], v188 offset:32
	s_waitcnt lgkmcnt(10)
	v_mfma_f32_32x32x16_bf16 a[32:47], v[52:55], v[4:7], a[32:47]
	s_waitcnt vmcnt(11)
	ds_write_b128 v186, v[250:253]
	s_waitcnt lgkmcnt(9)
	v_mfma_f32_32x32x16_bf16 a[48:63], v[52:55], v[8:11], a[48:63]
	s_waitcnt vmcnt(10)
	ds_write_b128 v186, v[246:249] offset:4608
	global_load_dwordx4 v[250:253], v254, s[100:101] offset:512
	v_mfma_f32_32x32x16_bf16 a[64:79], v[56:59], v[4:7], a[64:79]
	s_waitcnt vmcnt(10)
	ds_write_b128 v186, v[242:245] offset:9216
	global_load_dwordx4 v[246:249], v205, s[100:101] offset:512
	v_mfma_f32_32x32x16_bf16 a[96:111], v[56:59], v[8:11], a[96:111]
	s_waitcnt vmcnt(10)
	ds_write_b128 v186, v[238:241] offset:13824
	global_load_dwordx4 v[242:245], v204, s[100:101] offset:512
	s_waitcnt lgkmcnt(11)
	v_mfma_f32_32x32x16_bf16 a[80:95], v[60:63], v[4:7], a[80:95]
	s_waitcnt vmcnt(10)
	ds_write_b128 v186, v[234:237] offset:18432
	global_load_dwordx4 v[238:241], v203, s[100:101] offset:512
	v_mfma_f32_32x32x16_bf16 a[112:127], v[60:63], v[8:11], a[112:127]
	s_waitcnt vmcnt(10)
	ds_write_b128 v186, v[230:233] offset:23040
	global_load_dwordx4 v[234:237], v202, s[100:101] offset:512
	s_waitcnt lgkmcnt(12)
	v_mfma_f32_32x32x16_bf16 a[16:31], v[64:67], v[4:7], a[16:31]
	s_waitcnt vmcnt(10)
	ds_write_b128 v186, v[226:229] offset:27648
	global_load_dwordx4 v[230:233], v201, s[100:101] offset:512
	v_mfma_f32_32x32x16_bf16 a[0:15], v[64:67], v[8:11], a[0:15]
	s_waitcnt vmcnt(10)
	ds_write_b128 v186, v[222:225] offset:32256
	global_load_dwordx4 v[226:229], v200, s[100:101] offset:512
	ds_read_b128 v[52:55], v189 offset:64
	ds_read_b128 v[4:7], v187 offset:36928
	ds_read_b128 v[56:59], v189 offset:4672
	ds_read_b128 v[8:11], v187 offset:41536
	ds_read_b128 v[60:63], v189 offset:9280
	ds_read_b128 v[64:67], v188 offset:64
	s_waitcnt lgkmcnt(15)
	v_mfma_f32_32x32x16_bf16 a[32:47], v[12:15], v[24:27], a[32:47]
	s_waitcnt vmcnt(10)
	ds_write_b128 v186, v[218:221] offset:36864
	global_load_dwordx4 v[222:225], v199, s[100:101] offset:512
	v_mfma_f32_32x32x16_bf16 a[48:63], v[12:15], v[28:31], a[48:63]
	s_waitcnt vmcnt(10)
	ds_write_b128 v186, v[214:217] offset:41472
	global_load_dwordx4 v[218:221], v198, s[98:99] offset:256
	v_mfma_f32_32x32x16_bf16 a[64:79], v[16:19], v[24:27], a[64:79]
	s_waitcnt vmcnt(10)
	ds_write_b128 v186, v[210:213] offset:46080
	global_load_dwordx4 v[214:217], v197, s[98:99] offset:256
	v_mfma_f32_32x32x16_bf16 a[96:111], v[16:19], v[28:31], a[96:111]
	s_waitcnt vmcnt(10)
	ds_write_b128 v186, v[206:209] offset:50688
	global_load_dwordx4 v[210:213], v196, s[98:99] offset:256
	v_mfma_f32_32x32x16_bf16 a[80:95], v[20:23], v[24:27], a[80:95]
	global_load_dwordx4 v[206:209], v195, s[98:99] offset:256
	s_add_u32 s100, s100, 0x80
	s_addc_u32 s101, s101, 0
	s_add_u32 s98, s98, 0x80
	s_addc_u32 s99, s99, 0
	v_mfma_f32_32x32x16_bf16 a[112:127], v[20:23], v[28:31], a[112:127]
	s_waitcnt lgkmcnt(15)
	v_mfma_f32_32x32x16_bf16 a[16:31], v[48:51], v[24:27], a[16:31]
	v_mfma_f32_32x32x16_bf16 a[0:15], v[48:51], v[28:31], a[0:15]
	ds_read_b128 v[12:15], v189 offset:96
	ds_read_b128 v[24:27], v187 offset:36960
	ds_read_b128 v[16:19], v189 offset:4704
	ds_read_b128 v[28:31], v187 offset:41568
	ds_read_b128 v[20:23], v189 offset:9312
	ds_read_b128 v[48:51], v188 offset:96
	s_waitcnt lgkmcnt(14)
	v_mfma_f32_32x32x16_bf16 a[32:47], v[52:55], v[4:7], a[32:47]
	s_waitcnt lgkmcnt(12)
	v_mfma_f32_32x32x16_bf16 a[48:63], v[52:55], v[8:11], a[48:63]
	v_mfma_f32_32x32x16_bf16 a[64:79], v[56:59], v[4:7], a[64:79]
	v_mfma_f32_32x32x16_bf16 a[96:111], v[56:59], v[8:11], a[96:111]
	s_waitcnt lgkmcnt(11)
	v_mfma_f32_32x32x16_bf16 a[80:95], v[60:63], v[4:7], a[80:95]
	v_mfma_f32_32x32x16_bf16 a[112:127], v[60:63], v[8:11], a[112:127]
	s_waitcnt lgkmcnt(10)
	v_mfma_f32_32x32x16_bf16 a[16:31], v[64:67], v[4:7], a[16:31]
	v_mfma_f32_32x32x16_bf16 a[0:15], v[64:67], v[8:11], a[0:15]
	s_waitcnt lgkmcnt(0)
	v_mfma_f32_32x32x16_bf16 a[32:47], v[12:15], v[24:27], a[32:47]
	v_mfma_f32_32x32x16_bf16 a[48:63], v[12:15], v[28:31], a[48:63]
	v_mfma_f32_32x32x16_bf16 a[64:79], v[16:19], v[24:27], a[64:79]
	v_mfma_f32_32x32x16_bf16 a[96:111], v[16:19], v[28:31], a[96:111]
	s_barrier
	v_add_u32_e32 v189, s7, v192
	v_add_u32_e32 v188, s7, v191
	v_add_u32_e32 v187, s7, v190
	ds_read_b128 v[52:55], v189
	ds_read_b128 v[4:7], v187 offset:36864
	ds_read_b128 v[56:59], v189 offset:4608
	ds_read_b128 v[8:11], v187 offset:41472
	ds_read_b128 v[60:63], v189 offset:9216
	ds_read_b128 v[64:67], v188
	v_mfma_f32_32x32x16_bf16 a[80:95], v[20:23], v[24:27], a[80:95]
	v_mfma_f32_32x32x16_bf16 a[112:127], v[20:23], v[28:31], a[112:127]
	v_mfma_f32_32x32x16_bf16 a[16:31], v[48:51], v[24:27], a[16:31]
	v_mfma_f32_32x32x16_bf16 a[0:15], v[48:51], v[28:31], a[0:15]
	s_add_u32 s2, s2, 0x80
	s_addc_u32 s3, s3, 0
	s_cmpk_lg_i32 s2, 0x700
	s_cbranch_scc1 .LBB0_273
	s_branch xg5_tail_1
	.p2align 6

.LBB0_777:
	s_lshr_b32 s50, s49, 3
	s_lshl_b32 s44, s50, 18
	s_add_i32 s44, s70, s44
	v_lshl_add_u64 v[10:11], s[44:45], 1, v[8:9]
	s_and_b32 s44, s48, 7
	s_lshl_b32 s44, s44, 18
	s_add_i32 s50, s50, s67
	v_lshl_add_u64 v[12:13], v[8:9], 0, s[44:45]
	s_lshl_b32 s44, s50, 19
	v_lshl_add_u64 v[14:15], v[2:3], 0, s[44:45]
	v_add_co_u32_e32 v16, vcc, s71, v14
	s_mov_b32 s44, 0x40000
	s_nop 0
	v_addc_co_u32_e32 v17, vcc, 0, v15, vcc
	v_add_co_u32_e32 v18, vcc, s72, v14
	s_and_b32 s51, s49, 7
	s_nop 0
	v_addc_co_u32_e32 v19, vcc, 0, v15, vcc
	v_add_co_u32_e32 v76, vcc, s73, v14
	global_load_dwordx4 v[108:111], v[14:15], off
	global_load_dwordx4 v[112:115], v[16:17], off
	v_addc_co_u32_e32 v77, vcc, 0, v15, vcc
	v_add_co_u32_e32 v78, vcc, s44, v14
	s_lshl_b32 s44, s51, 18
	s_nop 0
	v_addc_co_u32_e32 v79, vcc, 0, v15, vcc
	v_add_co_u32_e32 v80, vcc, s74, v14
	v_lshl_add_u64 v[90:91], v[4:5], 0, s[44:45]
	s_nop 0
	v_addc_co_u32_e32 v81, vcc, 0, v15, vcc
	v_add_co_u32_e32 v82, vcc, s75, v14
	global_load_dwordx4 v[116:119], v[18:19], off
	global_load_dwordx4 v[120:123], v[76:77], off
	v_addc_co_u32_e32 v83, vcc, 0, v15, vcc
	v_add_co_u32_e32 v88, vcc, s76, v14
	global_load_dwordx4 v[124:127], v[78:79], off
	global_load_dwordx4 v[128:131], v[80:81], off
	v_addc_co_u32_e32 v89, vcc, 0, v15, vcc
	v_add_co_u32_e32 v92, vcc, s71, v90
	global_load_dwordx4 v[136:139], v[82:83], off
	global_load_dwordx4 v[140:143], v[88:89], off
	v_addc_co_u32_e32 v93, vcc, 0, v91, vcc
	v_add_co_u32_e32 v104, vcc, s72, v90
	global_load_dwordx4 v[144:147], v[90:91], off
	global_load_dwordx4 v[148:151], v[92:93], off
	v_addc_co_u32_e32 v105, vcc, 0, v91, vcc
	v_add_co_u32_e32 v106, vcc, s73, v90
	global_load_dwordx4 v[152:155], v[104:105], off
	s_nop 0
	v_addc_co_u32_e32 v107, vcc, 0, v91, vcc
	global_load_dwordx4 v[156:159], v[106:107], off
	global_load_dwordx4 v[250:253], v[14:15], off offset:128
	global_load_dwordx4 v[246:249], v[16:17], off offset:128
	global_load_dwordx4 v[242:245], v[18:19], off offset:128
	s_nop 0
	global_load_dwordx4 v[238:241], v[76:77], off offset:128
	global_load_dwordx4 v[234:237], v[78:79], off offset:128
	global_load_dwordx4 v[230:233], v[80:81], off offset:128
	s_nop 0
	global_load_dwordx4 v[226:229], v[82:83], off offset:128
	s_nop 0
	global_load_dwordx4 v[222:225], v[88:89], off offset:128
	global_load_dwordx4 v[218:221], v[90:91], off offset:128
	s_nop 0
	global_load_dwordx4 v[214:217], v[92:93], off offset:128
	s_nop 0
	global_load_dwordx4 v[210:213], v[104:105], off offset:128
	s_nop 0
	global_load_dwordx4 v[206:209], v[106:107], off offset:128
	s_mov_b32 s44, 0
	v_accvgpr_write_b32 a47, 0
	v_accvgpr_write_b32 a46, 0
	v_accvgpr_write_b32 a45, 0
	v_accvgpr_write_b32 a44, 0
	v_accvgpr_write_b32 a43, 0
	v_accvgpr_write_b32 a42, 0
	v_accvgpr_write_b32 a41, 0
	v_accvgpr_write_b32 a40, 0
	v_accvgpr_write_b32 a39, 0
	v_accvgpr_write_b32 a38, 0
	v_accvgpr_write_b32 a37, 0
	v_accvgpr_write_b32 a36, 0
	v_accvgpr_write_b32 a35, 0
	v_accvgpr_write_b32 a34, 0
	v_accvgpr_write_b32 a33, 0
	v_accvgpr_write_b32 a32, 0
	v_accvgpr_write_b32 a63, 0
	v_accvgpr_write_b32 a62, 0
	v_accvgpr_write_b32 a61, 0
	v_accvgpr_write_b32 a60, 0
	v_accvgpr_write_b32 a59, 0
	v_accvgpr_write_b32 a58, 0
	v_accvgpr_write_b32 a57, 0
	v_accvgpr_write_b32 a56, 0
	v_accvgpr_write_b32 a55, 0
	v_accvgpr_write_b32 a54, 0
	v_accvgpr_write_b32 a53, 0
	v_accvgpr_write_b32 a52, 0
	v_accvgpr_write_b32 a51, 0
	v_accvgpr_write_b32 a50, 0
	v_accvgpr_write_b32 a49, 0
	v_accvgpr_write_b32 a48, 0
	v_accvgpr_write_b32 a79, 0
	v_accvgpr_write_b32 a78, 0
	v_accvgpr_write_b32 a77, 0
	v_accvgpr_write_b32 a76, 0
	v_accvgpr_write_b32 a75, 0
	v_accvgpr_write_b32 a74, 0
	v_accvgpr_write_b32 a73, 0
	v_accvgpr_write_b32 a72, 0
	v_accvgpr_write_b32 a71, 0
	v_accvgpr_write_b32 a70, 0
	v_accvgpr_write_b32 a69, 0
	v_accvgpr_write_b32 a68, 0
	v_accvgpr_write_b32 a67, 0
	v_accvgpr_write_b32 a66, 0
	v_accvgpr_write_b32 a65, 0
	v_accvgpr_write_b32 a64, 0
	v_accvgpr_write_b32 a111, 0
	v_accvgpr_write_b32 a110, 0
	v_accvgpr_write_b32 a109, 0
	v_accvgpr_write_b32 a108, 0
	v_accvgpr_write_b32 a107, 0
	v_accvgpr_write_b32 a106, 0
	v_accvgpr_write_b32 a105, 0
	v_accvgpr_write_b32 a104, 0
	v_accvgpr_write_b32 a103, 0
	v_accvgpr_write_b32 a102, 0
	v_accvgpr_write_b32 a101, 0
	v_accvgpr_write_b32 a100, 0
	v_accvgpr_write_b32 a99, 0
	v_accvgpr_write_b32 a98, 0
	v_accvgpr_write_b32 a97, 0
	v_accvgpr_write_b32 a96, 0
	v_accvgpr_write_b32 a95, 0
	v_accvgpr_write_b32 a94, 0
	v_accvgpr_write_b32 a93, 0
	v_accvgpr_write_b32 a92, 0
	v_accvgpr_write_b32 a91, 0
	v_accvgpr_write_b32 a90, 0
	v_accvgpr_write_b32 a89, 0
	v_accvgpr_write_b32 a88, 0
	v_accvgpr_write_b32 a87, 0
	v_accvgpr_write_b32 a86, 0
	v_accvgpr_write_b32 a85, 0
	v_accvgpr_write_b32 a84, 0
	v_accvgpr_write_b32 a83, 0
	v_accvgpr_write_b32 a82, 0
	v_accvgpr_write_b32 a81, 0
	v_accvgpr_write_b32 a80, 0
	v_accvgpr_write_b32 a127, 0
	v_accvgpr_write_b32 a126, 0
	v_accvgpr_write_b32 a125, 0
	v_accvgpr_write_b32 a124, 0
	v_accvgpr_write_b32 a123, 0
	v_accvgpr_write_b32 a122, 0
	v_accvgpr_write_b32 a121, 0
	v_accvgpr_write_b32 a120, 0
	v_accvgpr_write_b32 a119, 0
	v_accvgpr_write_b32 a118, 0
	v_accvgpr_write_b32 a117, 0
	v_accvgpr_write_b32 a116, 0
	v_accvgpr_write_b32 a115, 0
	v_accvgpr_write_b32 a114, 0
	v_accvgpr_write_b32 a113, 0
	v_accvgpr_write_b32 a112, 0
	v_accvgpr_write_b32 a31, 0
	v_accvgpr_write_b32 a30, 0
	v_accvgpr_write_b32 a29, 0
	v_accvgpr_write_b32 a28, 0
	v_accvgpr_write_b32 a27, 0
	v_accvgpr_write_b32 a26, 0
	v_accvgpr_write_b32 a25, 0
	v_accvgpr_write_b32 a24, 0
	v_accvgpr_write_b32 a23, 0
	v_accvgpr_write_b32 a22, 0
	v_accvgpr_write_b32 a21, 0
	v_accvgpr_write_b32 a20, 0
	v_accvgpr_write_b32 a19, 0
	v_accvgpr_write_b32 a18, 0
	v_accvgpr_write_b32 a17, 0
	v_accvgpr_write_b32 a16, 0
	v_accvgpr_write_b32 a15, 0
	v_accvgpr_write_b32 a14, 0
	v_accvgpr_write_b32 a13, 0
	v_accvgpr_write_b32 a12, 0
	v_accvgpr_write_b32 a11, 0
	v_accvgpr_write_b32 a10, 0
	v_accvgpr_write_b32 a9, 0
	v_accvgpr_write_b32 a8, 0
	v_accvgpr_write_b32 a7, 0
	v_accvgpr_write_b32 a6, 0
	v_accvgpr_write_b32 a5, 0
	v_accvgpr_write_b32 a4, 0
	v_accvgpr_write_b32 a3, 0
	v_accvgpr_write_b32 a2, 0
	v_accvgpr_write_b32 a1, 0
	v_accvgpr_write_b32 a0, 0
	s_mov_b64 s[46:47], 0
	s_waitcnt vmcnt(23)
	ds_write_b128 v45, v[108:111]
	s_waitcnt vmcnt(22)
	ds_write_b128 v45, v[112:115] offset:4608
	s_waitcnt vmcnt(21)
	ds_write_b128 v45, v[116:119] offset:9216
	s_waitcnt vmcnt(20)
	ds_write_b128 v45, v[120:123] offset:13824
	s_waitcnt vmcnt(19)
	ds_write_b128 v45, v[124:127] offset:18432
	s_waitcnt vmcnt(18)
	ds_write_b128 v45, v[128:131] offset:23040
	s_waitcnt vmcnt(17)
	ds_write_b128 v45, v[136:139] offset:27648
	s_waitcnt vmcnt(16)
	ds_write_b128 v45, v[140:143] offset:32256
	s_waitcnt vmcnt(15)
	ds_write_b128 v45, v[144:147] offset:36864
	s_waitcnt vmcnt(14)
	ds_write_b128 v45, v[148:151] offset:41472
	s_waitcnt vmcnt(13)
	ds_write_b128 v45, v[152:155] offset:46080
	s_waitcnt vmcnt(12)
	ds_write_b128 v45, v[156:159] offset:50688
	s_waitcnt lgkmcnt(0)
	s_barrier
	s_waitcnt vmcnt(0)
	v_readfirstlane_b32 s100, v10
	v_readfirstlane_b32 s101, v11
	v_readfirstlane_b32 s98, v12
	v_readfirstlane_b32 s99, v13
	s_nop 1
	v_subrev_u32_e32 v194, s100, v10
	v_subrev_u32_e32 v193, s98, v12
	v_add_u32_e32 v254, s77, v194
	v_add_u32_e32 v205, s80, v194
	v_add_u32_e32 v204, s81, v194
	v_add_u32_e32 v203, s82, v194
	v_add_u32_e32 v202, s83, v194
	v_add_u32_e32 v201, s84, v194
	v_add_u32_e32 v200, s85, v194
	v_add_u32_e32 v199, s86, v194
	v_add_u32_e32 v198, s87, v193
	v_add_u32_e32 v197, s88, v193
	v_add_u32_e32 v196, s89, v193
	v_add_u32_e32 v195, s90, v193
	s_add_u32 s100, s100, s46
	s_addc_u32 s101, s101, s47
	s_add_u32 s98, s98, s46
	s_addc_u32 s99, s99, s47
	v_add_u32_e32 v192, v20, v46
	v_add_u32_e32 v191, v20, v47
	v_add_u32_e32 v190, v20, v48
	s_and_b32 s52, s44, 1
	s_mul_i32 s53, s52, 0xd800
	v_add_u32_e32 v189, s53, v192
	v_add_u32_e32 v188, s53, v191
	v_add_u32_e32 v187, s53, v190
	ds_read_b128 v[108:111], v189
	ds_read_b128 v[14:17], v187 offset:36864
	ds_read_b128 v[112:115], v189 offset:4608
	ds_read_b128 v[64:67], v187 offset:41472
	ds_read_b128 v[116:119], v189 offset:9216
	ds_read_b128 v[120:123], v188
	s_getreg_b32 s52, hwreg(HW_REG_HW_ID, 4, 1)
	s_cmp_lg_u32 s52, 0
	s_cbranch_scc1 xg5_varB_2
	.p2align 6
.LBB0_778:
	s_and_b32 s52, s44, 1
	s_mul_i32 s53, s52, 0xd800
	s_xor_b32 s52, s52, 1
	s_mul_i32 s52, s52, 0xd800
	s_add_i32 s44, s44, 1
	v_add_u32_e32 v186, s52, v45
	ds_read_b128 v[68:71], v189 offset:32
	ds_read_b128 v[80:83], v187 offset:36896
	ds_read_b128 v[72:75], v189 offset:4640
	ds_read_b128 v[84:87], v187 offset:41504
	ds_read_b128 v[76:79], v189 offset:9248
	ds_read_b128 v[104:107], v188 offset:32
	s_waitcnt lgkmcnt(10)
	v_mfma_f32_32x32x16_bf16 a[32:47], v[108:111], v[14:17], a[32:47]
	s_waitcnt vmcnt(11)
	ds_write_b128 v186, v[250:253]
	s_waitcnt lgkmcnt(9)
	v_mfma_f32_32x32x16_bf16 a[48:63], v[108:111], v[64:67], a[48:63]
	s_waitcnt vmcnt(10)
	ds_write_b128 v186, v[246:249] offset:4608
	global_load_dwordx4 v[250:253], v254, s[100:101] offset:512
	v_mfma_f32_32x32x16_bf16 a[64:79], v[112:115], v[14:17], a[64:79]
	s_waitcnt vmcnt(10)
	ds_write_b128 v186, v[242:245] offset:9216
	global_load_dwordx4 v[246:249], v205, s[100:101] offset:512
	v_mfma_f32_32x32x16_bf16 a[96:111], v[112:115], v[64:67], a[96:111]
	s_waitcnt vmcnt(10)
	ds_write_b128 v186, v[238:241] offset:13824
	global_load_dwordx4 v[242:245], v204, s[100:101] offset:512
	s_waitcnt lgkmcnt(11)
	v_mfma_f32_32x32x16_bf16 a[80:95], v[116:119], v[14:17], a[80:95]
	s_waitcnt vmcnt(10)
	ds_write_b128 v186, v[234:237] offset:18432
	global_load_dwordx4 v[238:241], v203, s[100:101] offset:512
	v_mfma_f32_32x32x16_bf16 a[112:127], v[116:119], v[64:67], a[112:127]
	s_waitcnt vmcnt(10)
	ds_write_b128 v186, v[230:233] offset:23040
	global_load_dwordx4 v[234:237], v202, s[100:101] offset:512
	s_waitcnt lgkmcnt(12)
	v_mfma_f32_32x32x16_bf16 a[16:31], v[120:123], v[14:17], a[16:31]
	s_waitcnt vmcnt(10)
	ds_write_b128 v186, v[226:229] offset:27648
	global_load_dwordx4 v[230:233], v201, s[100:101] offset:512
	v_mfma_f32_32x32x16_bf16 a[0:15], v[120:123], v[64:67], a[0:15]
	s_waitcnt vmcnt(10)
	ds_write_b128 v186, v[222:225] offset:32256
	global_load_dwordx4 v[226:229], v200, s[100:101] offset:512
	ds_read_b128 v[108:111], v189 offset:64
	ds_read_b128 v[14:17], v187 offset:36928
	ds_read_b128 v[112:115], v189 offset:4672
	ds_read_b128 v[64:67], v187 offset:41536
	ds_read_b128 v[116:119], v189 offset:9280
	ds_read_b128 v[120:123], v188 offset:64
	s_waitcnt lgkmcnt(15)
	v_mfma_f32_32x32x16_bf16 a[32:47], v[68:71], v[80:83], a[32:47]
	s_waitcnt vmcnt(10)
	ds_write_b128 v186, v[218:221] offset:36864
	global_load_dwordx4 v[222:225], v199, s[100:101] offset:512
	v_mfma_f32_32x32x16_bf16 a[48:63], v[68:71], v[84:87], a[48:63]
	s_waitcnt vmcnt(10)
	ds_write_b128 v186, v[214:217] offset:41472
	global_load_dwordx4 v[218:221], v198, s[98:99] offset:256
	v_mfma_f32_32x32x16_bf16 a[64:79], v[72:75], v[80:83], a[64:79]
	s_waitcnt vmcnt(10)
	ds_write_b128 v186, v[210:213] offset:46080
	global_load_dwordx4 v[214:217], v197, s[98:99] offset:256
	v_mfma_f32_32x32x16_bf16 a[96:111], v[72:75], v[84:87], a[96:111]
	s_waitcnt vmcnt(10)
	ds_write_b128 v186, v[206:209] offset:50688
	global_load_dwordx4 v[210:213], v196, s[98:99] offset:256
	v_mfma_f32_32x32x16_bf16 a[80:95], v[76:79], v[80:83], a[80:95]
	global_load_dwordx4 v[206:209], v195, s[98:99] offset:256
	s_add_u32 s100, s100, 0x80
	s_addc_u32 s101, s101, 0
	s_add_u32 s98, s98, 0x80
	s_addc_u32 s99, s99, 0
	v_mfma_f32_32x32x16_bf16 a[112:127], v[76:79], v[84:87], a[112:127]
	s_waitcnt lgkmcnt(15)
	v_mfma_f32_32x32x16_bf16 a[16:31], v[104:107], v[80:83], a[16:31]
	v_mfma_f32_32x32x16_bf16 a[0:15], v[104:107], v[84:87], a[0:15]
	ds_read_b128 v[68:71], v189 offset:96
	ds_read_b128 v[80:83], v187 offset:36960
	ds_read_b128 v[72:75], v189 offset:4704
	ds_read_b128 v[84:87], v187 offset:41568
	ds_read_b128 v[76:79], v189 offset:9312
	ds_read_b128 v[104:107], v188 offset:96
	s_waitcnt lgkmcnt(14)
	v_mfma_f32_32x32x16_bf16 a[32:47], v[108:111], v[14:17], a[32:47]
	s_waitcnt lgkmcnt(12)
	v_mfma_f32_32x32x16_bf16 a[48:63], v[108:111], v[64:67], a[48:63]
	v_mfma_f32_32x32x16_bf16 a[64:79], v[112:115], v[14:17], a[64:79]
	v_mfma_f32_32x32x16_bf16 a[96:111], v[112:115], v[64:67], a[96:111]
	s_waitcnt lgkmcnt(11)
	v_mfma_f32_32x32x16_bf16 a[80:95], v[116:119], v[14:17], a[80:95]
	v_mfma_f32_32x32x16_bf16 a[112:127], v[116:119], v[64:67], a[112:127]
	s_waitcnt lgkmcnt(10)
	v_mfma_f32_32x32x16_bf16 a[16:31], v[120:123], v[14:17], a[16:31]
	v_mfma_f32_32x32x16_bf16 a[0:15], v[120:123], v[64:67], a[0:15]
	s_waitcnt lgkmcnt(0)
	v_mfma_f32_32x32x16_bf16 a[32:47], v[68:71], v[80:83], a[32:47]
	v_mfma_f32_32x32x16_bf16 a[48:63], v[68:71], v[84:87], a[48:63]
	v_mfma_f32_32x32x16_bf16 a[64:79], v[72:75], v[80:83], a[64:79]
	v_mfma_f32_32x32x16_bf16 a[96:111], v[72:75], v[84:87], a[96:111]
	s_barrier
	v_add_u32_e32 v189, s52, v192
	v_add_u32_e32 v188, s52, v191
	v_add_u32_e32 v187, s52, v190
	ds_read_b128 v[108:111], v189
	ds_read_b128 v[14:17], v187 offset:36864
	ds_read_b128 v[112:115], v189 offset:4608
	ds_read_b128 v[64:67], v187 offset:41472
	ds_read_b128 v[116:119], v189 offset:9216
	ds_read_b128 v[120:123], v188
	v_mfma_f32_32x32x16_bf16 a[80:95], v[76:79], v[80:83], a[80:95]
	v_mfma_f32_32x32x16_bf16 a[112:127], v[76:79], v[84:87], a[112:127]
	v_mfma_f32_32x32x16_bf16 a[16:31], v[104:107], v[80:83], a[16:31]
	v_mfma_f32_32x32x16_bf16 a[0:15], v[104:107], v[84:87], a[0:15]
	s_add_u32 s46, s46, 0x80
	s_addc_u32 s47, s47, 0
	s_cmpk_lg_i32 s46, 0x700
	s_cbranch_scc1 .LBB0_778
	s_branch xg5_tail_2
	.p2align 6

.LBB0_902:
	s_add_i32 s58, s26, 16
	s_cmpk_gt_u32 s26, 0x6f
	s_cselect_b64 s[24:25], -1, 0
	s_cmpk_lt_u32 s26, 0x70
	s_cselect_b64 vcc, -1, 0
	s_bitcmp0_b32 s58, 6
	s_cselect_b64 s[10:11], -1, 0
	v_cndmask_b32_e64 v100, v116, v102, s[10:11]
	v_cndmask_b32_e32 v100, v118, v100, vcc
	s_nop 0
	v_readlane_b32 s28, v100, s58
	s_nop 1
	v_mad_i64_i32 v[148:149], s[10:11], s28, v130, v[96:97]
	global_load_dwordx4 a[20:23], v[148:149], off
	v_mad_i64_i32 v[148:149], s[10:11], s28, v130, v[98:99]
	s_add_i32 s10, s26, 17
	global_load_dwordx2 a[42:43], v[148:149], off
	s_nop 1
	v_readlane_b32 s28, v100, s10
	s_nop 1
	v_mad_i64_i32 v[148:149], s[10:11], s28, v130, v[96:97]
	global_load_dwordx4 a[24:27], v[148:149], off
	v_mad_i64_i32 v[148:149], s[10:11], s28, v130, v[98:99]
	s_add_i32 s10, s26, 18
	global_load_dwordx2 a[44:45], v[148:149], off
	s_nop 1
	v_readlane_b32 s28, v100, s10
	s_nop 1
	v_mad_i64_i32 v[148:149], s[10:11], s28, v130, v[96:97]
	global_load_dwordx4 a[28:31], v[148:149], off
	v_mad_i64_i32 v[148:149], s[10:11], s28, v130, v[98:99]
	s_add_i32 s10, s26, 19
	global_load_dwordx2 a[46:47], v[148:149], off
	s_nop 1
	v_readlane_b32 s28, v100, s10
	s_nop 1
	v_mad_i64_i32 v[148:149], s[10:11], s28, v130, v[96:97]
	global_load_dwordx4 v[232:235], v[148:149], off
	v_mad_i64_i32 v[148:149], s[10:11], s28, v130, v[98:99]
	s_add_i32 s10, s26, 20
	global_load_dwordx2 a[48:49], v[148:149], off
	s_nop 1
	v_readlane_b32 s28, v100, s10
	s_nop 1
	v_mad_i64_i32 v[148:149], s[10:11], s28, v130, v[96:97]
	global_load_dwordx4 v[236:239], v[148:149], off
	v_mad_i64_i32 v[148:149], s[10:11], s28, v130, v[98:99]
	s_add_i32 s10, s26, 21
	global_load_dwordx2 a[50:51], v[148:149], off
	s_nop 1
	v_readlane_b32 s28, v100, s10
	s_nop 1
	v_mad_i64_i32 v[148:149], s[10:11], s28, v130, v[96:97]
	global_load_dwordx4 v[240:243], v[148:149], off
	v_mad_i64_i32 v[148:149], s[10:11], s28, v130, v[98:99]
	s_add_i32 s10, s26, 22
	global_load_dwordx2 a[52:53], v[148:149], off
	s_nop 1
	v_readlane_b32 s28, v100, s10
	s_nop 1
	v_mad_i64_i32 v[148:149], s[10:11], s28, v130, v[96:97]
	global_load_dwordx4 v[244:247], v[148:149], off
	v_mad_i64_i32 v[148:149], s[10:11], s28, v130, v[98:99]
	s_add_i32 s10, s26, 23
	global_load_dwordx2 a[54:55], v[148:149], off
	s_nop 1
	v_readlane_b32 s28, v100, s10
	s_nop 1
	v_mad_i64_i32 v[148:149], s[10:11], s28, v130, v[96:97]
	global_load_dwordx4 v[248:251], v[148:149], off
	v_mad_i64_i32 v[148:149], s[10:11], s28, v130, v[98:99]
	s_add_i32 s10, s26, 24
	global_load_dwordx2 a[56:57], v[148:149], off
	s_nop 1
	v_readlane_b32 s28, v100, s10
	s_nop 1
	v_mad_i64_i32 v[148:149], s[10:11], s28, v130, v[96:97]
	global_load_dwordx4 a[0:3], v[148:149], off
	v_mad_i64_i32 v[148:149], s[10:11], s28, v130, v[98:99]
	s_add_i32 s10, s26, 25
	global_load_dwordx2 a[58:59], v[148:149], off
	s_nop 1
	v_readlane_b32 s28, v100, s10
	s_nop 1
	v_mad_i64_i32 v[148:149], s[10:11], s28, v130, v[96:97]
	global_load_dwordx4 a[4:7], v[148:149], off
	v_mad_i64_i32 v[148:149], s[10:11], s28, v130, v[98:99]
	s_add_i32 s10, s26, 26
	global_load_dwordx2 a[60:61], v[148:149], off
	s_nop 1
	v_readlane_b32 s28, v100, s10
	s_nop 1
	v_mad_i64_i32 v[148:149], s[10:11], s28, v130, v[96:97]
	global_load_dwordx4 a[8:11], v[148:149], off
	v_mad_i64_i32 v[148:149], s[10:11], s28, v130, v[98:99]
	s_add_i32 s10, s26, 27
	global_load_dwordx2 a[62:63], v[148:149], off
	s_nop 1
	v_readlane_b32 s28, v100, s10
	s_nop 1
	v_mad_i64_i32 v[148:149], s[10:11], s28, v130, v[96:97]
	global_load_dwordx4 a[12:15], v[148:149], off
	v_mad_i64_i32 v[148:149], s[10:11], s28, v130, v[98:99]
	s_add_i32 s10, s26, 28
	global_load_dwordx2 a[64:65], v[148:149], off
	s_nop 1
	v_readlane_b32 s28, v100, s10
	s_nop 1
	v_mad_i64_i32 v[148:149], s[10:11], s28, v130, v[96:97]
	global_load_dwordx4 a[16:19], v[148:149], off
	v_mad_i64_i32 v[148:149], s[10:11], s28, v130, v[98:99]
	s_add_i32 s10, s26, 29
	global_load_dwordx2 a[66:67], v[148:149], off
	s_nop 1
	v_readlane_b32 s28, v100, s10
	s_nop 1
	v_mad_i64_i32 v[148:149], s[10:11], s28, v130, v[96:97]
	global_load_dwordx4 v[220:223], v[148:149], off
	v_mad_i64_i32 v[148:149], s[10:11], s28, v130, v[98:99]
	s_add_i32 s10, s26, 30
	global_load_dwordx2 v[148:149], v[148:149], off
	s_nop 1
	v_readlane_b32 s28, v100, s10
	s_nop 1
	v_mad_i64_i32 v[224:225], s[10:11], s28, v130, v[96:97]
	v_mad_i64_i32 v[228:229], s[10:11], s28, v130, v[98:99]
	s_add_i32 s10, s26, 31
	global_load_dwordx4 v[224:227], v[224:225], off
	s_cmp_lg_u32 s26, 64
	s_nop 0
	v_readlane_b32 s28, v100, s10
	global_load_dwordx2 v[252:253], v[228:229], off
	s_nop 0
	v_mad_i64_i32 v[228:229], s[10:11], s28, v130, v[96:97]
	v_mad_i64_i32 v[100:101], s[10:11], s28, v130, v[98:99]
	global_load_dwordx4 v[228:231], v[228:229], off
	s_nop 0
	global_load_dwordx2 a[40:41], v[100:101], off
	s_cbranch_scc1 .LBB0_904
	global_load_dword a68, v[170:171], off
	global_load_dword a69, v[168:169], off
	global_load_dword v117, v[166:167], off
	global_load_dword v103, v[164:165], off
	.p2align 6

.LBB0_976:
	s_and_b32 s6, s72, 0xffff
	s_mul_i32 s6, s6, 0xaaab
	s_lshr_b32 s6, s6, 20
	s_add_i32 s74, s78, s6
	s_lshl_b32 s12, s74, 19
	v_lshl_add_u64 v[4:5], v[54:55], 0, s[12:13]
	v_add_co_u32_e32 v12, vcc, 0x10000, v4
	s_mul_i32 s6, s6, 24
	s_nop 0
	v_addc_co_u32_e32 v13, vcc, 0, v5, vcc
	v_add_co_u32_e32 v14, vcc, 0x20000, v4
	s_sub_i32 s9, s72, s6
	s_nop 0
	v_addc_co_u32_e32 v15, vcc, 0, v5, vcc
	v_add_co_u32_e32 v24, vcc, 0x30000, v4
	s_lshl_b32 s6, s9, 18
	s_nop 0
	v_addc_co_u32_e32 v25, vcc, 0, v5, vcc
	v_add_co_u32_e32 v26, vcc, 0x40000, v4
	s_mov_b32 s7, s13
	s_nop 0
	v_addc_co_u32_e32 v27, vcc, 0, v5, vcc
	global_load_dwordx4 v[0:3], v[4:5], off
	v_add_co_u32_e32 v28, vcc, 0x50000, v4
	v_lshl_add_u64 v[8:9], v[56:57], 0, s[6:7]
	s_nop 0
	v_addc_co_u32_e32 v29, vcc, 0, v5, vcc
	global_load_dwordx4 v[102:105], v[8:9], off
	global_load_dwordx4 v[74:77], v[12:13], off
	global_load_dwordx4 v[78:81], v[14:15], off
	v_add_co_u32_e32 v30, vcc, 0x60000, v4
	global_load_dwordx4 v[82:85], v[24:25], off
	global_load_dwordx4 v[86:89], v[26:27], off
	v_addc_co_u32_e32 v31, vcc, 0, v5, vcc
	v_add_co_u32_e32 v32, vcc, 0x70000, v4
	global_load_dwordx4 v[90:93], v[28:29], off
	global_load_dwordx4 v[94:97], v[30:31], off
	v_addc_co_u32_e32 v33, vcc, 0, v5, vcc
	v_add_co_u32_e32 v118, vcc, s11, v8
	s_mov_b32 s8, 0x20000
	s_nop 0
	v_addc_co_u32_e32 v119, vcc, 0, v9, vcc
	global_load_dwordx4 v[98:101], v[32:33], off
	global_load_dwordx4 v[106:109], v[118:119], off
	v_add_co_u32_e32 v120, vcc, s8, v8
	s_mov_b32 s8, 0x30000
	s_nop 0
	v_addc_co_u32_e32 v121, vcc, 0, v9, vcc
	global_load_dwordx4 v[110:113], v[120:121], off
	v_add_co_u32_e32 v122, vcc, s8, v8
	s_mov_b32 s8, 0
	s_nop 0
	v_addc_co_u32_e32 v123, vcc, 0, v9, vcc
	global_load_dwordx4 v[114:117], v[122:123], off
	s_nop 0
	global_load_dwordx4 v[250:253], v[4:5], off offset:128
	s_nop 0
	global_load_dwordx4 v[218:221], v[8:9], off offset:128
	s_nop 0
	global_load_dwordx4 v[246:249], v[12:13], off offset:128
	global_load_dwordx4 v[242:245], v[14:15], off offset:128
	s_nop 0
	global_load_dwordx4 v[238:241], v[24:25], off offset:128
	global_load_dwordx4 v[234:237], v[26:27], off offset:128
	global_load_dwordx4 v[230:233], v[28:29], off offset:128
	global_load_dwordx4 v[226:229], v[30:31], off offset:128
	s_nop 0
	global_load_dwordx4 v[222:225], v[32:33], off offset:128
	s_nop 0
	global_load_dwordx4 v[214:217], v[118:119], off offset:128
	global_load_dwordx4 v[210:213], v[120:121], off offset:128
	s_and_b32 s73, s9, 0xffff
	v_accvgpr_write_b32 a47, 0
	v_accvgpr_write_b32 a46, 0
	v_accvgpr_write_b32 a45, 0
	v_accvgpr_write_b32 a44, 0
	v_accvgpr_write_b32 a43, 0
	v_accvgpr_write_b32 a42, 0
	v_accvgpr_write_b32 a41, 0
	v_accvgpr_write_b32 a40, 0
	v_accvgpr_write_b32 a39, 0
	v_accvgpr_write_b32 a38, 0
	v_accvgpr_write_b32 a37, 0
	v_accvgpr_write_b32 a36, 0
	v_accvgpr_write_b32 a35, 0
	v_accvgpr_write_b32 a34, 0
	v_accvgpr_write_b32 a33, 0
	v_accvgpr_write_b32 a32, 0
	v_accvgpr_write_b32 a63, 0
	v_accvgpr_write_b32 a62, 0
	v_accvgpr_write_b32 a61, 0
	v_accvgpr_write_b32 a60, 0
	v_accvgpr_write_b32 a59, 0
	v_accvgpr_write_b32 a58, 0
	v_accvgpr_write_b32 a57, 0
	v_accvgpr_write_b32 a56, 0
	v_accvgpr_write_b32 a55, 0
	v_accvgpr_write_b32 a54, 0
	s_waitcnt vmcnt(22)
	ds_write_b128 v131, v[0:3]
	s_waitcnt vmcnt(21)
	ds_write_b128 v131, v[102:105] offset:36864
	s_waitcnt vmcnt(20)
	ds_write_b128 v131, v[74:77] offset:4608
	s_waitcnt vmcnt(19)
	ds_write_b128 v131, v[78:81] offset:9216
	s_waitcnt vmcnt(18)
	ds_write_b128 v131, v[82:85] offset:13824
	s_waitcnt vmcnt(17)
	ds_write_b128 v131, v[86:89] offset:18432
	s_waitcnt vmcnt(16)
	ds_write_b128 v131, v[90:93] offset:23040
	s_waitcnt vmcnt(15)
	ds_write_b128 v131, v[94:97] offset:27648
	s_waitcnt vmcnt(14)
	ds_write_b128 v131, v[98:101] offset:32256
	s_waitcnt vmcnt(13)
	ds_write_b128 v131, v[106:109] offset:41472
	s_waitcnt vmcnt(12)
	ds_write_b128 v131, v[110:113] offset:46080
	global_load_dwordx4 v[206:209], v[122:123], off offset:128
	v_lshl_add_u64 v[0:1], v[72:73], 0, s[12:13]
	v_lshl_add_u64 v[2:3], v[72:73], 0, s[6:7]
	v_accvgpr_write_b32 a53, 0
	v_accvgpr_write_b32 a52, 0
	v_accvgpr_write_b32 a51, 0
	v_accvgpr_write_b32 a50, 0
	v_accvgpr_write_b32 a49, 0
	v_accvgpr_write_b32 a48, 0
	v_accvgpr_write_b32 a79, 0
	v_accvgpr_write_b32 a78, 0
	v_accvgpr_write_b32 a77, 0
	v_accvgpr_write_b32 a76, 0
	v_accvgpr_write_b32 a75, 0
	v_accvgpr_write_b32 a74, 0
	v_accvgpr_write_b32 a73, 0
	v_accvgpr_write_b32 a72, 0
	v_accvgpr_write_b32 a71, 0
	v_accvgpr_write_b32 a70, 0
	v_accvgpr_write_b32 a69, 0
	v_accvgpr_write_b32 a68, 0
	v_accvgpr_write_b32 a67, 0
	v_accvgpr_write_b32 a66, 0
	v_accvgpr_write_b32 a65, 0
	v_accvgpr_write_b32 a64, 0
	v_accvgpr_write_b32 a111, 0
	v_accvgpr_write_b32 a110, 0
	v_accvgpr_write_b32 a109, 0
	v_accvgpr_write_b32 a108, 0
	v_accvgpr_write_b32 a107, 0
	v_accvgpr_write_b32 a106, 0
	v_accvgpr_write_b32 a105, 0
	v_accvgpr_write_b32 a104, 0
	v_accvgpr_write_b32 a103, 0
	v_accvgpr_write_b32 a102, 0
	v_accvgpr_write_b32 a101, 0
	v_accvgpr_write_b32 a100, 0
	v_accvgpr_write_b32 a99, 0
	v_accvgpr_write_b32 a98, 0
	v_accvgpr_write_b32 a97, 0
	v_accvgpr_write_b32 a96, 0
	v_accvgpr_write_b32 a95, 0
	v_accvgpr_write_b32 a94, 0
	v_accvgpr_write_b32 a93, 0
	v_accvgpr_write_b32 a92, 0
	v_accvgpr_write_b32 a91, 0
	v_accvgpr_write_b32 a90, 0
	v_accvgpr_write_b32 a89, 0
	v_accvgpr_write_b32 a88, 0
	v_accvgpr_write_b32 a87, 0
	v_accvgpr_write_b32 a86, 0
	v_accvgpr_write_b32 a85, 0
	v_accvgpr_write_b32 a84, 0
	v_accvgpr_write_b32 a83, 0
	v_accvgpr_write_b32 a82, 0
	v_accvgpr_write_b32 a81, 0
	v_accvgpr_write_b32 a80, 0
	v_accvgpr_write_b32 a127, 0
	v_accvgpr_write_b32 a126, 0
	v_accvgpr_write_b32 a125, 0
	v_accvgpr_write_b32 a124, 0
	v_accvgpr_write_b32 a123, 0
	v_accvgpr_write_b32 a122, 0
	v_accvgpr_write_b32 a121, 0
	v_accvgpr_write_b32 a120, 0
	v_accvgpr_write_b32 a119, 0
	v_accvgpr_write_b32 a118, 0
	v_accvgpr_write_b32 a117, 0
	v_accvgpr_write_b32 a116, 0
	v_accvgpr_write_b32 a115, 0
	v_accvgpr_write_b32 a114, 0
	v_accvgpr_write_b32 a113, 0
	v_accvgpr_write_b32 a112, 0
	v_accvgpr_write_b32 a31, 0
	v_accvgpr_write_b32 a30, 0
	v_accvgpr_write_b32 a29, 0
	v_accvgpr_write_b32 a28, 0
	v_accvgpr_write_b32 a27, 0
	v_accvgpr_write_b32 a26, 0
	v_accvgpr_write_b32 a25, 0
	v_accvgpr_write_b32 a24, 0
	v_accvgpr_write_b32 a23, 0
	v_accvgpr_write_b32 a22, 0
	v_accvgpr_write_b32 a21, 0
	v_accvgpr_write_b32 a20, 0
	v_accvgpr_write_b32 a19, 0
	v_accvgpr_write_b32 a18, 0
	v_accvgpr_write_b32 a17, 0
	v_accvgpr_write_b32 a16, 0
	v_accvgpr_write_b32 a15, 0
	v_accvgpr_write_b32 a14, 0
	v_accvgpr_write_b32 a13, 0
	v_accvgpr_write_b32 a12, 0
	v_accvgpr_write_b32 a11, 0
	v_accvgpr_write_b32 a10, 0
	v_accvgpr_write_b32 a9, 0
	v_accvgpr_write_b32 a8, 0
	v_accvgpr_write_b32 a7, 0
	v_accvgpr_write_b32 a6, 0
	v_accvgpr_write_b32 a5, 0
	v_accvgpr_write_b32 a4, 0
	v_accvgpr_write_b32 a3, 0
	v_accvgpr_write_b32 a2, 0
	v_accvgpr_write_b32 a1, 0
	v_accvgpr_write_b32 a0, 0
	s_mov_b64 s[6:7], 0
	s_waitcnt vmcnt(12)
	ds_write_b128 v131, v[114:117] offset:50688
	s_waitcnt lgkmcnt(0)
	s_barrier
	s_waitcnt vmcnt(0)
	v_readfirstlane_b32 s100, v0
	v_readfirstlane_b32 s101, v1
	v_readfirstlane_b32 s98, v2
	v_readfirstlane_b32 s99, v3
	s_nop 1
	v_subrev_u32_e32 v194, s100, v0
	v_subrev_u32_e32 v193, s98, v2
	v_add_u32_e32 v254, 0x126fa000, v194
	v_add_u32_e32 v205, 0x1270a000, v194
	v_add_u32_e32 v204, 0x1271a000, v194
	v_add_u32_e32 v203, 0x1272a000, v194
	v_add_u32_e32 v202, 0x1273a000, v194
	v_add_u32_e32 v201, 0x1274a000, v194
	v_add_u32_e32 v200, s82, v194
	v_add_u32_e32 v199, s83, v194
	v_add_u32_e32 v198, s84, v193
	v_add_u32_e32 v197, s85, v193
	v_add_u32_e32 v196, s86, v193
	v_add_u32_e32 v195, s87, v193
	s_add_u32 s100, s100, s6
	s_addc_u32 s101, s101, s7
	s_add_u32 s98, s98, s6
	s_addc_u32 s99, s99, s7
	v_add_u32_e32 v192, v51, v132
	v_add_u32_e32 v191, v51, v133
	v_add_u32_e32 v190, v51, v136
	s_and_b32 s9, s8, 1
	s_mul_i32 s12, s9, 0xd800
	v_add_u32_e32 v189, s12, v192
	v_add_u32_e32 v188, s12, v191
	v_add_u32_e32 v187, s12, v190
	ds_read_b128 v[78:81], v189
	ds_read_b128 v[4:7], v187 offset:36864
	ds_read_b128 v[82:85], v189 offset:4608
	ds_read_b128 v[8:11], v187 offset:41472
	ds_read_b128 v[86:89], v189 offset:9216
	ds_read_b128 v[90:93], v188
	s_getreg_b32 s9, hwreg(HW_REG_HW_ID, 4, 1)
	s_cmp_lg_u32 s9, 0
	s_cbranch_scc1 xg5_varB_3
	.p2align 6
.LBB0_977:
	s_and_b32 s9, s8, 1
	s_mul_i32 s12, s9, 0xd800
	s_xor_b32 s9, s9, 1
	s_mul_i32 s9, s9, 0xd800
	s_add_i32 s8, s8, 1
	v_add_u32_e32 v186, s9, v131
	ds_read_b128 v[12:15], v189 offset:32
	ds_read_b128 v[24:27], v187 offset:36896
	ds_read_b128 v[16:19], v189 offset:4640
	ds_read_b128 v[28:31], v187 offset:41504
	ds_read_b128 v[20:23], v189 offset:9248
	ds_read_b128 v[74:77], v188 offset:32
	s_waitcnt lgkmcnt(10)
	v_mfma_f32_32x32x16_bf16 a[32:47], v[78:81], v[4:7], a[32:47]
	s_waitcnt vmcnt(11)
	ds_write_b128 v186, v[250:253]
	s_waitcnt lgkmcnt(9)
	v_mfma_f32_32x32x16_bf16 a[48:63], v[78:81], v[8:11], a[48:63]
	s_waitcnt vmcnt(10)
	ds_write_b128 v186, v[246:249] offset:4608
	global_load_dwordx4 v[250:253], v254, s[100:101] offset:512
	v_mfma_f32_32x32x16_bf16 a[64:79], v[82:85], v[4:7], a[64:79]
	s_waitcnt vmcnt(10)
	ds_write_b128 v186, v[242:245] offset:9216
	global_load_dwordx4 v[246:249], v205, s[100:101] offset:512
	v_mfma_f32_32x32x16_bf16 a[96:111], v[82:85], v[8:11], a[96:111]
	s_waitcnt vmcnt(10)
	ds_write_b128 v186, v[238:241] offset:13824
	global_load_dwordx4 v[242:245], v204, s[100:101] offset:512
	s_waitcnt lgkmcnt(11)
	v_mfma_f32_32x32x16_bf16 a[80:95], v[86:89], v[4:7], a[80:95]
	s_waitcnt vmcnt(10)
	ds_write_b128 v186, v[234:237] offset:18432
	global_load_dwordx4 v[238:241], v203, s[100:101] offset:512
	v_mfma_f32_32x32x16_bf16 a[112:127], v[86:89], v[8:11], a[112:127]
	s_waitcnt vmcnt(10)
	ds_write_b128 v186, v[230:233] offset:23040
	global_load_dwordx4 v[234:237], v202, s[100:101] offset:512
	s_waitcnt lgkmcnt(12)
	v_mfma_f32_32x32x16_bf16 a[16:31], v[90:93], v[4:7], a[16:31]
	s_waitcnt vmcnt(10)
	ds_write_b128 v186, v[226:229] offset:27648
	global_load_dwordx4 v[230:233], v201, s[100:101] offset:512
	v_mfma_f32_32x32x16_bf16 a[0:15], v[90:93], v[8:11], a[0:15]
	s_waitcnt vmcnt(10)
	ds_write_b128 v186, v[222:225] offset:32256
	global_load_dwordx4 v[226:229], v200, s[100:101] offset:512
	ds_read_b128 v[78:81], v189 offset:64
	ds_read_b128 v[4:7], v187 offset:36928
	ds_read_b128 v[82:85], v189 offset:4672
	ds_read_b128 v[8:11], v187 offset:41536
	ds_read_b128 v[86:89], v189 offset:9280
	ds_read_b128 v[90:93], v188 offset:64
	s_waitcnt lgkmcnt(15)
	v_mfma_f32_32x32x16_bf16 a[32:47], v[12:15], v[24:27], a[32:47]
	s_waitcnt vmcnt(10)
	ds_write_b128 v186, v[218:221] offset:36864
	global_load_dwordx4 v[222:225], v199, s[100:101] offset:512
	v_mfma_f32_32x32x16_bf16 a[48:63], v[12:15], v[28:31], a[48:63]
	s_waitcnt vmcnt(10)
	ds_write_b128 v186, v[214:217] offset:41472
	global_load_dwordx4 v[218:221], v198, s[98:99] offset:256
	v_mfma_f32_32x32x16_bf16 a[64:79], v[16:19], v[24:27], a[64:79]
	s_waitcnt vmcnt(10)
	ds_write_b128 v186, v[210:213] offset:46080
	global_load_dwordx4 v[214:217], v197, s[98:99] offset:256
	v_mfma_f32_32x32x16_bf16 a[96:111], v[16:19], v[28:31], a[96:111]
	s_waitcnt vmcnt(10)
	ds_write_b128 v186, v[206:209] offset:50688
	global_load_dwordx4 v[210:213], v196, s[98:99] offset:256
	v_mfma_f32_32x32x16_bf16 a[80:95], v[20:23], v[24:27], a[80:95]
	global_load_dwordx4 v[206:209], v195, s[98:99] offset:256
	s_add_u32 s100, s100, 0x80
	s_addc_u32 s101, s101, 0
	s_add_u32 s98, s98, 0x80
	s_addc_u32 s99, s99, 0
	v_mfma_f32_32x32x16_bf16 a[112:127], v[20:23], v[28:31], a[112:127]
	s_waitcnt lgkmcnt(15)
	v_mfma_f32_32x32x16_bf16 a[16:31], v[74:77], v[24:27], a[16:31]
	v_mfma_f32_32x32x16_bf16 a[0:15], v[74:77], v[28:31], a[0:15]
	ds_read_b128 v[12:15], v189 offset:96
	ds_read_b128 v[24:27], v187 offset:36960
	ds_read_b128 v[16:19], v189 offset:4704
	ds_read_b128 v[28:31], v187 offset:41568
	ds_read_b128 v[20:23], v189 offset:9312
	ds_read_b128 v[74:77], v188 offset:96
	s_waitcnt lgkmcnt(14)
	v_mfma_f32_32x32x16_bf16 a[32:47], v[78:81], v[4:7], a[32:47]
	s_waitcnt lgkmcnt(12)
	v_mfma_f32_32x32x16_bf16 a[48:63], v[78:81], v[8:11], a[48:63]
	v_mfma_f32_32x32x16_bf16 a[64:79], v[82:85], v[4:7], a[64:79]
	v_mfma_f32_32x32x16_bf16 a[96:111], v[82:85], v[8:11], a[96:111]
	s_waitcnt lgkmcnt(11)
	v_mfma_f32_32x32x16_bf16 a[80:95], v[86:89], v[4:7], a[80:95]
	v_mfma_f32_32x32x16_bf16 a[112:127], v[86:89], v[8:11], a[112:127]
	s_waitcnt lgkmcnt(10)
	v_mfma_f32_32x32x16_bf16 a[16:31], v[90:93], v[4:7], a[16:31]
	v_mfma_f32_32x32x16_bf16 a[0:15], v[90:93], v[8:11], a[0:15]
	s_waitcnt lgkmcnt(0)
	v_mfma_f32_32x32x16_bf16 a[32:47], v[12:15], v[24:27], a[32:47]
	v_mfma_f32_32x32x16_bf16 a[48:63], v[12:15], v[28:31], a[48:63]
	v_mfma_f32_32x32x16_bf16 a[64:79], v[16:19], v[24:27], a[64:79]
	v_mfma_f32_32x32x16_bf16 a[96:111], v[16:19], v[28:31], a[96:111]
	s_barrier
	v_add_u32_e32 v189, s9, v192
	v_add_u32_e32 v188, s9, v191
	v_add_u32_e32 v187, s9, v190
	ds_read_b128 v[78:81], v189
	ds_read_b128 v[4:7], v187 offset:36864
	ds_read_b128 v[82:85], v189 offset:4608
	ds_read_b128 v[8:11], v187 offset:41472
	ds_read_b128 v[86:89], v189 offset:9216
	ds_read_b128 v[90:93], v188
	v_mfma_f32_32x32x16_bf16 a[80:95], v[20:23], v[24:27], a[80:95]
	v_mfma_f32_32x32x16_bf16 a[112:127], v[20:23], v[28:31], a[112:127]
	v_mfma_f32_32x32x16_bf16 a[16:31], v[74:77], v[24:27], a[16:31]
	v_mfma_f32_32x32x16_bf16 a[0:15], v[74:77], v[28:31], a[0:15]
	s_add_u32 s6, s6, 0x80
	s_addc_u32 s7, s7, 0
	s_cmpk_lg_i32 s6, 0x700
	s_cbranch_scc1 .LBB0_977
	s_branch xg5_tail_3
	.p2align 6

.LBB0_1086:
	s_lshl_b64 s[58:59], s[8:9], 10
	s_lshl_b64 s[64:65], s[8:9], 11
	v_mov_b32_e32 v245, v151
	s_lshl_b32 s8, s68, 7
	v_lshl_add_u64 v[0:1], s[62:63], 0, v[244:245]
	v_mov_b32_e32 v165, v151
	v_mov_b32_e32 v247, v151
	s_add_u32 s70, s62, s8
	v_lshl_add_u64 v[0:1], v[0:1], 0, v[164:165]
	v_lshl_add_u64 v[2:3], s[62:63], 0, v[246:247]
	s_addc_u32 s71, s63, 0
	v_lshl_add_u64 v[2:3], v[2:3], 0, v[164:165]
	global_load_dwordx4 v[32:35], v[0:1], off
	global_load_dwordx4 v[36:39], v[2:3], off
	v_lshl_add_u64 v[0:1], s[70:71], 0, v[244:245]
	v_lshl_add_u64 v[0:1], v[0:1], 0, v[164:165]
	v_lshl_add_u64 v[2:3], s[70:71], 0, v[246:247]
	v_lshl_add_u64 v[2:3], v[2:3], 0, v[164:165]
	global_load_dwordx4 v[40:43], v[0:1], off
	global_load_dwordx4 v[44:47], v[2:3], off
	v_accvgpr_read_b32 v0, a209
	v_mul_u32_u24_e32 v0, s68, v0
	v_lshlrev_b32_e32 v64, 1, v0
	v_mov_b32_e32 v65, v151
	v_mul_u32_u24_e32 v2, s68, v154
	v_lshl_add_u64 v[0:1], s[60:61], 0, v[64:65]
	v_lshlrev_b32_e32 v66, 1, v2
	v_mov_b32_e32 v67, v151
	v_lshl_add_u64 v[0:1], v[0:1], 0, v[164:165]
	v_lshl_add_u64 v[2:3], s[60:61], 0, v[66:67]
	v_lshl_add_u64 v[2:3], v[2:3], 0, v[164:165]
	global_load_dwordx4 v[48:51], v[0:1], off
	global_load_dwordx4 v[52:55], v[2:3], off
	v_mul_u32_u24_e32 v0, s68, v155
	v_lshlrev_b32_e32 v68, 1, v0
	v_mov_b32_e32 v69, v151
	v_mul_u32_u24_e32 v2, s68, v162
	v_lshl_add_u64 v[0:1], s[60:61], 0, v[68:69]
	v_lshlrev_b32_e32 v70, 1, v2
	v_mov_b32_e32 v71, v151
	v_lshl_add_u64 v[0:1], v[0:1], 0, v[164:165]
	v_lshl_add_u64 v[2:3], s[60:61], 0, v[70:71]
	v_lshl_add_u64 v[2:3], v[2:3], 0, v[164:165]
	global_load_dwordx4 v[56:59], v[0:1], off
	global_load_dwordx4 v[60:63], v[2:3], off
	v_mov_b32_e32 v251, v151
	v_lshl_add_u64 v[0:1], v[168:169], 0, s[64:65]
	v_lshl_add_u64 v[2:3], v[0:1], 0, v[150:151]
	v_lshl_add_u64 v[0:1], v[0:1], 0, v[250:251]
	global_load_dwordx4 v[28:31], v[2:3], off
	global_load_dwordx4 v[24:27], v[2:3], off offset:32
	global_load_dwordx4 v[20:23], v[2:3], off offset:64
	global_load_dwordx4 v[16:19], v[2:3], off offset:96
	global_load_dwordx4 v[12:15], v[0:1], off
	global_load_dwordx4 v[8:11], v[0:1], off offset:32
	global_load_dwordx4 v[4:7], v[0:1], off offset:64
	s_nop 0
	global_load_dwordx4 v[0:3], v[0:1], off offset:96
	v_lshl_add_u64 v[82:83], s[62:63], 0, v[170:171]
	v_lshl_add_u64 v[84:85], s[62:63], 0, v[242:243]
	v_lshl_add_u64 v[86:87], v[82:83], 0, s[8:9]
	v_lshl_add_u64 v[88:89], v[84:85], 0, s[8:9]
	s_add_i32 s8, s67, 1
	s_add_u32 s60, s60, 0x80
	v_mov_b32_e32 v80, 0
	s_addc_u32 s61, s61, 0
	v_accvgpr_write_b32 a31, 0
	v_accvgpr_write_b32 a30, 0
	v_accvgpr_write_b32 a29, 0
	v_accvgpr_write_b32 a28, 0
	v_accvgpr_write_b32 a27, 0
	v_accvgpr_write_b32 a26, 0
	v_accvgpr_write_b32 a25, 0
	v_accvgpr_write_b32 a24, 0
	v_accvgpr_write_b32 a23, 0
	v_accvgpr_write_b32 a22, 0
	v_lshl_add_u64 v[90:91], s[60:61], 0, v[64:65]
	v_lshl_add_u64 v[92:93], s[60:61], 0, v[66:67]
	v_lshl_add_u64 v[94:95], s[60:61], 0, v[68:69]
	v_lshl_add_u64 v[96:97], s[60:61], 0, v[70:71]
	v_accvgpr_write_b32 a21, 0
	v_accvgpr_write_b32 a20, 0
	v_accvgpr_write_b32 a19, 0
	v_accvgpr_write_b32 a18, 0
	v_accvgpr_write_b32 a17, 0
	v_accvgpr_write_b32 a16, 0
	v_accvgpr_write_b32 a111, 0
	v_accvgpr_write_b32 a110, 0
	v_accvgpr_write_b32 a109, 0
	v_accvgpr_write_b32 a108, 0
	v_accvgpr_write_b32 a107, 0
	v_accvgpr_write_b32 a106, 0
	v_accvgpr_write_b32 a105, 0
	v_accvgpr_write_b32 a104, 0
	v_accvgpr_write_b32 a103, 0
	v_accvgpr_write_b32 a102, 0
	v_accvgpr_write_b32 a101, 0
	v_accvgpr_write_b32 a100, 0
	v_accvgpr_write_b32 a99, 0
	v_accvgpr_write_b32 a98, 0
	v_accvgpr_write_b32 a97, 0
	v_accvgpr_write_b32 a96, 0
	v_accvgpr_write_b32 a143, 0
	v_accvgpr_write_b32 a142, 0
	v_accvgpr_write_b32 a141, 0
	v_accvgpr_write_b32 a140, 0
	v_accvgpr_write_b32 a139, 0
	v_accvgpr_write_b32 a138, 0
	v_accvgpr_write_b32 a137, 0
	v_accvgpr_write_b32 a136, 0
	v_accvgpr_write_b32 a135, 0
	v_accvgpr_write_b32 a134, 0
	v_accvgpr_write_b32 a133, 0
	v_accvgpr_write_b32 a132, 0
	v_accvgpr_write_b32 a131, 0
	v_accvgpr_write_b32 a130, 0
	v_accvgpr_write_b32 a129, 0
	v_accvgpr_write_b32 a128, 0
	v_accvgpr_write_b32 a63, 0
	v_accvgpr_write_b32 a62, 0
	v_accvgpr_write_b32 a61, 0
	v_accvgpr_write_b32 a60, 0
	v_accvgpr_write_b32 a59, 0
	v_accvgpr_write_b32 a58, 0
	v_accvgpr_write_b32 a57, 0
	v_accvgpr_write_b32 a56, 0
	v_accvgpr_write_b32 a55, 0
	v_accvgpr_write_b32 a54, 0
	v_accvgpr_write_b32 a53, 0
	v_accvgpr_write_b32 a52, 0
	v_accvgpr_write_b32 a51, 0
	v_accvgpr_write_b32 a50, 0
	v_accvgpr_write_b32 a49, 0
	v_accvgpr_write_b32 a48, 0
	v_accvgpr_write_b32 a95, 0
	v_accvgpr_write_b32 a94, 0
	v_accvgpr_write_b32 a93, 0
	v_accvgpr_write_b32 a92, 0
	v_accvgpr_write_b32 a91, 0
	v_accvgpr_write_b32 a90, 0
	v_accvgpr_write_b32 a89, 0
	v_accvgpr_write_b32 a88, 0
	v_accvgpr_write_b32 a87, 0
	v_accvgpr_write_b32 a86, 0
	v_accvgpr_write_b32 a85, 0
	v_accvgpr_write_b32 a84, 0
	v_accvgpr_write_b32 a83, 0
	v_accvgpr_write_b32 a82, 0
	v_accvgpr_write_b32 a81, 0
	v_accvgpr_write_b32 a80, 0
	v_accvgpr_write_b32 a47, 0
	v_accvgpr_write_b32 a46, 0
	v_accvgpr_write_b32 a45, 0
	v_accvgpr_write_b32 a44, 0
	v_accvgpr_write_b32 a43, 0
	v_accvgpr_write_b32 a42, 0
	v_accvgpr_write_b32 a41, 0
	v_accvgpr_write_b32 a40, 0
	v_accvgpr_write_b32 a39, 0
	v_accvgpr_write_b32 a38, 0
	v_accvgpr_write_b32 a37, 0
	v_accvgpr_write_b32 a36, 0
	v_accvgpr_write_b32 a35, 0
	v_accvgpr_write_b32 a34, 0
	v_accvgpr_write_b32 a33, 0
	v_accvgpr_write_b32 a32, 0
	v_accvgpr_write_b32 a127, 0
	v_accvgpr_write_b32 a126, 0
	v_accvgpr_write_b32 a125, 0
	v_accvgpr_write_b32 a124, 0
	v_accvgpr_write_b32 a123, 0
	v_accvgpr_write_b32 a122, 0
	v_accvgpr_write_b32 a121, 0
	v_accvgpr_write_b32 a120, 0
	v_accvgpr_write_b32 a119, 0
	v_accvgpr_write_b32 a118, 0
	v_accvgpr_write_b32 a117, 0
	v_accvgpr_write_b32 a116, 0
	v_accvgpr_write_b32 a115, 0
	v_accvgpr_write_b32 a114, 0
	v_accvgpr_write_b32 a113, 0
	v_accvgpr_write_b32 a112, 0
	v_accvgpr_write_b32 a79, 0
	v_accvgpr_write_b32 a78, 0
	v_accvgpr_write_b32 a77, 0
	v_accvgpr_write_b32 a76, 0
	v_accvgpr_write_b32 a75, 0
	v_accvgpr_write_b32 a74, 0
	v_accvgpr_write_b32 a73, 0
	v_accvgpr_write_b32 a72, 0
	v_accvgpr_write_b32 a71, 0
	v_accvgpr_write_b32 a70, 0
	v_accvgpr_write_b32 a69, 0
	v_accvgpr_write_b32 a68, 0
	v_accvgpr_write_b32 a67, 0
	v_accvgpr_write_b32 a66, 0
	v_accvgpr_write_b32 a65, 0
	v_accvgpr_write_b32 a64, 0
	s_mov_b32 s60, 0
	v_mov_b32_e32 v81, v80
	s_waitcnt vmcnt(15)
	ds_write_b128 v129, v[32:35]
	s_waitcnt vmcnt(14)
	ds_write_b128 v135, v[36:39]
	s_waitcnt vmcnt(13)
	ds_write_b128 v129, v[40:43] offset:9216
	s_waitcnt vmcnt(12)
	ds_write_b128 v135, v[44:47] offset:9216
	s_waitcnt vmcnt(11)
	ds_write_b128 v129, v[48:51] offset:36864
	s_waitcnt vmcnt(10)
	ds_write_b128 v135, v[52:55] offset:36864
	s_waitcnt vmcnt(9)
	ds_write_b128 v163, v[56:59] offset:36864
	s_waitcnt vmcnt(8)
	ds_write_b128 v166, v[60:63] offset:36864
	v_accvgpr_write_b32 a160, 0
	v_mov_b32_e32 v48, 0
	v_accvgpr_write_b32 a161, 0
	v_mov_b32_e32 v49, 0
	v_accvgpr_write_b32 a162, 0
	v_mov_b32_e32 v50, 0
	v_accvgpr_write_b32 a163, 0
	v_mov_b32_e32 v51, 0
	v_accvgpr_write_b32 a164, 0
	v_mov_b32_e32 v52, 0
	v_accvgpr_write_b32 a165, 0
	v_mov_b32_e32 v53, 0
	v_accvgpr_write_b32 a166, 0
	v_mov_b32_e32 v54, 0
	v_accvgpr_write_b32 a167, 0
	v_mov_b32_e32 v55, 0
	v_accvgpr_write_b32 a168, 0
	v_mov_b32_e32 v56, 0
	v_accvgpr_write_b32 a169, 0
	v_mov_b32_e32 v57, 0
	v_accvgpr_write_b32 a170, 0
	v_mov_b32_e32 v58, 0
	v_accvgpr_write_b32 a171, 0
	v_mov_b32_e32 v59, 0
	v_accvgpr_write_b32 a172, 0
	v_mov_b32_e32 v60, 0
	v_accvgpr_write_b32 a173, 0
	v_mov_b32_e32 v61, 0
	v_accvgpr_write_b32 a174, 0
	v_mov_b32_e32 v62, 0
	v_accvgpr_write_b32 a175, 0
	v_mov_b32_e32 v63, 0
	v_accvgpr_write_b32 a176, 0
	v_mov_b32_e32 v116, 0
	v_accvgpr_write_b32 a177, 0
	v_mov_b32_e32 v117, 0
	v_accvgpr_write_b32 a178, 0
	v_mov_b32_e32 v118, 0
	v_accvgpr_write_b32 a179, 0
	v_mov_b32_e32 v119, 0
	v_accvgpr_write_b32 a180, 0
	v_mov_b32_e32 v120, 0
	v_accvgpr_write_b32 a181, 0
	v_mov_b32_e32 v121, 0
	v_accvgpr_write_b32 a182, 0
	v_mov_b32_e32 v122, 0
	v_accvgpr_write_b32 a183, 0
	v_mov_b32_e32 v123, 0
	v_accvgpr_write_b32 a184, 0
	v_mov_b32_e32 v124, 0
	v_accvgpr_write_b32 a185, 0
	v_mov_b32_e32 v125, 0
	v_accvgpr_write_b32 a186, 0
	v_mov_b32_e32 v126, 0
	v_accvgpr_write_b32 a187, 0
	v_mov_b32_e32 v127, 0
	v_accvgpr_write_b32 a188, 0
	v_mov_b32_e32 v130, 0
	v_accvgpr_write_b32 a189, 0
	v_mov_b32_e32 v131, 0
	v_accvgpr_write_b32 a190, 0
	v_mov_b32_e32 v132, 0
	v_accvgpr_write_b32 a191, 0
	v_mov_b32_e32 v133, 0
	v_accvgpr_read_b32 v32, a0
	v_accvgpr_read_b32 v33, a0
	v_accvgpr_read_b32 v34, a0
	v_accvgpr_read_b32 v35, a0
	v_accvgpr_read_b32 v36, a0
	v_accvgpr_read_b32 v37, a0
	v_accvgpr_read_b32 v38, a0
	v_accvgpr_read_b32 v39, a0
	v_accvgpr_read_b32 v40, a0
	v_accvgpr_read_b32 v41, a0
	v_accvgpr_read_b32 v42, a0
	v_accvgpr_read_b32 v43, a0
	v_accvgpr_read_b32 v44, a0
	v_accvgpr_read_b32 v45, a0
	v_accvgpr_read_b32 v46, a0
	v_accvgpr_read_b32 v47, a0
	v_mbcnt_lo_u32_b32 v235, -1, 0
	v_mbcnt_hi_u32_b32 v235, -1, v235
	v_lshlrev_b32_e32 v235, 4, v235
	v_add_u32_e32 v235, 0xd800, v235
	s_waitcnt lgkmcnt(0)
	ds_write_b128 v235, a[160:163]
	ds_write_b128 v235, a[160:163] offset:1024
	ds_write_b128 v235, a[160:163] offset:2048
	ds_write_b128 v235, a[160:163] offset:3072
	ds_write_b128 v235, a[160:163] offset:4096
	ds_write_b128 v235, a[160:163] offset:5120
	ds_write_b128 v235, a[160:163] offset:6144
	ds_write_b128 v235, a[160:163] offset:7168
	ds_write_b128 v235, a[160:163] offset:8192
	s_waitcnt lgkmcnt(0)
	ds_write_b128 v235, a[160:163] offset:9216
	ds_write_b128 v235, a[160:163] offset:10240
	ds_write_b128 v235, a[160:163] offset:11264
	ds_write_b128 v235, a[160:163] offset:12288
	ds_write_b128 v235, a[160:163] offset:13312
	ds_write_b128 v235, a[160:163] offset:14336
	ds_write_b128 v235, a[160:163] offset:15360
	ds_write_b128 v235, a[160:163] offset:16384
	ds_write_b128 v235, a[160:163] offset:17408
	.p2align 6

.LBB0_1264:
	s_lshr_b32 s48, s47, 3
	s_lshl_b32 s42, s48, 18
	s_add_i32 s42, s68, s42
	v_lshl_add_u64 v[10:11], s[42:43], 1, v[8:9]
	s_and_b32 s42, s46, 7
	s_lshl_b32 s42, s42, 18
	s_add_i32 s48, s48, s65
	v_lshl_add_u64 v[12:13], v[8:9], 0, s[42:43]
	s_lshl_b32 s42, s48, 19
	v_lshl_add_u64 v[14:15], v[2:3], 0, s[42:43]
	v_add_co_u32_e32 v16, vcc, s69, v14
	s_mov_b32 s42, 0x40000
	s_nop 0
	v_addc_co_u32_e32 v17, vcc, 0, v15, vcc
	v_add_co_u32_e32 v18, vcc, s70, v14
	s_and_b32 s49, s47, 7
	s_nop 0
	v_addc_co_u32_e32 v19, vcc, 0, v15, vcc
	v_add_co_u32_e32 v76, vcc, s71, v14
	global_load_dwordx4 v[108:111], v[14:15], off
	global_load_dwordx4 v[112:115], v[16:17], off
	v_addc_co_u32_e32 v77, vcc, 0, v15, vcc
	v_add_co_u32_e32 v78, vcc, s42, v14
	s_mov_b32 s42, 0x50000
	s_nop 0
	v_addc_co_u32_e32 v79, vcc, 0, v15, vcc
	v_add_co_u32_e32 v80, vcc, s42, v14
	s_mov_b32 s42, 0x60000
	s_nop 0
	v_addc_co_u32_e32 v81, vcc, 0, v15, vcc
	v_add_co_u32_e32 v82, vcc, s42, v14
	s_lshl_b32 s42, s49, 18
	s_nop 0
	v_addc_co_u32_e32 v83, vcc, 0, v15, vcc
	v_add_co_u32_e32 v88, vcc, s72, v14
	v_lshl_add_u64 v[90:91], v[4:5], 0, s[42:43]
	s_nop 0
	v_addc_co_u32_e32 v89, vcc, 0, v15, vcc
	v_add_co_u32_e32 v92, vcc, s69, v90
	global_load_dwordx4 v[116:119], v[18:19], off
	global_load_dwordx4 v[120:123], v[76:77], off
	v_addc_co_u32_e32 v93, vcc, 0, v91, vcc
	v_add_co_u32_e32 v104, vcc, s70, v90
	global_load_dwordx4 v[124:127], v[78:79], off
	global_load_dwordx4 v[128:131], v[80:81], off
	v_addc_co_u32_e32 v105, vcc, 0, v91, vcc
	v_add_co_u32_e32 v106, vcc, s71, v90
	global_load_dwordx4 v[140:143], v[82:83], off
	global_load_dwordx4 v[144:147], v[88:89], off
	v_addc_co_u32_e32 v107, vcc, 0, v91, vcc
	global_load_dwordx4 v[148:151], v[90:91], off
	global_load_dwordx4 v[152:155], v[92:93], off
	global_load_dwordx4 v[156:159], v[104:105], off
	global_load_dwordx4 v[160:163], v[106:107], off
	global_load_dwordx4 v[250:253], v[14:15], off offset:128
	global_load_dwordx4 v[246:249], v[16:17], off offset:128
	global_load_dwordx4 v[242:245], v[18:19], off offset:128
	s_nop 0
	global_load_dwordx4 v[238:241], v[76:77], off offset:128
	global_load_dwordx4 v[234:237], v[78:79], off offset:128
	global_load_dwordx4 v[230:233], v[80:81], off offset:128
	s_nop 0
	global_load_dwordx4 v[226:229], v[82:83], off offset:128
	s_nop 0
	global_load_dwordx4 v[222:225], v[88:89], off offset:128
	global_load_dwordx4 v[218:221], v[90:91], off offset:128
	s_nop 0
	global_load_dwordx4 v[214:217], v[92:93], off offset:128
	s_nop 0
	global_load_dwordx4 v[210:213], v[104:105], off offset:128
	s_nop 0
	global_load_dwordx4 v[206:209], v[106:107], off offset:128
	s_mov_b32 s42, 0
	v_accvgpr_write_b32 a47, 0
	v_accvgpr_write_b32 a46, 0
	v_accvgpr_write_b32 a45, 0
	v_accvgpr_write_b32 a44, 0
	v_accvgpr_write_b32 a43, 0
	v_accvgpr_write_b32 a42, 0
	v_accvgpr_write_b32 a41, 0
	v_accvgpr_write_b32 a40, 0
	v_accvgpr_write_b32 a39, 0
	v_accvgpr_write_b32 a38, 0
	v_accvgpr_write_b32 a37, 0
	v_accvgpr_write_b32 a36, 0
	v_accvgpr_write_b32 a35, 0
	v_accvgpr_write_b32 a34, 0
	v_accvgpr_write_b32 a33, 0
	v_accvgpr_write_b32 a32, 0
	v_accvgpr_write_b32 a63, 0
	v_accvgpr_write_b32 a62, 0
	v_accvgpr_write_b32 a61, 0
	v_accvgpr_write_b32 a60, 0
	v_accvgpr_write_b32 a59, 0
	v_accvgpr_write_b32 a58, 0
	v_accvgpr_write_b32 a57, 0
	v_accvgpr_write_b32 a56, 0
	v_accvgpr_write_b32 a55, 0
	v_accvgpr_write_b32 a54, 0
	v_accvgpr_write_b32 a53, 0
	v_accvgpr_write_b32 a52, 0
	v_accvgpr_write_b32 a51, 0
	v_accvgpr_write_b32 a50, 0
	v_accvgpr_write_b32 a49, 0
	v_accvgpr_write_b32 a48, 0
	v_accvgpr_write_b32 a79, 0
	v_accvgpr_write_b32 a78, 0
	v_accvgpr_write_b32 a77, 0
	v_accvgpr_write_b32 a76, 0
	v_accvgpr_write_b32 a75, 0
	v_accvgpr_write_b32 a74, 0
	v_accvgpr_write_b32 a73, 0
	v_accvgpr_write_b32 a72, 0
	v_accvgpr_write_b32 a71, 0
	v_accvgpr_write_b32 a70, 0
	v_accvgpr_write_b32 a69, 0
	v_accvgpr_write_b32 a68, 0
	v_accvgpr_write_b32 a67, 0
	v_accvgpr_write_b32 a66, 0
	v_accvgpr_write_b32 a65, 0
	v_accvgpr_write_b32 a64, 0
	v_accvgpr_write_b32 a111, 0
	v_accvgpr_write_b32 a110, 0
	v_accvgpr_write_b32 a109, 0
	v_accvgpr_write_b32 a108, 0
	v_accvgpr_write_b32 a107, 0
	v_accvgpr_write_b32 a106, 0
	v_accvgpr_write_b32 a105, 0
	v_accvgpr_write_b32 a104, 0
	v_accvgpr_write_b32 a103, 0
	v_accvgpr_write_b32 a102, 0
	v_accvgpr_write_b32 a101, 0
	v_accvgpr_write_b32 a100, 0
	v_accvgpr_write_b32 a99, 0
	v_accvgpr_write_b32 a98, 0
	v_accvgpr_write_b32 a97, 0
	v_accvgpr_write_b32 a96, 0
	v_accvgpr_write_b32 a95, 0
	v_accvgpr_write_b32 a94, 0
	v_accvgpr_write_b32 a93, 0
	v_accvgpr_write_b32 a92, 0
	v_accvgpr_write_b32 a91, 0
	v_accvgpr_write_b32 a90, 0
	v_accvgpr_write_b32 a89, 0
	v_accvgpr_write_b32 a88, 0
	v_accvgpr_write_b32 a87, 0
	v_accvgpr_write_b32 a86, 0
	v_accvgpr_write_b32 a85, 0
	v_accvgpr_write_b32 a84, 0
	v_accvgpr_write_b32 a83, 0
	v_accvgpr_write_b32 a82, 0
	v_accvgpr_write_b32 a81, 0
	v_accvgpr_write_b32 a80, 0
	v_accvgpr_write_b32 a127, 0
	v_accvgpr_write_b32 a126, 0
	v_accvgpr_write_b32 a125, 0
	v_accvgpr_write_b32 a124, 0
	v_accvgpr_write_b32 a123, 0
	v_accvgpr_write_b32 a122, 0
	v_accvgpr_write_b32 a121, 0
	v_accvgpr_write_b32 a120, 0
	v_accvgpr_write_b32 a119, 0
	v_accvgpr_write_b32 a118, 0
	v_accvgpr_write_b32 a117, 0
	v_accvgpr_write_b32 a116, 0
	v_accvgpr_write_b32 a115, 0
	v_accvgpr_write_b32 a114, 0
	v_accvgpr_write_b32 a113, 0
	v_accvgpr_write_b32 a112, 0
	v_accvgpr_write_b32 a31, 0
	v_accvgpr_write_b32 a30, 0
	v_accvgpr_write_b32 a29, 0
	v_accvgpr_write_b32 a28, 0
	v_accvgpr_write_b32 a27, 0
	v_accvgpr_write_b32 a26, 0
	v_accvgpr_write_b32 a25, 0
	v_accvgpr_write_b32 a24, 0
	v_accvgpr_write_b32 a23, 0
	v_accvgpr_write_b32 a22, 0
	v_accvgpr_write_b32 a21, 0
	v_accvgpr_write_b32 a20, 0
	v_accvgpr_write_b32 a19, 0
	v_accvgpr_write_b32 a18, 0
	v_accvgpr_write_b32 a17, 0
	v_accvgpr_write_b32 a16, 0
	v_accvgpr_write_b32 a15, 0
	v_accvgpr_write_b32 a14, 0
	v_accvgpr_write_b32 a13, 0
	v_accvgpr_write_b32 a12, 0
	v_accvgpr_write_b32 a11, 0
	v_accvgpr_write_b32 a10, 0
	v_accvgpr_write_b32 a9, 0
	v_accvgpr_write_b32 a8, 0
	v_accvgpr_write_b32 a7, 0
	v_accvgpr_write_b32 a6, 0
	v_accvgpr_write_b32 a5, 0
	v_accvgpr_write_b32 a4, 0
	v_accvgpr_write_b32 a3, 0
	v_accvgpr_write_b32 a2, 0
	v_accvgpr_write_b32 a1, 0
	v_accvgpr_write_b32 a0, 0
	s_mov_b64 s[44:45], 0
	s_waitcnt vmcnt(23)
	ds_write_b128 v45, v[108:111]
	s_waitcnt vmcnt(22)
	ds_write_b128 v45, v[112:115] offset:4608
	s_waitcnt vmcnt(21)
	ds_write_b128 v45, v[116:119] offset:9216
	s_waitcnt vmcnt(20)
	ds_write_b128 v45, v[120:123] offset:13824
	s_waitcnt vmcnt(19)
	ds_write_b128 v45, v[124:127] offset:18432
	s_waitcnt vmcnt(18)
	ds_write_b128 v45, v[128:131] offset:23040
	s_waitcnt vmcnt(17)
	ds_write_b128 v45, v[140:143] offset:27648
	s_waitcnt vmcnt(16)
	ds_write_b128 v45, v[144:147] offset:32256
	s_waitcnt vmcnt(15)
	ds_write_b128 v45, v[148:151] offset:36864
	s_waitcnt vmcnt(14)
	ds_write_b128 v45, v[152:155] offset:41472
	s_waitcnt vmcnt(13)
	ds_write_b128 v45, v[156:159] offset:46080
	s_waitcnt vmcnt(12)
	ds_write_b128 v45, v[160:163] offset:50688
	s_waitcnt lgkmcnt(0)
	s_barrier
	s_waitcnt vmcnt(0)
	v_readfirstlane_b32 s100, v10
	v_readfirstlane_b32 s101, v11
	v_readfirstlane_b32 s98, v12
	v_readfirstlane_b32 s99, v13
	s_nop 1
	v_subrev_u32_e32 v194, s100, v10
	v_subrev_u32_e32 v193, s98, v12
	v_add_u32_e32 v254, s73, v194
	v_add_u32_e32 v205, s74, v194
	v_add_u32_e32 v204, s75, v194
	v_add_u32_e32 v203, s78, v194
	v_add_u32_e32 v202, s79, v194
	v_add_u32_e32 v201, s80, v194
	v_add_u32_e32 v200, s81, v194
	v_add_u32_e32 v199, s82, v194
	v_add_u32_e32 v198, s83, v193
	v_add_u32_e32 v197, s84, v193
	v_add_u32_e32 v196, s85, v193
	v_add_u32_e32 v195, s86, v193
	s_add_u32 s100, s100, s44
	s_addc_u32 s101, s101, s45
	s_add_u32 s98, s98, s44
	s_addc_u32 s99, s99, s45
	v_add_u32_e32 v192, v20, v46
	v_add_u32_e32 v191, v20, v47
	v_add_u32_e32 v190, v20, v48
	s_and_b32 s50, s42, 1
	s_mul_i32 s51, s50, 0xd800
	v_add_u32_e32 v189, s51, v192
	v_add_u32_e32 v188, s51, v191
	v_add_u32_e32 v187, s51, v190
	ds_read_b128 v[108:111], v189
	ds_read_b128 v[14:17], v187 offset:36864
	ds_read_b128 v[112:115], v189 offset:4608
	ds_read_b128 v[64:67], v187 offset:41472
	ds_read_b128 v[116:119], v189 offset:9216
	ds_read_b128 v[120:123], v188
	s_getreg_b32 s50, hwreg(HW_REG_HW_ID, 4, 1)
	s_cmp_lg_u32 s50, 0
	s_cbranch_scc1 xg5_varB_4
	.p2align 6
.LBB0_1265:
	s_and_b32 s50, s42, 1
	s_mul_i32 s51, s50, 0xd800
	s_xor_b32 s50, s50, 1
	s_mul_i32 s50, s50, 0xd800
	s_add_i32 s42, s42, 1
	v_add_u32_e32 v186, s50, v45
	ds_read_b128 v[68:71], v189 offset:32
	ds_read_b128 v[80:83], v187 offset:36896
	ds_read_b128 v[72:75], v189 offset:4640
	ds_read_b128 v[84:87], v187 offset:41504
	ds_read_b128 v[76:79], v189 offset:9248
	ds_read_b128 v[104:107], v188 offset:32
	s_waitcnt lgkmcnt(10)
	v_mfma_f32_32x32x16_bf16 a[32:47], v[108:111], v[14:17], a[32:47]
	s_waitcnt vmcnt(11)
	ds_write_b128 v186, v[250:253]
	s_waitcnt lgkmcnt(9)
	v_mfma_f32_32x32x16_bf16 a[48:63], v[108:111], v[64:67], a[48:63]
	s_waitcnt vmcnt(10)
	ds_write_b128 v186, v[246:249] offset:4608
	global_load_dwordx4 v[250:253], v254, s[100:101] offset:512
	v_mfma_f32_32x32x16_bf16 a[64:79], v[112:115], v[14:17], a[64:79]
	s_waitcnt vmcnt(10)
	ds_write_b128 v186, v[242:245] offset:9216
	global_load_dwordx4 v[246:249], v205, s[100:101] offset:512
	v_mfma_f32_32x32x16_bf16 a[96:111], v[112:115], v[64:67], a[96:111]
	s_waitcnt vmcnt(10)
	ds_write_b128 v186, v[238:241] offset:13824
	global_load_dwordx4 v[242:245], v204, s[100:101] offset:512
	s_waitcnt lgkmcnt(11)
	v_mfma_f32_32x32x16_bf16 a[80:95], v[116:119], v[14:17], a[80:95]
	s_waitcnt vmcnt(10)
	ds_write_b128 v186, v[234:237] offset:18432
	global_load_dwordx4 v[238:241], v203, s[100:101] offset:512
	v_mfma_f32_32x32x16_bf16 a[112:127], v[116:119], v[64:67], a[112:127]
	s_waitcnt vmcnt(10)
	ds_write_b128 v186, v[230:233] offset:23040
	global_load_dwordx4 v[234:237], v202, s[100:101] offset:512
	s_waitcnt lgkmcnt(12)
	v_mfma_f32_32x32x16_bf16 a[16:31], v[120:123], v[14:17], a[16:31]
	s_waitcnt vmcnt(10)
	ds_write_b128 v186, v[226:229] offset:27648
	global_load_dwordx4 v[230:233], v201, s[100:101] offset:512
	v_mfma_f32_32x32x16_bf16 a[0:15], v[120:123], v[64:67], a[0:15]
	s_waitcnt vmcnt(10)
	ds_write_b128 v186, v[222:225] offset:32256
	global_load_dwordx4 v[226:229], v200, s[100:101] offset:512
	ds_read_b128 v[108:111], v189 offset:64
	ds_read_b128 v[14:17], v187 offset:36928
	ds_read_b128 v[112:115], v189 offset:4672
	ds_read_b128 v[64:67], v187 offset:41536
	ds_read_b128 v[116:119], v189 offset:9280
	ds_read_b128 v[120:123], v188 offset:64
	s_waitcnt lgkmcnt(15)
	v_mfma_f32_32x32x16_bf16 a[32:47], v[68:71], v[80:83], a[32:47]
	s_waitcnt vmcnt(10)
	ds_write_b128 v186, v[218:221] offset:36864
	global_load_dwordx4 v[222:225], v199, s[100:101] offset:512
	v_mfma_f32_32x32x16_bf16 a[48:63], v[68:71], v[84:87], a[48:63]
	s_waitcnt vmcnt(10)
	ds_write_b128 v186, v[214:217] offset:41472
	global_load_dwordx4 v[218:221], v198, s[98:99] offset:256
	v_mfma_f32_32x32x16_bf16 a[64:79], v[72:75], v[80:83], a[64:79]
	s_waitcnt vmcnt(10)
	ds_write_b128 v186, v[210:213] offset:46080
	global_load_dwordx4 v[214:217], v197, s[98:99] offset:256
	v_mfma_f32_32x32x16_bf16 a[96:111], v[72:75], v[84:87], a[96:111]
	s_waitcnt vmcnt(10)
	ds_write_b128 v186, v[206:209] offset:50688
	global_load_dwordx4 v[210:213], v196, s[98:99] offset:256
	v_mfma_f32_32x32x16_bf16 a[80:95], v[76:79], v[80:83], a[80:95]
	global_load_dwordx4 v[206:209], v195, s[98:99] offset:256
	s_add_u32 s100, s100, 0x80
	s_addc_u32 s101, s101, 0
	s_add_u32 s98, s98, 0x80
	s_addc_u32 s99, s99, 0
	v_mfma_f32_32x32x16_bf16 a[112:127], v[76:79], v[84:87], a[112:127]
	s_waitcnt lgkmcnt(15)
	v_mfma_f32_32x32x16_bf16 a[16:31], v[104:107], v[80:83], a[16:31]
	v_mfma_f32_32x32x16_bf16 a[0:15], v[104:107], v[84:87], a[0:15]
	ds_read_b128 v[68:71], v189 offset:96
	ds_read_b128 v[80:83], v187 offset:36960
	ds_read_b128 v[72:75], v189 offset:4704
	ds_read_b128 v[84:87], v187 offset:41568
	ds_read_b128 v[76:79], v189 offset:9312
	ds_read_b128 v[104:107], v188 offset:96
	s_waitcnt lgkmcnt(14)
	v_mfma_f32_32x32x16_bf16 a[32:47], v[108:111], v[14:17], a[32:47]
	s_waitcnt lgkmcnt(12)
	v_mfma_f32_32x32x16_bf16 a[48:63], v[108:111], v[64:67], a[48:63]
	v_mfma_f32_32x32x16_bf16 a[64:79], v[112:115], v[14:17], a[64:79]
	v_mfma_f32_32x32x16_bf16 a[96:111], v[112:115], v[64:67], a[96:111]
	s_waitcnt lgkmcnt(11)
	v_mfma_f32_32x32x16_bf16 a[80:95], v[116:119], v[14:17], a[80:95]
	v_mfma_f32_32x32x16_bf16 a[112:127], v[116:119], v[64:67], a[112:127]
	s_waitcnt lgkmcnt(10)
	v_mfma_f32_32x32x16_bf16 a[16:31], v[120:123], v[14:17], a[16:31]
	v_mfma_f32_32x32x16_bf16 a[0:15], v[120:123], v[64:67], a[0:15]
	s_waitcnt lgkmcnt(0)
	v_mfma_f32_32x32x16_bf16 a[32:47], v[68:71], v[80:83], a[32:47]
	v_mfma_f32_32x32x16_bf16 a[48:63], v[68:71], v[84:87], a[48:63]
	v_mfma_f32_32x32x16_bf16 a[64:79], v[72:75], v[80:83], a[64:79]
	v_mfma_f32_32x32x16_bf16 a[96:111], v[72:75], v[84:87], a[96:111]
	s_barrier
	v_add_u32_e32 v189, s50, v192
	v_add_u32_e32 v188, s50, v191
	v_add_u32_e32 v187, s50, v190
	ds_read_b128 v[108:111], v189
	ds_read_b128 v[14:17], v187 offset:36864
	ds_read_b128 v[112:115], v189 offset:4608
	ds_read_b128 v[64:67], v187 offset:41472
	ds_read_b128 v[116:119], v189 offset:9216
	ds_read_b128 v[120:123], v188
	v_mfma_f32_32x32x16_bf16 a[80:95], v[76:79], v[80:83], a[80:95]
	v_mfma_f32_32x32x16_bf16 a[112:127], v[76:79], v[84:87], a[112:127]
	v_mfma_f32_32x32x16_bf16 a[16:31], v[104:107], v[80:83], a[16:31]
	v_mfma_f32_32x32x16_bf16 a[0:15], v[104:107], v[84:87], a[0:15]
	s_add_u32 s44, s44, 0x80
	s_addc_u32 s45, s45, 0
	s_cmpk_lg_i32 s44, 0x700
	s_cbranch_scc1 .LBB0_1265
	s_branch xg5_tail_4
	.p2align 6

.LBB0_1387:
	s_add_i32 s58, s26, 16
	s_cmpk_gt_u32 s26, 0x6f
	s_cselect_b64 s[24:25], -1, 0
	s_cmpk_lt_u32 s26, 0x70
	s_cselect_b64 vcc, -1, 0
	s_bitcmp0_b32 s58, 6
	s_cselect_b64 s[12:13], -1, 0
	v_cndmask_b32_e64 v100, v116, v104, s[12:13]
	v_cndmask_b32_e32 v100, v118, v100, vcc
	s_nop 0
	v_readlane_b32 s28, v100, s58
	s_nop 1
	v_mad_i64_i32 v[148:149], s[12:13], s28, v130, v[96:97]
	global_load_dwordx4 a[20:23], v[148:149], off
	v_mad_i64_i32 v[148:149], s[12:13], s28, v130, v[98:99]
	s_add_i32 s12, s26, 17
	global_load_dwordx2 a[42:43], v[148:149], off
	s_nop 1
	v_readlane_b32 s28, v100, s12
	s_nop 1
	v_mad_i64_i32 v[148:149], s[12:13], s28, v130, v[96:97]
	global_load_dwordx4 a[28:31], v[148:149], off
	v_mad_i64_i32 v[148:149], s[12:13], s28, v130, v[98:99]
	s_add_i32 s12, s26, 18
	global_load_dwordx2 a[44:45], v[148:149], off
	s_nop 1
	v_readlane_b32 s28, v100, s12
	s_nop 1
	v_mad_i64_i32 v[148:149], s[12:13], s28, v130, v[96:97]
	global_load_dwordx4 v[232:235], v[148:149], off
	v_mad_i64_i32 v[148:149], s[12:13], s28, v130, v[98:99]
	s_add_i32 s12, s26, 19
	global_load_dwordx2 a[46:47], v[148:149], off
	s_nop 1
	v_readlane_b32 s28, v100, s12
	s_nop 1
	v_mad_i64_i32 v[148:149], s[12:13], s28, v130, v[96:97]
	global_load_dwordx4 v[236:239], v[148:149], off
	v_mad_i64_i32 v[148:149], s[12:13], s28, v130, v[98:99]
	s_add_i32 s12, s26, 20
	global_load_dwordx2 a[48:49], v[148:149], off
	s_nop 1
	v_readlane_b32 s28, v100, s12
	s_nop 1
	v_mad_i64_i32 v[148:149], s[12:13], s28, v130, v[96:97]
	global_load_dwordx4 v[240:243], v[148:149], off
	v_mad_i64_i32 v[148:149], s[12:13], s28, v130, v[98:99]
	s_add_i32 s12, s26, 21
	global_load_dwordx2 a[50:51], v[148:149], off
	s_nop 1
	v_readlane_b32 s28, v100, s12
	s_nop 1
	v_mad_i64_i32 v[148:149], s[12:13], s28, v130, v[96:97]
	global_load_dwordx4 v[244:247], v[148:149], off
	v_mad_i64_i32 v[148:149], s[12:13], s28, v130, v[98:99]
	s_add_i32 s12, s26, 22
	global_load_dwordx2 a[52:53], v[148:149], off
	s_nop 1
	v_readlane_b32 s28, v100, s12
	s_nop 1
	v_mad_i64_i32 v[148:149], s[12:13], s28, v130, v[96:97]
	global_load_dwordx4 v[248:251], v[148:149], off
	v_mad_i64_i32 v[148:149], s[12:13], s28, v130, v[98:99]
	s_add_i32 s12, s26, 23
	global_load_dwordx2 a[54:55], v[148:149], off
	s_nop 1
	v_readlane_b32 s28, v100, s12
	s_nop 1
	v_mad_i64_i32 v[148:149], s[12:13], s28, v130, v[96:97]
	global_load_dwordx4 a[0:3], v[148:149], off
	v_mad_i64_i32 v[148:149], s[12:13], s28, v130, v[98:99]
	s_add_i32 s12, s26, 24
	global_load_dwordx2 a[56:57], v[148:149], off
	s_nop 1
	v_readlane_b32 s28, v100, s12
	s_nop 1
	v_mad_i64_i32 v[148:149], s[12:13], s28, v130, v[96:97]
	global_load_dwordx4 a[4:7], v[148:149], off
	v_mad_i64_i32 v[148:149], s[12:13], s28, v130, v[98:99]
	s_add_i32 s12, s26, 25
	global_load_dwordx2 a[58:59], v[148:149], off
	s_nop 1
	v_readlane_b32 s28, v100, s12
	s_nop 1
	v_mad_i64_i32 v[148:149], s[12:13], s28, v130, v[96:97]
	global_load_dwordx4 a[8:11], v[148:149], off
	v_mad_i64_i32 v[148:149], s[12:13], s28, v130, v[98:99]
	s_add_i32 s12, s26, 26
	global_load_dwordx2 a[60:61], v[148:149], off
	s_nop 1
	v_readlane_b32 s28, v100, s12
	s_nop 1
	v_mad_i64_i32 v[148:149], s[12:13], s28, v130, v[96:97]
	global_load_dwordx4 a[12:15], v[148:149], off
	v_mad_i64_i32 v[148:149], s[12:13], s28, v130, v[98:99]
	s_add_i32 s12, s26, 27
	global_load_dwordx2 a[62:63], v[148:149], off
	s_nop 1
	v_readlane_b32 s28, v100, s12
	s_nop 1
	v_mad_i64_i32 v[148:149], s[12:13], s28, v130, v[96:97]
	global_load_dwordx4 a[16:19], v[148:149], off
	v_mad_i64_i32 v[148:149], s[12:13], s28, v130, v[98:99]
	s_add_i32 s12, s26, 28
	global_load_dwordx2 a[64:65], v[148:149], off
	s_nop 1
	v_readlane_b32 s28, v100, s12
	s_nop 1
	v_mad_i64_i32 v[148:149], s[12:13], s28, v130, v[96:97]
	global_load_dwordx4 a[24:27], v[148:149], off
	v_mad_i64_i32 v[148:149], s[12:13], s28, v130, v[98:99]
	s_add_i32 s12, s26, 29
	global_load_dwordx2 a[66:67], v[148:149], off
	s_nop 1
	v_readlane_b32 s28, v100, s12
	s_nop 1
	v_mad_i64_i32 v[148:149], s[12:13], s28, v130, v[96:97]
	global_load_dwordx4 v[220:223], v[148:149], off
	v_mad_i64_i32 v[148:149], s[12:13], s28, v130, v[98:99]
	s_add_i32 s12, s26, 30
	global_load_dwordx2 v[148:149], v[148:149], off
	s_nop 1
	v_readlane_b32 s28, v100, s12
	s_nop 1
	v_mad_i64_i32 v[224:225], s[12:13], s28, v130, v[96:97]
	v_mad_i64_i32 v[228:229], s[12:13], s28, v130, v[98:99]
	s_add_i32 s12, s26, 31
	global_load_dwordx4 v[224:227], v[224:225], off
	s_cmp_lg_u32 s26, 64
	s_nop 0
	v_readlane_b32 s28, v100, s12
	global_load_dwordx2 v[252:253], v[228:229], off
	s_nop 0
	v_mad_i64_i32 v[228:229], s[12:13], s28, v130, v[96:97]
	v_mad_i64_i32 v[100:101], s[12:13], s28, v130, v[98:99]
	global_load_dwordx4 v[228:231], v[228:229], off
	s_nop 0
	global_load_dwordx2 a[40:41], v[100:101], off
	s_cbranch_scc1 .LBB0_1389
	global_load_dword a68, v[170:171], off
	global_load_dword a69, v[168:169], off
	global_load_dword v117, v[166:167], off
	global_load_dword v105, v[164:165], off
	.p2align 6

.LBB0_1461:
	s_and_b32 s2, s33, 0xff
	s_mul_i32 s2, s2, 27
	s_lshr_b32 s2, s2, 9
	s_add_i32 s61, s97, s2
	s_lshl_b32 s14, s61, 19
	v_lshl_add_u64 v[8:9], v[82:83], 0, s[14:15]
	v_add_co_u32_e32 v10, vcc, 0x10000, v8
	s_mul_i32 s2, s2, 19
	s_nop 0
	v_addc_co_u32_e32 v11, vcc, 0, v9, vcc
	v_add_co_u32_e32 v20, vcc, 0x20000, v8
	s_sub_i32 s2, s33, s2
	s_nop 0
	v_addc_co_u32_e32 v21, vcc, 0, v9, vcc
	v_add_co_u32_e32 v22, vcc, 0x30000, v8
	s_and_b32 s60, s2, 0xff
	s_nop 0
	v_addc_co_u32_e32 v23, vcc, 0, v9, vcc
	v_add_co_u32_e32 v28, vcc, 0x40000, v8
	global_load_dwordx4 v[0:3], v[8:9], off
	global_load_dwordx4 v[4:7], v[10:11], off
	v_addc_co_u32_e32 v29, vcc, 0, v9, vcc
	v_add_co_u32_e32 v30, vcc, 0x50000, v8
	s_lshl_b32 s2, s60, 18
	s_mov_b32 s3, s15
	v_addc_co_u32_e32 v31, vcc, 0, v9, vcc
	v_lshl_add_u64 v[16:17], v[84:85], 0, s[2:3]
	global_load_dwordx4 v[52:55], v[20:21], off
	global_load_dwordx4 v[76:79], v[16:17], off
	v_add_co_u32_e32 v32, vcc, 0x60000, v8
	global_load_dwordx4 v[56:59], v[22:23], off
	global_load_dwordx4 v[60:63], v[28:29], off
	v_addc_co_u32_e32 v33, vcc, 0, v9, vcc
	v_add_co_u32_e32 v34, vcc, 0x70000, v8
	s_mov_b32 s4, 0x10000
	s_nop 0
	v_addc_co_u32_e32 v35, vcc, 0, v9, vcc
	global_load_dwordx4 v[64:67], v[30:31], off
	global_load_dwordx4 v[68:71], v[32:33], off
	v_add_co_u32_e32 v116, vcc, s4, v16
	s_mov_b32 s4, 0x20000
	s_nop 0
	v_addc_co_u32_e32 v117, vcc, 0, v17, vcc
	global_load_dwordx4 v[72:75], v[34:35], off
	global_load_dwordx4 v[104:107], v[116:117], off
	v_add_co_u32_e32 v118, vcc, s4, v16
	s_mov_b32 s4, 0x30000
	s_nop 0
	v_addc_co_u32_e32 v119, vcc, 0, v17, vcc
	global_load_dwordx4 v[108:111], v[118:119], off
	v_add_co_u32_e32 v120, vcc, s4, v16
	s_mov_b32 s4, 0
	s_nop 0
	v_addc_co_u32_e32 v121, vcc, 0, v17, vcc
	global_load_dwordx4 v[112:115], v[120:121], off
	global_load_dwordx4 v[250:253], v[8:9], off offset:128
	s_nop 0
	global_load_dwordx4 v[246:249], v[10:11], off offset:128
	s_nop 0
	global_load_dwordx4 v[218:221], v[16:17], off offset:128
	s_nop 0
	global_load_dwordx4 v[242:245], v[20:21], off offset:128
	s_nop 0
	global_load_dwordx4 v[238:241], v[22:23], off offset:128
	s_nop 0
	global_load_dwordx4 v[234:237], v[28:29], off offset:128
	global_load_dwordx4 v[230:233], v[30:31], off offset:128
	global_load_dwordx4 v[226:229], v[32:33], off offset:128
	global_load_dwordx4 v[222:225], v[34:35], off offset:128
	s_nop 0
	global_load_dwordx4 v[214:217], v[116:117], off offset:128
	global_load_dwordx4 v[210:213], v[118:119], off offset:128
	v_accvgpr_write_b32 a47, 0
	v_accvgpr_write_b32 a46, 0
	v_accvgpr_write_b32 a45, 0
	v_accvgpr_write_b32 a44, 0
	v_accvgpr_write_b32 a43, 0
	v_accvgpr_write_b32 a42, 0
	v_accvgpr_write_b32 a41, 0
	v_accvgpr_write_b32 a40, 0
	v_accvgpr_write_b32 a39, 0
	v_accvgpr_write_b32 a38, 0
	v_accvgpr_write_b32 a37, 0
	v_accvgpr_write_b32 a36, 0
	v_accvgpr_write_b32 a35, 0
	v_accvgpr_write_b32 a34, 0
	v_accvgpr_write_b32 a33, 0
	v_accvgpr_write_b32 a32, 0
	v_accvgpr_write_b32 a63, 0
	v_accvgpr_write_b32 a62, 0
	v_accvgpr_write_b32 a61, 0
	v_accvgpr_write_b32 a60, 0
	v_accvgpr_write_b32 a59, 0
	v_accvgpr_write_b32 a58, 0
	v_accvgpr_write_b32 a57, 0
	v_accvgpr_write_b32 a56, 0
	v_accvgpr_write_b32 a55, 0
	s_waitcnt vmcnt(22)
	ds_write_b128 v152, v[0:3]
	s_waitcnt vmcnt(21)
	ds_write_b128 v152, v[4:7] offset:4608
	s_waitcnt vmcnt(19)
	ds_write_b128 v152, v[76:79] offset:36864
	ds_write_b128 v152, v[52:55] offset:9216
	s_waitcnt vmcnt(18)
	ds_write_b128 v152, v[56:59] offset:13824
	s_waitcnt vmcnt(17)
	ds_write_b128 v152, v[60:63] offset:18432
	s_waitcnt vmcnt(16)
	ds_write_b128 v152, v[64:67] offset:23040
	s_waitcnt vmcnt(15)
	ds_write_b128 v152, v[68:71] offset:27648
	s_waitcnt vmcnt(14)
	ds_write_b128 v152, v[72:75] offset:32256
	s_waitcnt vmcnt(13)
	ds_write_b128 v152, v[104:107] offset:41472
	s_waitcnt vmcnt(12)
	ds_write_b128 v152, v[108:111] offset:46080
	global_load_dwordx4 v[206:209], v[120:121], off offset:128
	v_lshl_add_u64 v[4:5], v[102:103], 0, s[14:15]
	v_lshl_add_u64 v[6:7], v[102:103], 0, s[2:3]
	v_accvgpr_write_b32 a54, 0
	v_accvgpr_write_b32 a53, 0
	v_accvgpr_write_b32 a52, 0
	v_accvgpr_write_b32 a51, 0
	v_accvgpr_write_b32 a50, 0
	v_accvgpr_write_b32 a49, 0
	v_accvgpr_write_b32 a48, 0
	v_accvgpr_write_b32 a79, 0
	v_accvgpr_write_b32 a78, 0
	v_accvgpr_write_b32 a77, 0
	v_accvgpr_write_b32 a76, 0
	v_accvgpr_write_b32 a75, 0
	v_accvgpr_write_b32 a74, 0
	v_accvgpr_write_b32 a73, 0
	v_accvgpr_write_b32 a72, 0
	v_accvgpr_write_b32 a71, 0
	v_accvgpr_write_b32 a70, 0
	v_accvgpr_write_b32 a69, 0
	v_accvgpr_write_b32 a68, 0
	v_accvgpr_write_b32 a67, 0
	v_accvgpr_write_b32 a66, 0
	v_accvgpr_write_b32 a65, 0
	v_accvgpr_write_b32 a64, 0
	v_accvgpr_write_b32 a111, 0
	v_accvgpr_write_b32 a110, 0
	v_accvgpr_write_b32 a109, 0
	v_accvgpr_write_b32 a108, 0
	v_accvgpr_write_b32 a107, 0
	v_accvgpr_write_b32 a106, 0
	v_accvgpr_write_b32 a105, 0
	v_accvgpr_write_b32 a104, 0
	v_accvgpr_write_b32 a103, 0
	v_accvgpr_write_b32 a102, 0
	v_accvgpr_write_b32 a101, 0
	v_accvgpr_write_b32 a100, 0
	v_accvgpr_write_b32 a99, 0
	v_accvgpr_write_b32 a98, 0
	v_accvgpr_write_b32 a97, 0
	v_accvgpr_write_b32 a96, 0
	v_accvgpr_write_b32 a95, 0
	v_accvgpr_write_b32 a94, 0
	v_accvgpr_write_b32 a93, 0
	v_accvgpr_write_b32 a92, 0
	v_accvgpr_write_b32 a91, 0
	v_accvgpr_write_b32 a90, 0
	v_accvgpr_write_b32 a89, 0
	v_accvgpr_write_b32 a88, 0
	v_accvgpr_write_b32 a87, 0
	v_accvgpr_write_b32 a86, 0
	v_accvgpr_write_b32 a85, 0
	v_accvgpr_write_b32 a84, 0
	v_accvgpr_write_b32 a83, 0
	v_accvgpr_write_b32 a82, 0
	v_accvgpr_write_b32 a81, 0
	v_accvgpr_write_b32 a80, 0
	v_accvgpr_write_b32 a127, 0
	v_accvgpr_write_b32 a126, 0
	v_accvgpr_write_b32 a125, 0
	v_accvgpr_write_b32 a124, 0
	v_accvgpr_write_b32 a123, 0
	v_accvgpr_write_b32 a122, 0
	v_accvgpr_write_b32 a121, 0
	v_accvgpr_write_b32 a120, 0
	v_accvgpr_write_b32 a119, 0
	v_accvgpr_write_b32 a118, 0
	v_accvgpr_write_b32 a117, 0
	v_accvgpr_write_b32 a116, 0
	v_accvgpr_write_b32 a115, 0
	v_accvgpr_write_b32 a114, 0
	v_accvgpr_write_b32 a113, 0
	v_accvgpr_write_b32 a112, 0
	v_accvgpr_write_b32 a31, 0
	v_accvgpr_write_b32 a30, 0
	v_accvgpr_write_b32 a29, 0
	v_accvgpr_write_b32 a28, 0
	v_accvgpr_write_b32 a27, 0
	v_accvgpr_write_b32 a26, 0
	v_accvgpr_write_b32 a25, 0
	v_accvgpr_write_b32 a24, 0
	v_accvgpr_write_b32 a23, 0
	v_accvgpr_write_b32 a22, 0
	v_accvgpr_write_b32 a21, 0
	v_accvgpr_write_b32 a20, 0
	v_accvgpr_write_b32 a19, 0
	v_accvgpr_write_b32 a18, 0
	v_accvgpr_write_b32 a17, 0
	v_accvgpr_write_b32 a16, 0
	v_accvgpr_write_b32 a15, 0
	v_accvgpr_write_b32 a14, 0
	v_accvgpr_write_b32 a13, 0
	v_accvgpr_write_b32 a12, 0
	v_accvgpr_write_b32 a11, 0
	v_accvgpr_write_b32 a10, 0
	v_accvgpr_write_b32 a9, 0
	v_accvgpr_write_b32 a8, 0
	v_accvgpr_write_b32 a7, 0
	v_accvgpr_write_b32 a6, 0
	v_accvgpr_write_b32 a5, 0
	v_accvgpr_write_b32 a4, 0
	v_accvgpr_write_b32 a3, 0
	v_accvgpr_write_b32 a2, 0
	v_accvgpr_write_b32 a1, 0
	v_accvgpr_write_b32 a0, 0
	s_mov_b64 s[2:3], 0
	s_waitcnt vmcnt(12)
	ds_write_b128 v152, v[112:115] offset:50688
	s_waitcnt lgkmcnt(0)
	s_barrier
	s_waitcnt vmcnt(0)
	v_readfirstlane_b32 s100, v4
	v_readfirstlane_b32 s101, v5
	v_readfirstlane_b32 s98, v6
	v_readfirstlane_b32 s99, v7
	s_nop 1
	v_subrev_u32_e32 v194, s100, v4
	v_subrev_u32_e32 v193, s98, v6
	v_add_u32_e32 v254, 0x126fa000, v194
	v_add_u32_e32 v205, 0x1270a000, v194
	v_add_u32_e32 v204, 0x1271a000, v194
	v_add_u32_e32 v203, 0x1272a000, v194
	v_add_u32_e32 v202, 0x1273a000, v194
	v_add_u32_e32 v201, 0x1274a000, v194
	v_add_u32_e32 v200, 0x1275a000, v194
	v_add_u32_e32 v199, 0x1276a000, v194
	v_add_u32_e32 v198, 0x4c0000, v193
	v_add_u32_e32 v197, 0x4d0000, v193
	v_add_u32_e32 v196, 0x4e0000, v193
	v_add_u32_e32 v195, 0x4f0000, v193
	s_add_u32 s100, s100, s2
	s_addc_u32 s101, s101, s3
	s_add_u32 s98, s98, s2
	s_addc_u32 s99, s99, s3
	v_add_u32_e32 v192, v148, v153
	v_add_u32_e32 v191, v148, v154
	v_add_u32_e32 v190, v148, v155
	s_and_b32 s5, s4, 1
	s_mul_i32 s8, s5, 0xd800
	v_add_u32_e32 v189, s8, v192
	v_add_u32_e32 v188, s8, v191
	v_add_u32_e32 v187, s8, v190
	ds_read_b128 v[52:55], v189
	ds_read_b128 v[8:11], v187 offset:36864
	ds_read_b128 v[56:59], v189 offset:4608
	ds_read_b128 v[12:15], v187 offset:41472
	ds_read_b128 v[60:63], v189 offset:9216
	ds_read_b128 v[64:67], v188
	s_getreg_b32 s5, hwreg(HW_REG_HW_ID, 4, 1)
	s_cmp_lg_u32 s5, 0
	s_cbranch_scc1 xg5_varB_5
	.p2align 6
.LBB0_1462:
	s_and_b32 s5, s4, 1
	s_mul_i32 s8, s5, 0xd800
	s_xor_b32 s5, s5, 1
	s_mul_i32 s5, s5, 0xd800
	s_add_i32 s4, s4, 1
	v_add_u32_e32 v186, s5, v152
	ds_read_b128 v[16:19], v189 offset:32
	ds_read_b128 v[28:31], v187 offset:36896
	ds_read_b128 v[20:23], v189 offset:4640
	ds_read_b128 v[32:35], v187 offset:41504
	ds_read_b128 v[24:27], v189 offset:9248
	ds_read_b128 v[0:3], v188 offset:32
	s_waitcnt lgkmcnt(10)
	v_mfma_f32_32x32x16_bf16 a[32:47], v[52:55], v[8:11], a[32:47]
	s_waitcnt vmcnt(11)
	ds_write_b128 v186, v[250:253]
	s_waitcnt lgkmcnt(9)
	v_mfma_f32_32x32x16_bf16 a[48:63], v[52:55], v[12:15], a[48:63]
	s_waitcnt vmcnt(10)
	ds_write_b128 v186, v[246:249] offset:4608
	global_load_dwordx4 v[250:253], v254, s[100:101] offset:512
	v_mfma_f32_32x32x16_bf16 a[64:79], v[56:59], v[8:11], a[64:79]
	s_waitcnt vmcnt(10)
	ds_write_b128 v186, v[242:245] offset:9216
	global_load_dwordx4 v[246:249], v205, s[100:101] offset:512
	v_mfma_f32_32x32x16_bf16 a[96:111], v[56:59], v[12:15], a[96:111]
	s_waitcnt vmcnt(10)
	ds_write_b128 v186, v[238:241] offset:13824
	global_load_dwordx4 v[242:245], v204, s[100:101] offset:512
	s_waitcnt lgkmcnt(11)
	v_mfma_f32_32x32x16_bf16 a[80:95], v[60:63], v[8:11], a[80:95]
	s_waitcnt vmcnt(10)
	ds_write_b128 v186, v[234:237] offset:18432
	global_load_dwordx4 v[238:241], v203, s[100:101] offset:512
	v_mfma_f32_32x32x16_bf16 a[112:127], v[60:63], v[12:15], a[112:127]
	s_waitcnt vmcnt(10)
	ds_write_b128 v186, v[230:233] offset:23040
	global_load_dwordx4 v[234:237], v202, s[100:101] offset:512
	s_waitcnt lgkmcnt(12)
	v_mfma_f32_32x32x16_bf16 a[16:31], v[64:67], v[8:11], a[16:31]
	s_waitcnt vmcnt(10)
	ds_write_b128 v186, v[226:229] offset:27648
	global_load_dwordx4 v[230:233], v201, s[100:101] offset:512
	v_mfma_f32_32x32x16_bf16 a[0:15], v[64:67], v[12:15], a[0:15]
	s_waitcnt vmcnt(10)
	ds_write_b128 v186, v[222:225] offset:32256
	global_load_dwordx4 v[226:229], v200, s[100:101] offset:512
	ds_read_b128 v[52:55], v189 offset:64
	ds_read_b128 v[8:11], v187 offset:36928
	ds_read_b128 v[56:59], v189 offset:4672
	ds_read_b128 v[12:15], v187 offset:41536
	ds_read_b128 v[60:63], v189 offset:9280
	ds_read_b128 v[64:67], v188 offset:64
	s_waitcnt lgkmcnt(15)
	v_mfma_f32_32x32x16_bf16 a[32:47], v[16:19], v[28:31], a[32:47]
	s_waitcnt vmcnt(10)
	ds_write_b128 v186, v[218:221] offset:36864
	global_load_dwordx4 v[222:225], v199, s[100:101] offset:512
	v_mfma_f32_32x32x16_bf16 a[48:63], v[16:19], v[32:35], a[48:63]
	s_waitcnt vmcnt(10)
	ds_write_b128 v186, v[214:217] offset:41472
	global_load_dwordx4 v[218:221], v198, s[98:99] offset:256
	v_mfma_f32_32x32x16_bf16 a[64:79], v[20:23], v[28:31], a[64:79]
	s_waitcnt vmcnt(10)
	ds_write_b128 v186, v[210:213] offset:46080
	global_load_dwordx4 v[214:217], v197, s[98:99] offset:256
	v_mfma_f32_32x32x16_bf16 a[96:111], v[20:23], v[32:35], a[96:111]
	s_waitcnt vmcnt(10)
	ds_write_b128 v186, v[206:209] offset:50688
	global_load_dwordx4 v[210:213], v196, s[98:99] offset:256
	v_mfma_f32_32x32x16_bf16 a[80:95], v[24:27], v[28:31], a[80:95]
	global_load_dwordx4 v[206:209], v195, s[98:99] offset:256
	s_add_u32 s100, s100, 0x80
	s_addc_u32 s101, s101, 0
	s_add_u32 s98, s98, 0x80
	s_addc_u32 s99, s99, 0
	v_mfma_f32_32x32x16_bf16 a[112:127], v[24:27], v[32:35], a[112:127]
	s_waitcnt lgkmcnt(15)
	v_mfma_f32_32x32x16_bf16 a[16:31], v[0:3], v[28:31], a[16:31]
	v_mfma_f32_32x32x16_bf16 a[0:15], v[0:3], v[32:35], a[0:15]
	ds_read_b128 v[16:19], v189 offset:96
	ds_read_b128 v[28:31], v187 offset:36960
	ds_read_b128 v[20:23], v189 offset:4704
	ds_read_b128 v[32:35], v187 offset:41568
	ds_read_b128 v[24:27], v189 offset:9312
	ds_read_b128 v[0:3], v188 offset:96
	s_waitcnt lgkmcnt(14)
	v_mfma_f32_32x32x16_bf16 a[32:47], v[52:55], v[8:11], a[32:47]
	s_waitcnt lgkmcnt(12)
	v_mfma_f32_32x32x16_bf16 a[48:63], v[52:55], v[12:15], a[48:63]
	v_mfma_f32_32x32x16_bf16 a[64:79], v[56:59], v[8:11], a[64:79]
	v_mfma_f32_32x32x16_bf16 a[96:111], v[56:59], v[12:15], a[96:111]
	s_waitcnt lgkmcnt(11)
	v_mfma_f32_32x32x16_bf16 a[80:95], v[60:63], v[8:11], a[80:95]
	v_mfma_f32_32x32x16_bf16 a[112:127], v[60:63], v[12:15], a[112:127]
	s_waitcnt lgkmcnt(10)
	v_mfma_f32_32x32x16_bf16 a[16:31], v[64:67], v[8:11], a[16:31]
	v_mfma_f32_32x32x16_bf16 a[0:15], v[64:67], v[12:15], a[0:15]
	s_waitcnt lgkmcnt(0)
	v_mfma_f32_32x32x16_bf16 a[32:47], v[16:19], v[28:31], a[32:47]
	v_mfma_f32_32x32x16_bf16 a[48:63], v[16:19], v[32:35], a[48:63]
	v_mfma_f32_32x32x16_bf16 a[64:79], v[20:23], v[28:31], a[64:79]
	v_mfma_f32_32x32x16_bf16 a[96:111], v[20:23], v[32:35], a[96:111]
	s_barrier
	v_add_u32_e32 v189, s5, v192
	v_add_u32_e32 v188, s5, v191
	v_add_u32_e32 v187, s5, v190
	ds_read_b128 v[52:55], v189
	ds_read_b128 v[8:11], v187 offset:36864
	ds_read_b128 v[56:59], v189 offset:4608
	ds_read_b128 v[12:15], v187 offset:41472
	ds_read_b128 v[60:63], v189 offset:9216
	ds_read_b128 v[64:67], v188
	v_mfma_f32_32x32x16_bf16 a[80:95], v[24:27], v[28:31], a[80:95]
	v_mfma_f32_32x32x16_bf16 a[112:127], v[24:27], v[32:35], a[112:127]
	v_mfma_f32_32x32x16_bf16 a[16:31], v[0:3], v[28:31], a[16:31]
	v_mfma_f32_32x32x16_bf16 a[0:15], v[0:3], v[32:35], a[0:15]
	s_add_u32 s2, s2, 0x80
	s_addc_u32 s3, s3, 0
	s_cmpk_lg_i32 s2, 0x700
	s_cbranch_scc1 .LBB0_1462
	s_branch xg5_tail_5
	.p2align 6

.LBB0_1963:
	s_lshr_b32 s48, s47, 3
	s_lshl_b32 s42, s48, 18
	s_add_i32 s42, s68, s42
	v_lshl_add_u64 v[10:11], s[42:43], 1, v[8:9]
	s_and_b32 s42, s46, 7
	s_lshl_b32 s42, s42, 18
	s_add_i32 s48, s48, s65
	v_lshl_add_u64 v[12:13], v[8:9], 0, s[42:43]
	s_lshl_b32 s42, s48, 19
	v_lshl_add_u64 v[14:15], v[2:3], 0, s[42:43]
	v_add_co_u32_e32 v16, vcc, s69, v14
	s_and_b32 s49, s47, 7
	s_nop 0
	v_addc_co_u32_e32 v17, vcc, 0, v15, vcc
	v_add_co_u32_e32 v18, vcc, s70, v14
	s_lshl_b32 s42, s49, 18
	s_nop 0
	v_addc_co_u32_e32 v19, vcc, 0, v15, vcc
	v_add_co_u32_e32 v76, vcc, s71, v14
	v_lshl_add_u64 v[90:91], v[4:5], 0, s[42:43]
	s_nop 0
	v_addc_co_u32_e32 v77, vcc, 0, v15, vcc
	v_add_co_u32_e32 v78, vcc, s72, v14
	global_load_dwordx4 v[108:111], v[14:15], off
	global_load_dwordx4 v[112:115], v[16:17], off
	v_addc_co_u32_e32 v79, vcc, 0, v15, vcc
	v_add_co_u32_e32 v80, vcc, s73, v14
	global_load_dwordx4 v[116:119], v[18:19], off
	global_load_dwordx4 v[120:123], v[76:77], off
	v_addc_co_u32_e32 v81, vcc, 0, v15, vcc
	v_add_co_u32_e32 v82, vcc, s74, v14
	global_load_dwordx4 v[124:127], v[78:79], off
	global_load_dwordx4 v[128:131], v[80:81], off
	v_addc_co_u32_e32 v83, vcc, 0, v15, vcc
	v_add_co_u32_e32 v88, vcc, s75, v14
	global_load_dwordx4 v[140:143], v[82:83], off
	s_nop 0
	v_addc_co_u32_e32 v89, vcc, 0, v15, vcc
	v_add_co_u32_e32 v92, vcc, s69, v90
	global_load_dwordx4 v[144:147], v[88:89], off
	s_nop 0
	v_addc_co_u32_e32 v93, vcc, 0, v91, vcc
	v_add_co_u32_e32 v104, vcc, s70, v90
	global_load_dwordx4 v[148:151], v[90:91], off
	global_load_dwordx4 v[152:155], v[92:93], off
	v_addc_co_u32_e32 v105, vcc, 0, v91, vcc
	v_add_co_u32_e32 v106, vcc, s71, v90
	global_load_dwordx4 v[156:159], v[104:105], off
	s_nop 0
	v_addc_co_u32_e32 v107, vcc, 0, v91, vcc
	global_load_dwordx4 v[160:163], v[106:107], off
	global_load_dwordx4 v[250:253], v[14:15], off offset:128
	global_load_dwordx4 v[246:249], v[16:17], off offset:128
	global_load_dwordx4 v[242:245], v[18:19], off offset:128
	s_nop 0
	global_load_dwordx4 v[238:241], v[76:77], off offset:128
	global_load_dwordx4 v[234:237], v[78:79], off offset:128
	global_load_dwordx4 v[230:233], v[80:81], off offset:128
	s_nop 0
	global_load_dwordx4 v[226:229], v[82:83], off offset:128
	s_nop 0
	global_load_dwordx4 v[222:225], v[88:89], off offset:128
	global_load_dwordx4 v[218:221], v[90:91], off offset:128
	s_nop 0
	global_load_dwordx4 v[214:217], v[92:93], off offset:128
	s_nop 0
	global_load_dwordx4 v[210:213], v[104:105], off offset:128
	s_nop 0
	global_load_dwordx4 v[206:209], v[106:107], off offset:128
	s_mov_b32 s42, 0
	v_accvgpr_write_b32 a47, 0
	v_accvgpr_write_b32 a46, 0
	v_accvgpr_write_b32 a45, 0
	v_accvgpr_write_b32 a44, 0
	v_accvgpr_write_b32 a43, 0
	v_accvgpr_write_b32 a42, 0
	v_accvgpr_write_b32 a41, 0
	v_accvgpr_write_b32 a40, 0
	v_accvgpr_write_b32 a39, 0
	v_accvgpr_write_b32 a38, 0
	v_accvgpr_write_b32 a37, 0
	v_accvgpr_write_b32 a36, 0
	v_accvgpr_write_b32 a35, 0
	v_accvgpr_write_b32 a34, 0
	v_accvgpr_write_b32 a33, 0
	v_accvgpr_write_b32 a32, 0
	v_accvgpr_write_b32 a63, 0
	v_accvgpr_write_b32 a62, 0
	v_accvgpr_write_b32 a61, 0
	v_accvgpr_write_b32 a60, 0
	v_accvgpr_write_b32 a59, 0
	v_accvgpr_write_b32 a58, 0
	v_accvgpr_write_b32 a57, 0
	v_accvgpr_write_b32 a56, 0
	v_accvgpr_write_b32 a55, 0
	v_accvgpr_write_b32 a54, 0
	v_accvgpr_write_b32 a53, 0
	v_accvgpr_write_b32 a52, 0
	v_accvgpr_write_b32 a51, 0
	v_accvgpr_write_b32 a50, 0
	v_accvgpr_write_b32 a49, 0
	v_accvgpr_write_b32 a48, 0
	v_accvgpr_write_b32 a79, 0
	v_accvgpr_write_b32 a78, 0
	v_accvgpr_write_b32 a77, 0
	v_accvgpr_write_b32 a76, 0
	v_accvgpr_write_b32 a75, 0
	v_accvgpr_write_b32 a74, 0
	v_accvgpr_write_b32 a73, 0
	v_accvgpr_write_b32 a72, 0
	v_accvgpr_write_b32 a71, 0
	v_accvgpr_write_b32 a70, 0
	v_accvgpr_write_b32 a69, 0
	v_accvgpr_write_b32 a68, 0
	v_accvgpr_write_b32 a67, 0
	v_accvgpr_write_b32 a66, 0
	v_accvgpr_write_b32 a65, 0
	v_accvgpr_write_b32 a64, 0
	v_accvgpr_write_b32 a111, 0
	v_accvgpr_write_b32 a110, 0
	v_accvgpr_write_b32 a109, 0
	v_accvgpr_write_b32 a108, 0
	v_accvgpr_write_b32 a107, 0
	v_accvgpr_write_b32 a106, 0
	v_accvgpr_write_b32 a105, 0
	v_accvgpr_write_b32 a104, 0
	v_accvgpr_write_b32 a103, 0
	v_accvgpr_write_b32 a102, 0
	v_accvgpr_write_b32 a101, 0
	v_accvgpr_write_b32 a100, 0
	v_accvgpr_write_b32 a99, 0
	v_accvgpr_write_b32 a98, 0
	v_accvgpr_write_b32 a97, 0
	v_accvgpr_write_b32 a96, 0
	v_accvgpr_write_b32 a95, 0
	v_accvgpr_write_b32 a94, 0
	v_accvgpr_write_b32 a93, 0
	v_accvgpr_write_b32 a92, 0
	v_accvgpr_write_b32 a91, 0
	v_accvgpr_write_b32 a90, 0
	v_accvgpr_write_b32 a89, 0
	v_accvgpr_write_b32 a88, 0
	v_accvgpr_write_b32 a87, 0
	v_accvgpr_write_b32 a86, 0
	v_accvgpr_write_b32 a85, 0
	v_accvgpr_write_b32 a84, 0
	v_accvgpr_write_b32 a83, 0
	v_accvgpr_write_b32 a82, 0
	v_accvgpr_write_b32 a81, 0
	v_accvgpr_write_b32 a80, 0
	v_accvgpr_write_b32 a127, 0
	v_accvgpr_write_b32 a126, 0
	v_accvgpr_write_b32 a125, 0
	v_accvgpr_write_b32 a124, 0
	v_accvgpr_write_b32 a123, 0
	v_accvgpr_write_b32 a122, 0
	v_accvgpr_write_b32 a121, 0
	v_accvgpr_write_b32 a120, 0
	v_accvgpr_write_b32 a119, 0
	v_accvgpr_write_b32 a118, 0
	v_accvgpr_write_b32 a117, 0
	v_accvgpr_write_b32 a116, 0
	v_accvgpr_write_b32 a115, 0
	v_accvgpr_write_b32 a114, 0
	v_accvgpr_write_b32 a113, 0
	v_accvgpr_write_b32 a112, 0
	v_accvgpr_write_b32 a31, 0
	v_accvgpr_write_b32 a30, 0
	v_accvgpr_write_b32 a29, 0
	v_accvgpr_write_b32 a28, 0
	v_accvgpr_write_b32 a27, 0
	v_accvgpr_write_b32 a26, 0
	v_accvgpr_write_b32 a25, 0
	v_accvgpr_write_b32 a24, 0
	v_accvgpr_write_b32 a23, 0
	v_accvgpr_write_b32 a22, 0
	v_accvgpr_write_b32 a21, 0
	v_accvgpr_write_b32 a20, 0
	v_accvgpr_write_b32 a19, 0
	v_accvgpr_write_b32 a18, 0
	v_accvgpr_write_b32 a17, 0
	v_accvgpr_write_b32 a16, 0
	v_accvgpr_write_b32 a15, 0
	v_accvgpr_write_b32 a14, 0
	v_accvgpr_write_b32 a13, 0
	v_accvgpr_write_b32 a12, 0
	v_accvgpr_write_b32 a11, 0
	v_accvgpr_write_b32 a10, 0
	v_accvgpr_write_b32 a9, 0
	v_accvgpr_write_b32 a8, 0
	v_accvgpr_write_b32 a7, 0
	v_accvgpr_write_b32 a6, 0
	v_accvgpr_write_b32 a5, 0
	v_accvgpr_write_b32 a4, 0
	v_accvgpr_write_b32 a3, 0
	v_accvgpr_write_b32 a2, 0
	v_accvgpr_write_b32 a1, 0
	v_accvgpr_write_b32 a0, 0
	s_mov_b64 s[44:45], 0
	s_waitcnt vmcnt(23)
	ds_write_b128 v45, v[108:111]
	s_waitcnt vmcnt(22)
	ds_write_b128 v45, v[112:115] offset:4608
	s_waitcnt vmcnt(21)
	ds_write_b128 v45, v[116:119] offset:9216
	s_waitcnt vmcnt(20)
	ds_write_b128 v45, v[120:123] offset:13824
	s_waitcnt vmcnt(19)
	ds_write_b128 v45, v[124:127] offset:18432
	s_waitcnt vmcnt(18)
	ds_write_b128 v45, v[128:131] offset:23040
	s_waitcnt vmcnt(17)
	ds_write_b128 v45, v[140:143] offset:27648
	s_waitcnt vmcnt(16)
	ds_write_b128 v45, v[144:147] offset:32256
	s_waitcnt vmcnt(15)
	ds_write_b128 v45, v[148:151] offset:36864
	s_waitcnt vmcnt(14)
	ds_write_b128 v45, v[152:155] offset:41472
	s_waitcnt vmcnt(13)
	ds_write_b128 v45, v[156:159] offset:46080
	s_waitcnt vmcnt(12)
	ds_write_b128 v45, v[160:163] offset:50688
	s_waitcnt lgkmcnt(0)
	s_barrier
	s_waitcnt vmcnt(0)
	v_readfirstlane_b32 s100, v10
	v_readfirstlane_b32 s101, v11
	v_readfirstlane_b32 s98, v12
	v_readfirstlane_b32 s99, v13
	s_nop 1
	v_subrev_u32_e32 v194, s100, v10
	v_subrev_u32_e32 v193, s98, v12
	v_add_u32_e32 v254, s78, v194
	v_add_u32_e32 v205, s79, v194
	v_add_u32_e32 v204, s80, v194
	v_add_u32_e32 v203, s81, v194
	v_add_u32_e32 v202, s82, v194
	v_add_u32_e32 v201, s83, v194
	v_add_u32_e32 v200, s84, v194
	v_add_u32_e32 v199, s85, v194
	v_add_u32_e32 v198, s86, v193
	v_add_u32_e32 v197, s87, v193
	v_add_u32_e32 v196, s88, v193
	v_add_u32_e32 v195, s89, v193
	s_add_u32 s100, s100, s44
	s_addc_u32 s101, s101, s45
	s_add_u32 s98, s98, s44
	s_addc_u32 s99, s99, s45
	v_add_u32_e32 v192, v20, v46
	v_add_u32_e32 v191, v20, v47
	v_add_u32_e32 v190, v20, v48
	s_and_b32 s50, s42, 1
	s_mul_i32 s51, s50, 0xd800
	v_add_u32_e32 v189, s51, v192
	v_add_u32_e32 v188, s51, v191
	v_add_u32_e32 v187, s51, v190
	ds_read_b128 v[108:111], v189
	ds_read_b128 v[14:17], v187 offset:36864
	ds_read_b128 v[112:115], v189 offset:4608
	ds_read_b128 v[64:67], v187 offset:41472
	ds_read_b128 v[116:119], v189 offset:9216
	ds_read_b128 v[120:123], v188
	s_getreg_b32 s50, hwreg(HW_REG_HW_ID, 4, 1)
	s_cmp_lg_u32 s50, 0
	s_cbranch_scc1 xg5_varB_6
	.p2align 6
.LBB0_1964:
	s_and_b32 s50, s42, 1
	s_mul_i32 s51, s50, 0xd800
	s_xor_b32 s50, s50, 1
	s_mul_i32 s50, s50, 0xd800
	s_add_i32 s42, s42, 1
	v_add_u32_e32 v186, s50, v45
	ds_read_b128 v[68:71], v189 offset:32
	ds_read_b128 v[80:83], v187 offset:36896
	ds_read_b128 v[72:75], v189 offset:4640
	ds_read_b128 v[84:87], v187 offset:41504
	ds_read_b128 v[76:79], v189 offset:9248
	ds_read_b128 v[104:107], v188 offset:32
	s_waitcnt lgkmcnt(10)
	v_mfma_f32_32x32x16_bf16 a[32:47], v[108:111], v[14:17], a[32:47]
	s_waitcnt vmcnt(11)
	ds_write_b128 v186, v[250:253]
	s_waitcnt lgkmcnt(9)
	v_mfma_f32_32x32x16_bf16 a[48:63], v[108:111], v[64:67], a[48:63]
	s_waitcnt vmcnt(10)
	ds_write_b128 v186, v[246:249] offset:4608
	global_load_dwordx4 v[250:253], v254, s[100:101] offset:512
	v_mfma_f32_32x32x16_bf16 a[64:79], v[112:115], v[14:17], a[64:79]
	s_waitcnt vmcnt(10)
	ds_write_b128 v186, v[242:245] offset:9216
	global_load_dwordx4 v[246:249], v205, s[100:101] offset:512
	v_mfma_f32_32x32x16_bf16 a[96:111], v[112:115], v[64:67], a[96:111]
	s_waitcnt vmcnt(10)
	ds_write_b128 v186, v[238:241] offset:13824
	global_load_dwordx4 v[242:245], v204, s[100:101] offset:512
	s_waitcnt lgkmcnt(11)
	v_mfma_f32_32x32x16_bf16 a[80:95], v[116:119], v[14:17], a[80:95]
	s_waitcnt vmcnt(10)
	ds_write_b128 v186, v[234:237] offset:18432
	global_load_dwordx4 v[238:241], v203, s[100:101] offset:512
	v_mfma_f32_32x32x16_bf16 a[112:127], v[116:119], v[64:67], a[112:127]
	s_waitcnt vmcnt(10)
	ds_write_b128 v186, v[230:233] offset:23040
	global_load_dwordx4 v[234:237], v202, s[100:101] offset:512
	s_waitcnt lgkmcnt(12)
	v_mfma_f32_32x32x16_bf16 a[16:31], v[120:123], v[14:17], a[16:31]
	s_waitcnt vmcnt(10)
	ds_write_b128 v186, v[226:229] offset:27648
	global_load_dwordx4 v[230:233], v201, s[100:101] offset:512
	v_mfma_f32_32x32x16_bf16 a[0:15], v[120:123], v[64:67], a[0:15]
	s_waitcnt vmcnt(10)
	ds_write_b128 v186, v[222:225] offset:32256
	global_load_dwordx4 v[226:229], v200, s[100:101] offset:512
	ds_read_b128 v[108:111], v189 offset:64
	ds_read_b128 v[14:17], v187 offset:36928
	ds_read_b128 v[112:115], v189 offset:4672
	ds_read_b128 v[64:67], v187 offset:41536
	ds_read_b128 v[116:119], v189 offset:9280
	ds_read_b128 v[120:123], v188 offset:64
	s_waitcnt lgkmcnt(15)
	v_mfma_f32_32x32x16_bf16 a[32:47], v[68:71], v[80:83], a[32:47]
	s_waitcnt vmcnt(10)
	ds_write_b128 v186, v[218:221] offset:36864
	global_load_dwordx4 v[222:225], v199, s[100:101] offset:512
	v_mfma_f32_32x32x16_bf16 a[48:63], v[68:71], v[84:87], a[48:63]
	s_waitcnt vmcnt(10)
	ds_write_b128 v186, v[214:217] offset:41472
	global_load_dwordx4 v[218:221], v198, s[98:99] offset:256
	v_mfma_f32_32x32x16_bf16 a[64:79], v[72:75], v[80:83], a[64:79]
	s_waitcnt vmcnt(10)
	ds_write_b128 v186, v[210:213] offset:46080
	global_load_dwordx4 v[214:217], v197, s[98:99] offset:256
	v_mfma_f32_32x32x16_bf16 a[96:111], v[72:75], v[84:87], a[96:111]
	s_waitcnt vmcnt(10)
	ds_write_b128 v186, v[206:209] offset:50688
	global_load_dwordx4 v[210:213], v196, s[98:99] offset:256
	v_mfma_f32_32x32x16_bf16 a[80:95], v[76:79], v[80:83], a[80:95]
	global_load_dwordx4 v[206:209], v195, s[98:99] offset:256
	s_add_u32 s100, s100, 0x80
	s_addc_u32 s101, s101, 0
	s_add_u32 s98, s98, 0x80
	s_addc_u32 s99, s99, 0
	v_mfma_f32_32x32x16_bf16 a[112:127], v[76:79], v[84:87], a[112:127]
	s_waitcnt lgkmcnt(15)
	v_mfma_f32_32x32x16_bf16 a[16:31], v[104:107], v[80:83], a[16:31]
	v_mfma_f32_32x32x16_bf16 a[0:15], v[104:107], v[84:87], a[0:15]
	ds_read_b128 v[68:71], v189 offset:96
	ds_read_b128 v[80:83], v187 offset:36960
	ds_read_b128 v[72:75], v189 offset:4704
	ds_read_b128 v[84:87], v187 offset:41568
	ds_read_b128 v[76:79], v189 offset:9312
	ds_read_b128 v[104:107], v188 offset:96
	s_waitcnt lgkmcnt(14)
	v_mfma_f32_32x32x16_bf16 a[32:47], v[108:111], v[14:17], a[32:47]
	s_waitcnt lgkmcnt(12)
	v_mfma_f32_32x32x16_bf16 a[48:63], v[108:111], v[64:67], a[48:63]
	v_mfma_f32_32x32x16_bf16 a[64:79], v[112:115], v[14:17], a[64:79]
	v_mfma_f32_32x32x16_bf16 a[96:111], v[112:115], v[64:67], a[96:111]
	s_waitcnt lgkmcnt(11)
	v_mfma_f32_32x32x16_bf16 a[80:95], v[116:119], v[14:17], a[80:95]
	v_mfma_f32_32x32x16_bf16 a[112:127], v[116:119], v[64:67], a[112:127]
	s_waitcnt lgkmcnt(10)
	v_mfma_f32_32x32x16_bf16 a[16:31], v[120:123], v[14:17], a[16:31]
	v_mfma_f32_32x32x16_bf16 a[0:15], v[120:123], v[64:67], a[0:15]
	s_waitcnt lgkmcnt(0)
	v_mfma_f32_32x32x16_bf16 a[32:47], v[68:71], v[80:83], a[32:47]
	v_mfma_f32_32x32x16_bf16 a[48:63], v[68:71], v[84:87], a[48:63]
	v_mfma_f32_32x32x16_bf16 a[64:79], v[72:75], v[80:83], a[64:79]
	v_mfma_f32_32x32x16_bf16 a[96:111], v[72:75], v[84:87], a[96:111]
	s_barrier
	v_add_u32_e32 v189, s50, v192
	v_add_u32_e32 v188, s50, v191
	v_add_u32_e32 v187, s50, v190
	ds_read_b128 v[108:111], v189
	ds_read_b128 v[14:17], v187 offset:36864
	ds_read_b128 v[112:115], v189 offset:4608
	ds_read_b128 v[64:67], v187 offset:41472
	ds_read_b128 v[116:119], v189 offset:9216
	ds_read_b128 v[120:123], v188
	v_mfma_f32_32x32x16_bf16 a[80:95], v[76:79], v[80:83], a[80:95]
	v_mfma_f32_32x32x16_bf16 a[112:127], v[76:79], v[84:87], a[112:127]
	v_mfma_f32_32x32x16_bf16 a[16:31], v[104:107], v[80:83], a[16:31]
	v_mfma_f32_32x32x16_bf16 a[0:15], v[104:107], v[84:87], a[0:15]
	s_add_u32 s44, s44, 0x80
	s_addc_u32 s45, s45, 0
	s_cmpk_lg_i32 s44, 0x700
	s_cbranch_scc1 .LBB0_1964
	s_branch xg5_tail_6
	.p2align 6

.LBB0_2086:
	s_add_i32 s58, s26, 16
	s_cmpk_gt_u32 s26, 0x6f
	s_cselect_b64 s[24:25], -1, 0
	s_cmpk_lt_u32 s26, 0x70
	s_cselect_b64 vcc, -1, 0
	s_bitcmp0_b32 s58, 6
	s_cselect_b64 s[12:13], -1, 0
	v_cndmask_b32_e64 v100, v116, v102, s[12:13]
	v_cndmask_b32_e32 v100, v118, v100, vcc
	s_nop 0
	v_readlane_b32 s28, v100, s58
	s_nop 1
	v_mad_i64_i32 v[218:219], s[12:13], s28, v130, v[96:97]
	global_load_dwordx4 a[20:23], v[218:219], off
	v_mad_i64_i32 v[218:219], s[12:13], s28, v130, v[98:99]
	s_add_i32 s12, s26, 17
	global_load_dwordx2 a[42:43], v[218:219], off
	s_nop 1
	v_readlane_b32 s28, v100, s12
	s_nop 1
	v_mad_i64_i32 v[218:219], s[12:13], s28, v130, v[96:97]
	global_load_dwordx4 a[24:27], v[218:219], off
	v_mad_i64_i32 v[218:219], s[12:13], s28, v130, v[98:99]
	s_add_i32 s12, s26, 18
	global_load_dwordx2 a[44:45], v[218:219], off
	s_nop 1
	v_readlane_b32 s28, v100, s12
	s_nop 1
	v_mad_i64_i32 v[218:219], s[12:13], s28, v130, v[96:97]
	global_load_dwordx4 v[230:233], v[218:219], off
	v_mad_i64_i32 v[218:219], s[12:13], s28, v130, v[98:99]
	s_add_i32 s12, s26, 19
	global_load_dwordx2 a[46:47], v[218:219], off
	s_nop 1
	v_readlane_b32 s28, v100, s12
	s_nop 1
	v_mad_i64_i32 v[218:219], s[12:13], s28, v130, v[96:97]
	global_load_dwordx4 v[234:237], v[218:219], off
	v_mad_i64_i32 v[218:219], s[12:13], s28, v130, v[98:99]
	s_add_i32 s12, s26, 20
	global_load_dwordx2 a[48:49], v[218:219], off
	s_nop 1
	v_readlane_b32 s28, v100, s12
	s_nop 1
	v_mad_i64_i32 v[218:219], s[12:13], s28, v130, v[96:97]
	global_load_dwordx4 v[238:241], v[218:219], off
	v_mad_i64_i32 v[218:219], s[12:13], s28, v130, v[98:99]
	s_add_i32 s12, s26, 21
	global_load_dwordx2 a[50:51], v[218:219], off
	s_nop 1
	v_readlane_b32 s28, v100, s12
	s_nop 1
	v_mad_i64_i32 v[218:219], s[12:13], s28, v130, v[96:97]
	global_load_dwordx4 v[242:245], v[218:219], off
	v_mad_i64_i32 v[218:219], s[12:13], s28, v130, v[98:99]
	s_add_i32 s12, s26, 22
	global_load_dwordx2 a[52:53], v[218:219], off
	s_nop 1
	v_readlane_b32 s28, v100, s12
	s_nop 1
	v_mad_i64_i32 v[218:219], s[12:13], s28, v130, v[96:97]
	global_load_dwordx4 v[246:249], v[218:219], off
	v_mad_i64_i32 v[218:219], s[12:13], s28, v130, v[98:99]
	s_add_i32 s12, s26, 23
	global_load_dwordx2 a[54:55], v[218:219], off
	s_nop 1
	v_readlane_b32 s28, v100, s12
	s_nop 1
	v_mad_i64_i32 v[218:219], s[12:13], s28, v130, v[96:97]
	global_load_dwordx4 v[250:253], v[218:219], off
	v_mad_i64_i32 v[218:219], s[12:13], s28, v130, v[98:99]
	s_add_i32 s12, s26, 24
	global_load_dwordx2 a[56:57], v[218:219], off
	s_nop 1
	v_readlane_b32 s28, v100, s12
	s_nop 1
	v_mad_i64_i32 v[218:219], s[12:13], s28, v130, v[96:97]
	global_load_dwordx4 a[0:3], v[218:219], off
	v_mad_i64_i32 v[218:219], s[12:13], s28, v130, v[98:99]
	s_add_i32 s12, s26, 25
	global_load_dwordx2 a[58:59], v[218:219], off
	s_nop 1
	v_readlane_b32 s28, v100, s12
	s_nop 1
	v_mad_i64_i32 v[218:219], s[12:13], s28, v130, v[96:97]
	global_load_dwordx4 a[4:7], v[218:219], off
	v_mad_i64_i32 v[218:219], s[12:13], s28, v130, v[98:99]
	s_add_i32 s12, s26, 26
	global_load_dwordx2 a[60:61], v[218:219], off
	s_nop 1
	v_readlane_b32 s28, v100, s12
	s_nop 1
	v_mad_i64_i32 v[218:219], s[12:13], s28, v130, v[96:97]
	global_load_dwordx4 a[8:11], v[218:219], off
	v_mad_i64_i32 v[218:219], s[12:13], s28, v130, v[98:99]
	s_add_i32 s12, s26, 27
	global_load_dwordx2 a[62:63], v[218:219], off
	s_nop 1
	v_readlane_b32 s28, v100, s12
	s_nop 1
	v_mad_i64_i32 v[218:219], s[12:13], s28, v130, v[96:97]
	global_load_dwordx4 a[12:15], v[218:219], off
	v_mad_i64_i32 v[218:219], s[12:13], s28, v130, v[98:99]
	s_add_i32 s12, s26, 28
	global_load_dwordx2 a[64:65], v[218:219], off
	s_nop 1
	v_readlane_b32 s28, v100, s12
	s_nop 1
	v_mad_i64_i32 v[218:219], s[12:13], s28, v130, v[96:97]
	global_load_dwordx4 a[16:19], v[218:219], off
	v_mad_i64_i32 v[218:219], s[12:13], s28, v130, v[98:99]
	s_add_i32 s12, s26, 29
	global_load_dwordx2 a[66:67], v[218:219], off
	s_nop 1
	v_readlane_b32 s28, v100, s12
	s_nop 1
	v_mad_i64_i32 v[222:223], s[12:13], s28, v130, v[98:99]
	global_load_dwordx2 a[36:37], v[222:223], off
	v_mad_i64_i32 v[218:219], s[12:13], s28, v130, v[96:97]
	s_add_i32 s12, s26, 30
	global_load_dwordx4 v[218:221], v[218:219], off
	s_nop 1
	v_readlane_b32 s28, v100, s12
	s_nop 1
	v_mad_i64_i32 v[222:223], s[12:13], s28, v130, v[96:97]
	v_mad_i64_i32 v[226:227], s[12:13], s28, v130, v[98:99]
	s_add_i32 s12, s26, 31
	global_load_dwordx4 v[222:225], v[222:223], off
	s_cmp_lg_u32 s26, 64
	s_nop 0
	v_readlane_b32 s28, v100, s12
	global_load_dwordx2 a[38:39], v[226:227], off
	s_nop 0
	v_mad_i64_i32 v[226:227], s[12:13], s28, v130, v[96:97]
	v_mad_i64_i32 v[100:101], s[12:13], s28, v130, v[98:99]
	global_load_dwordx4 v[226:229], v[226:227], off
	s_nop 0
	global_load_dwordx2 a[40:41], v[100:101], off
	s_cbranch_scc1 .LBB0_2088
	global_load_dword a68, v[168:169], off
	global_load_dword a69, v[166:167], off
	global_load_dword v117, v[164:165], off
	global_load_dword v103, v[162:163], off
	.p2align 6

.LBB0_2160:
	s_and_b32 s4, s72, 0xffff
	s_mul_i32 s4, s4, 0xaaab
	s_lshr_b32 s4, s4, 20
	s_add_i32 s74, s77, s4
	s_mul_i32 s4, s4, 24
	s_sub_i32 s11, s72, s4
	s_lshl_b32 s4, s74, 19
	v_lshl_add_u64 v[4:5], v[56:57], 0, s[4:5]
	v_add_co_u32_e32 v12, vcc, 0x10000, v4
	s_lshl_b32 s8, s11, 18
	s_nop 0
	v_addc_co_u32_e32 v13, vcc, 0, v5, vcc
	v_add_co_u32_e32 v14, vcc, 0x20000, v4
	s_mov_b32 s9, s5
	s_nop 0
	v_addc_co_u32_e32 v15, vcc, 0, v5, vcc
	v_add_co_u32_e32 v24, vcc, 0x30000, v4
	global_load_dwordx4 v[0:3], v[4:5], off
	s_nop 0
	v_addc_co_u32_e32 v25, vcc, 0, v5, vcc
	v_add_co_u32_e32 v26, vcc, 0x40000, v4
	v_lshl_add_u64 v[8:9], v[58:59], 0, s[8:9]
	s_nop 0
	v_addc_co_u32_e32 v27, vcc, 0, v5, vcc
	v_add_co_u32_e32 v28, vcc, 0x50000, v4
	global_load_dwordx4 v[104:107], v[8:9], off
	s_nop 0
	v_addc_co_u32_e32 v29, vcc, 0, v5, vcc
	global_load_dwordx4 v[76:79], v[12:13], off
	global_load_dwordx4 v[80:83], v[14:15], off
	v_add_co_u32_e32 v30, vcc, 0x60000, v4
	global_load_dwordx4 v[84:87], v[24:25], off
	global_load_dwordx4 v[88:91], v[26:27], off
	v_addc_co_u32_e32 v31, vcc, 0, v5, vcc
	v_add_co_u32_e32 v32, vcc, 0x70000, v4
	global_load_dwordx4 v[92:95], v[28:29], off
	global_load_dwordx4 v[96:99], v[30:31], off
	v_addc_co_u32_e32 v33, vcc, 0, v5, vcc
	v_add_co_u32_e32 v120, vcc, s81, v8
	s_mov_b32 s10, 0x20000
	s_nop 0
	v_addc_co_u32_e32 v121, vcc, 0, v9, vcc
	global_load_dwordx4 v[100:103], v[32:33], off
	global_load_dwordx4 v[108:111], v[120:121], off
	v_add_co_u32_e32 v122, vcc, s10, v8
	s_mov_b32 s10, 0x30000
	s_nop 0
	v_addc_co_u32_e32 v123, vcc, 0, v9, vcc
	global_load_dwordx4 v[112:115], v[122:123], off
	v_add_co_u32_e32 v124, vcc, s10, v8
	s_mov_b32 s10, 0
	s_nop 0
	v_addc_co_u32_e32 v125, vcc, 0, v9, vcc
	global_load_dwordx4 v[116:119], v[124:125], off
	s_nop 0
	global_load_dwordx4 v[250:253], v[4:5], off offset:128
	s_nop 0
	global_load_dwordx4 v[218:221], v[8:9], off offset:128
	s_nop 0
	global_load_dwordx4 v[246:249], v[12:13], off offset:128
	global_load_dwordx4 v[242:245], v[14:15], off offset:128
	s_nop 0
	global_load_dwordx4 v[238:241], v[24:25], off offset:128
	global_load_dwordx4 v[234:237], v[26:27], off offset:128
	global_load_dwordx4 v[230:233], v[28:29], off offset:128
	global_load_dwordx4 v[226:229], v[30:31], off offset:128
	s_nop 0
	global_load_dwordx4 v[222:225], v[32:33], off offset:128
	s_nop 0
	global_load_dwordx4 v[214:217], v[120:121], off offset:128
	global_load_dwordx4 v[210:213], v[122:123], off offset:128
	s_and_b32 s73, s11, 0xffff
	v_accvgpr_write_b32 a47, 0
	v_accvgpr_write_b32 a46, 0
	v_accvgpr_write_b32 a45, 0
	v_accvgpr_write_b32 a44, 0
	v_accvgpr_write_b32 a43, 0
	v_accvgpr_write_b32 a42, 0
	v_accvgpr_write_b32 a41, 0
	v_accvgpr_write_b32 a40, 0
	v_accvgpr_write_b32 a39, 0
	v_accvgpr_write_b32 a38, 0
	v_accvgpr_write_b32 a37, 0
	v_accvgpr_write_b32 a36, 0
	v_accvgpr_write_b32 a35, 0
	v_accvgpr_write_b32 a34, 0
	v_accvgpr_write_b32 a33, 0
	v_accvgpr_write_b32 a32, 0
	v_accvgpr_write_b32 a63, 0
	v_accvgpr_write_b32 a62, 0
	v_accvgpr_write_b32 a61, 0
	v_accvgpr_write_b32 a60, 0
	v_accvgpr_write_b32 a59, 0
	v_accvgpr_write_b32 a58, 0
	v_accvgpr_write_b32 a57, 0
	v_accvgpr_write_b32 a56, 0
	v_accvgpr_write_b32 a55, 0
	v_accvgpr_write_b32 a54, 0
	s_waitcnt vmcnt(22)
	ds_write_b128 v130, v[0:3]
	s_waitcnt vmcnt(21)
	ds_write_b128 v130, v[104:107] offset:36864
	s_waitcnt vmcnt(20)
	ds_write_b128 v130, v[76:79] offset:4608
	s_waitcnt vmcnt(19)
	ds_write_b128 v130, v[80:83] offset:9216
	s_waitcnt vmcnt(18)
	ds_write_b128 v130, v[84:87] offset:13824
	s_waitcnt vmcnt(17)
	ds_write_b128 v130, v[88:91] offset:18432
	s_waitcnt vmcnt(16)
	ds_write_b128 v130, v[92:95] offset:23040
	s_waitcnt vmcnt(15)
	ds_write_b128 v130, v[96:99] offset:27648
	s_waitcnt vmcnt(14)
	ds_write_b128 v130, v[100:103] offset:32256
	s_waitcnt vmcnt(13)
	ds_write_b128 v130, v[108:111] offset:41472
	s_waitcnt vmcnt(12)
	ds_write_b128 v130, v[112:115] offset:46080
	global_load_dwordx4 v[206:209], v[124:125], off offset:128
	v_lshl_add_u64 v[0:1], v[74:75], 0, s[4:5]
	v_lshl_add_u64 v[2:3], v[74:75], 0, s[8:9]
	v_accvgpr_write_b32 a53, 0
	v_accvgpr_write_b32 a52, 0
	v_accvgpr_write_b32 a51, 0
	v_accvgpr_write_b32 a50, 0
	v_accvgpr_write_b32 a49, 0
	v_accvgpr_write_b32 a48, 0
	v_accvgpr_write_b32 a79, 0
	v_accvgpr_write_b32 a78, 0
	v_accvgpr_write_b32 a77, 0
	v_accvgpr_write_b32 a76, 0
	v_accvgpr_write_b32 a75, 0
	v_accvgpr_write_b32 a74, 0
	v_accvgpr_write_b32 a73, 0
	v_accvgpr_write_b32 a72, 0
	v_accvgpr_write_b32 a71, 0
	v_accvgpr_write_b32 a70, 0
	v_accvgpr_write_b32 a69, 0
	v_accvgpr_write_b32 a68, 0
	v_accvgpr_write_b32 a67, 0
	v_accvgpr_write_b32 a66, 0
	v_accvgpr_write_b32 a65, 0
	v_accvgpr_write_b32 a64, 0
	v_accvgpr_write_b32 a111, 0
	v_accvgpr_write_b32 a110, 0
	v_accvgpr_write_b32 a109, 0
	v_accvgpr_write_b32 a108, 0
	v_accvgpr_write_b32 a107, 0
	v_accvgpr_write_b32 a106, 0
	v_accvgpr_write_b32 a105, 0
	v_accvgpr_write_b32 a104, 0
	v_accvgpr_write_b32 a103, 0
	v_accvgpr_write_b32 a102, 0
	v_accvgpr_write_b32 a101, 0
	v_accvgpr_write_b32 a100, 0
	v_accvgpr_write_b32 a99, 0
	v_accvgpr_write_b32 a98, 0
	v_accvgpr_write_b32 a97, 0
	v_accvgpr_write_b32 a96, 0
	v_accvgpr_write_b32 a95, 0
	v_accvgpr_write_b32 a94, 0
	v_accvgpr_write_b32 a93, 0
	v_accvgpr_write_b32 a92, 0
	v_accvgpr_write_b32 a91, 0
	v_accvgpr_write_b32 a90, 0
	v_accvgpr_write_b32 a89, 0
	v_accvgpr_write_b32 a88, 0
	v_accvgpr_write_b32 a87, 0
	v_accvgpr_write_b32 a86, 0
	v_accvgpr_write_b32 a85, 0
	v_accvgpr_write_b32 a84, 0
	v_accvgpr_write_b32 a83, 0
	v_accvgpr_write_b32 a82, 0
	v_accvgpr_write_b32 a81, 0
	v_accvgpr_write_b32 a80, 0
	v_accvgpr_write_b32 a127, 0
	v_accvgpr_write_b32 a126, 0
	v_accvgpr_write_b32 a125, 0
	v_accvgpr_write_b32 a124, 0
	v_accvgpr_write_b32 a123, 0
	v_accvgpr_write_b32 a122, 0
	v_accvgpr_write_b32 a121, 0
	v_accvgpr_write_b32 a120, 0
	v_accvgpr_write_b32 a119, 0
	v_accvgpr_write_b32 a118, 0
	v_accvgpr_write_b32 a117, 0
	v_accvgpr_write_b32 a116, 0
	v_accvgpr_write_b32 a115, 0
	v_accvgpr_write_b32 a114, 0
	v_accvgpr_write_b32 a113, 0
	v_accvgpr_write_b32 a112, 0
	v_accvgpr_write_b32 a31, 0
	v_accvgpr_write_b32 a30, 0
	v_accvgpr_write_b32 a29, 0
	v_accvgpr_write_b32 a28, 0
	v_accvgpr_write_b32 a27, 0
	v_accvgpr_write_b32 a26, 0
	v_accvgpr_write_b32 a25, 0
	v_accvgpr_write_b32 a24, 0
	v_accvgpr_write_b32 a23, 0
	v_accvgpr_write_b32 a22, 0
	v_accvgpr_write_b32 a21, 0
	v_accvgpr_write_b32 a20, 0
	v_accvgpr_write_b32 a19, 0
	v_accvgpr_write_b32 a18, 0
	v_accvgpr_write_b32 a17, 0
	v_accvgpr_write_b32 a16, 0
	v_accvgpr_write_b32 a15, 0
	v_accvgpr_write_b32 a14, 0
	v_accvgpr_write_b32 a13, 0
	v_accvgpr_write_b32 a12, 0
	v_accvgpr_write_b32 a11, 0
	v_accvgpr_write_b32 a10, 0
	v_accvgpr_write_b32 a9, 0
	v_accvgpr_write_b32 a8, 0
	v_accvgpr_write_b32 a7, 0
	v_accvgpr_write_b32 a6, 0
	v_accvgpr_write_b32 a5, 0
	v_accvgpr_write_b32 a4, 0
	v_accvgpr_write_b32 a3, 0
	v_accvgpr_write_b32 a2, 0
	v_accvgpr_write_b32 a1, 0
	v_accvgpr_write_b32 a0, 0
	s_mov_b64 s[8:9], 0
	s_waitcnt vmcnt(12)
	ds_write_b128 v130, v[116:119] offset:50688
	s_waitcnt lgkmcnt(0)
	s_barrier
	s_waitcnt vmcnt(0)
	v_readfirstlane_b32 s100, v0
	v_readfirstlane_b32 s101, v1
	v_readfirstlane_b32 s98, v2
	v_readfirstlane_b32 s99, v3
	s_nop 1
	v_subrev_u32_e32 v194, s100, v0
	v_subrev_u32_e32 v193, s98, v2
	v_add_u32_e32 v254, 0x126fa000, v194
	v_add_u32_e32 v205, 0x1270a000, v194
	v_add_u32_e32 v204, 0x1271a000, v194
	v_add_u32_e32 v203, 0x1272a000, v194
	v_add_u32_e32 v202, s82, v194
	v_add_u32_e32 v201, s83, v194
	v_add_u32_e32 v200, s84, v194
	v_add_u32_e32 v199, s85, v194
	v_add_u32_e32 v198, s86, v193
	v_add_u32_e32 v197, s87, v193
	v_add_u32_e32 v196, s88, v193
	v_add_u32_e32 v195, s89, v193
	s_add_u32 s100, s100, s8
	s_addc_u32 s101, s101, s9
	s_add_u32 s98, s98, s8
	s_addc_u32 s99, s99, s9
	v_add_u32_e32 v192, v49, v131
	v_add_u32_e32 v191, v49, v132
	v_add_u32_e32 v190, v49, v133
	s_and_b32 s4, s10, 1
	s_mul_i32 s11, s4, 0xd800
	v_add_u32_e32 v189, s11, v192
	v_add_u32_e32 v188, s11, v191
	v_add_u32_e32 v187, s11, v190
	ds_read_b128 v[80:83], v189
	ds_read_b128 v[4:7], v187 offset:36864
	ds_read_b128 v[84:87], v189 offset:4608
	ds_read_b128 v[8:11], v187 offset:41472
	ds_read_b128 v[88:91], v189 offset:9216
	ds_read_b128 v[92:95], v188
	s_getreg_b32 s4, hwreg(HW_REG_HW_ID, 4, 1)
	s_cmp_lg_u32 s4, 0
	s_cbranch_scc1 xg5_varB_7
	.p2align 6
.LBB0_2161:
	s_and_b32 s4, s10, 1
	s_mul_i32 s11, s4, 0xd800
	s_xor_b32 s4, s4, 1
	s_mul_i32 s4, s4, 0xd800
	s_add_i32 s10, s10, 1
	v_add_u32_e32 v186, s4, v130
	ds_read_b128 v[12:15], v189 offset:32
	ds_read_b128 v[24:27], v187 offset:36896
	ds_read_b128 v[16:19], v189 offset:4640
	ds_read_b128 v[28:31], v187 offset:41504
	ds_read_b128 v[20:23], v189 offset:9248
	ds_read_b128 v[76:79], v188 offset:32
	s_waitcnt lgkmcnt(10)
	v_mfma_f32_32x32x16_bf16 a[32:47], v[80:83], v[4:7], a[32:47]
	s_waitcnt vmcnt(11)
	ds_write_b128 v186, v[250:253]
	s_waitcnt lgkmcnt(9)
	v_mfma_f32_32x32x16_bf16 a[48:63], v[80:83], v[8:11], a[48:63]
	s_waitcnt vmcnt(10)
	ds_write_b128 v186, v[246:249] offset:4608
	global_load_dwordx4 v[250:253], v254, s[100:101] offset:512
	v_mfma_f32_32x32x16_bf16 a[64:79], v[84:87], v[4:7], a[64:79]
	s_waitcnt vmcnt(10)
	ds_write_b128 v186, v[242:245] offset:9216
	global_load_dwordx4 v[246:249], v205, s[100:101] offset:512
	v_mfma_f32_32x32x16_bf16 a[96:111], v[84:87], v[8:11], a[96:111]
	s_waitcnt vmcnt(10)
	ds_write_b128 v186, v[238:241] offset:13824
	global_load_dwordx4 v[242:245], v204, s[100:101] offset:512
	s_waitcnt lgkmcnt(11)
	v_mfma_f32_32x32x16_bf16 a[80:95], v[88:91], v[4:7], a[80:95]
	s_waitcnt vmcnt(10)
	ds_write_b128 v186, v[234:237] offset:18432
	global_load_dwordx4 v[238:241], v203, s[100:101] offset:512
	v_mfma_f32_32x32x16_bf16 a[112:127], v[88:91], v[8:11], a[112:127]
	s_waitcnt vmcnt(10)
	ds_write_b128 v186, v[230:233] offset:23040
	global_load_dwordx4 v[234:237], v202, s[100:101] offset:512
	s_waitcnt lgkmcnt(12)
	v_mfma_f32_32x32x16_bf16 a[16:31], v[92:95], v[4:7], a[16:31]
	s_waitcnt vmcnt(10)
	ds_write_b128 v186, v[226:229] offset:27648
	global_load_dwordx4 v[230:233], v201, s[100:101] offset:512
	v_mfma_f32_32x32x16_bf16 a[0:15], v[92:95], v[8:11], a[0:15]
	s_waitcnt vmcnt(10)
	ds_write_b128 v186, v[222:225] offset:32256
	global_load_dwordx4 v[226:229], v200, s[100:101] offset:512
	ds_read_b128 v[80:83], v189 offset:64
	ds_read_b128 v[4:7], v187 offset:36928
	ds_read_b128 v[84:87], v189 offset:4672
	ds_read_b128 v[8:11], v187 offset:41536
	ds_read_b128 v[88:91], v189 offset:9280
	ds_read_b128 v[92:95], v188 offset:64
	s_waitcnt lgkmcnt(15)
	v_mfma_f32_32x32x16_bf16 a[32:47], v[12:15], v[24:27], a[32:47]
	s_waitcnt vmcnt(10)
	ds_write_b128 v186, v[218:221] offset:36864
	global_load_dwordx4 v[222:225], v199, s[100:101] offset:512
	v_mfma_f32_32x32x16_bf16 a[48:63], v[12:15], v[28:31], a[48:63]
	s_waitcnt vmcnt(10)
	ds_write_b128 v186, v[214:217] offset:41472
	global_load_dwordx4 v[218:221], v198, s[98:99] offset:256
	v_mfma_f32_32x32x16_bf16 a[64:79], v[16:19], v[24:27], a[64:79]
	s_waitcnt vmcnt(10)
	ds_write_b128 v186, v[210:213] offset:46080
	global_load_dwordx4 v[214:217], v197, s[98:99] offset:256
	v_mfma_f32_32x32x16_bf16 a[96:111], v[16:19], v[28:31], a[96:111]
	s_waitcnt vmcnt(10)
	ds_write_b128 v186, v[206:209] offset:50688
	global_load_dwordx4 v[210:213], v196, s[98:99] offset:256
	v_mfma_f32_32x32x16_bf16 a[80:95], v[20:23], v[24:27], a[80:95]
	global_load_dwordx4 v[206:209], v195, s[98:99] offset:256
	s_add_u32 s100, s100, 0x80
	s_addc_u32 s101, s101, 0
	s_add_u32 s98, s98, 0x80
	s_addc_u32 s99, s99, 0
	v_mfma_f32_32x32x16_bf16 a[112:127], v[20:23], v[28:31], a[112:127]
	s_waitcnt lgkmcnt(15)
	v_mfma_f32_32x32x16_bf16 a[16:31], v[76:79], v[24:27], a[16:31]
	v_mfma_f32_32x32x16_bf16 a[0:15], v[76:79], v[28:31], a[0:15]
	ds_read_b128 v[12:15], v189 offset:96
	ds_read_b128 v[24:27], v187 offset:36960
	ds_read_b128 v[16:19], v189 offset:4704
	ds_read_b128 v[28:31], v187 offset:41568
	ds_read_b128 v[20:23], v189 offset:9312
	ds_read_b128 v[76:79], v188 offset:96
	s_waitcnt lgkmcnt(14)
	v_mfma_f32_32x32x16_bf16 a[32:47], v[80:83], v[4:7], a[32:47]
	s_waitcnt lgkmcnt(12)
	v_mfma_f32_32x32x16_bf16 a[48:63], v[80:83], v[8:11], a[48:63]
	v_mfma_f32_32x32x16_bf16 a[64:79], v[84:87], v[4:7], a[64:79]
	v_mfma_f32_32x32x16_bf16 a[96:111], v[84:87], v[8:11], a[96:111]
	s_waitcnt lgkmcnt(11)
	v_mfma_f32_32x32x16_bf16 a[80:95], v[88:91], v[4:7], a[80:95]
	v_mfma_f32_32x32x16_bf16 a[112:127], v[88:91], v[8:11], a[112:127]
	s_waitcnt lgkmcnt(10)
	v_mfma_f32_32x32x16_bf16 a[16:31], v[92:95], v[4:7], a[16:31]
	v_mfma_f32_32x32x16_bf16 a[0:15], v[92:95], v[8:11], a[0:15]
	s_waitcnt lgkmcnt(0)
	v_mfma_f32_32x32x16_bf16 a[32:47], v[12:15], v[24:27], a[32:47]
	v_mfma_f32_32x32x16_bf16 a[48:63], v[12:15], v[28:31], a[48:63]
	v_mfma_f32_32x32x16_bf16 a[64:79], v[16:19], v[24:27], a[64:79]
	v_mfma_f32_32x32x16_bf16 a[96:111], v[16:19], v[28:31], a[96:111]
	s_barrier
	v_add_u32_e32 v189, s4, v192
	v_add_u32_e32 v188, s4, v191
	v_add_u32_e32 v187, s4, v190
	ds_read_b128 v[80:83], v189
	ds_read_b128 v[4:7], v187 offset:36864
	ds_read_b128 v[84:87], v189 offset:4608
	ds_read_b128 v[8:11], v187 offset:41472
	ds_read_b128 v[88:91], v189 offset:9216
	ds_read_b128 v[92:95], v188
	v_mfma_f32_32x32x16_bf16 a[80:95], v[20:23], v[24:27], a[80:95]
	v_mfma_f32_32x32x16_bf16 a[112:127], v[20:23], v[28:31], a[112:127]
	v_mfma_f32_32x32x16_bf16 a[16:31], v[76:79], v[24:27], a[16:31]
	v_mfma_f32_32x32x16_bf16 a[0:15], v[76:79], v[28:31], a[0:15]
	s_add_u32 s8, s8, 0x80
	s_addc_u32 s9, s9, 0
	s_cmpk_lg_i32 s8, 0x700
	s_cbranch_scc1 .LBB0_2161
	s_branch xg5_tail_7
	.p2align 6

.LBB0_2270:
	s_lshl_b64 s[58:59], s[4:5], 10
	s_lshl_b64 s[64:65], s[4:5], 11
	v_mov_b32_e32 v243, v149
	s_lshl_b32 s4, s68, 7
	v_lshl_add_u64 v[0:1], s[62:63], 0, v[242:243]
	v_mov_b32_e32 v245, v149
	v_mov_b32_e32 v247, v149
	s_add_u32 s70, s62, s4
	v_lshl_add_u64 v[0:1], v[0:1], 0, v[244:245]
	v_lshl_add_u64 v[2:3], s[62:63], 0, v[246:247]
	s_addc_u32 s71, s63, 0
	v_lshl_add_u64 v[2:3], v[2:3], 0, v[244:245]
	global_load_dwordx4 v[32:35], v[0:1], off
	global_load_dwordx4 v[36:39], v[2:3], off
	v_lshl_add_u64 v[0:1], s[70:71], 0, v[242:243]
	v_lshl_add_u64 v[0:1], v[0:1], 0, v[244:245]
	v_lshl_add_u64 v[2:3], s[70:71], 0, v[246:247]
	v_lshl_add_u64 v[2:3], v[2:3], 0, v[244:245]
	global_load_dwordx4 v[40:43], v[0:1], off
	global_load_dwordx4 v[44:47], v[2:3], off
	v_accvgpr_read_b32 v0, a209
	v_mul_u32_u24_e32 v0, s68, v0
	v_lshlrev_b32_e32 v64, 1, v0
	v_mov_b32_e32 v65, v149
	v_mul_u32_u24_e32 v2, s68, v152
	v_lshl_add_u64 v[0:1], s[60:61], 0, v[64:65]
	v_lshlrev_b32_e32 v66, 1, v2
	v_mov_b32_e32 v67, v149
	v_lshl_add_u64 v[0:1], v[0:1], 0, v[244:245]
	v_lshl_add_u64 v[2:3], s[60:61], 0, v[66:67]
	v_lshl_add_u64 v[2:3], v[2:3], 0, v[244:245]
	global_load_dwordx4 v[48:51], v[0:1], off
	global_load_dwordx4 v[52:55], v[2:3], off
	v_mul_u32_u24_e32 v0, s68, v153
	v_lshlrev_b32_e32 v68, 1, v0
	v_mov_b32_e32 v69, v149
	v_mul_u32_u24_e32 v2, s68, v160
	v_lshl_add_u64 v[0:1], s[60:61], 0, v[68:69]
	v_lshlrev_b32_e32 v70, 1, v2
	v_mov_b32_e32 v71, v149
	v_lshl_add_u64 v[0:1], v[0:1], 0, v[244:245]
	v_lshl_add_u64 v[2:3], s[60:61], 0, v[70:71]
	v_lshl_add_u64 v[2:3], v[2:3], 0, v[244:245]
	global_load_dwordx4 v[56:59], v[0:1], off
	global_load_dwordx4 v[60:63], v[2:3], off
	v_mov_b32_e32 v251, v149
	v_lshl_add_u64 v[0:1], v[164:165], 0, s[64:65]
	v_lshl_add_u64 v[2:3], v[0:1], 0, v[148:149]
	v_lshl_add_u64 v[0:1], v[0:1], 0, v[250:251]
	global_load_dwordx4 v[28:31], v[2:3], off
	global_load_dwordx4 v[24:27], v[2:3], off offset:32
	global_load_dwordx4 v[20:23], v[2:3], off offset:64
	global_load_dwordx4 v[16:19], v[2:3], off offset:96
	global_load_dwordx4 v[12:15], v[0:1], off
	global_load_dwordx4 v[8:11], v[0:1], off offset:32
	global_load_dwordx4 v[4:7], v[0:1], off offset:64
	s_nop 0
	global_load_dwordx4 v[0:3], v[0:1], off offset:96
	v_lshl_add_u64 v[82:83], s[62:63], 0, v[146:147]
	v_lshl_add_u64 v[84:85], s[62:63], 0, v[166:167]
	v_lshl_add_u64 v[86:87], v[82:83], 0, s[4:5]
	v_lshl_add_u64 v[88:89], v[84:85], 0, s[4:5]
	s_add_i32 s4, s67, 1
	s_add_u32 s60, s60, 0x80
	v_mov_b32_e32 v80, 0
	s_addc_u32 s61, s61, 0
	v_accvgpr_write_b32 a31, 0
	v_accvgpr_write_b32 a30, 0
	v_accvgpr_write_b32 a29, 0
	v_accvgpr_write_b32 a28, 0
	v_accvgpr_write_b32 a27, 0
	v_accvgpr_write_b32 a26, 0
	v_accvgpr_write_b32 a25, 0
	v_accvgpr_write_b32 a24, 0
	v_accvgpr_write_b32 a23, 0
	v_accvgpr_write_b32 a22, 0
	v_lshl_add_u64 v[90:91], s[60:61], 0, v[64:65]
	v_lshl_add_u64 v[92:93], s[60:61], 0, v[66:67]
	v_lshl_add_u64 v[94:95], s[60:61], 0, v[68:69]
	v_lshl_add_u64 v[96:97], s[60:61], 0, v[70:71]
	v_accvgpr_write_b32 a21, 0
	v_accvgpr_write_b32 a20, 0
	v_accvgpr_write_b32 a19, 0
	v_accvgpr_write_b32 a18, 0
	v_accvgpr_write_b32 a17, 0
	v_accvgpr_write_b32 a16, 0
	v_accvgpr_write_b32 a111, 0
	v_accvgpr_write_b32 a110, 0
	v_accvgpr_write_b32 a109, 0
	v_accvgpr_write_b32 a108, 0
	v_accvgpr_write_b32 a107, 0
	v_accvgpr_write_b32 a106, 0
	v_accvgpr_write_b32 a105, 0
	v_accvgpr_write_b32 a104, 0
	v_accvgpr_write_b32 a103, 0
	v_accvgpr_write_b32 a102, 0
	v_accvgpr_write_b32 a101, 0
	v_accvgpr_write_b32 a100, 0
	v_accvgpr_write_b32 a99, 0
	v_accvgpr_write_b32 a98, 0
	v_accvgpr_write_b32 a97, 0
	v_accvgpr_write_b32 a96, 0
	v_accvgpr_write_b32 a143, 0
	v_accvgpr_write_b32 a142, 0
	v_accvgpr_write_b32 a141, 0
	v_accvgpr_write_b32 a140, 0
	v_accvgpr_write_b32 a139, 0
	v_accvgpr_write_b32 a138, 0
	v_accvgpr_write_b32 a137, 0
	v_accvgpr_write_b32 a136, 0
	v_accvgpr_write_b32 a135, 0
	v_accvgpr_write_b32 a134, 0
	v_accvgpr_write_b32 a133, 0
	v_accvgpr_write_b32 a132, 0
	v_accvgpr_write_b32 a131, 0
	v_accvgpr_write_b32 a130, 0
	v_accvgpr_write_b32 a129, 0
	v_accvgpr_write_b32 a128, 0
	v_accvgpr_write_b32 a63, 0
	v_accvgpr_write_b32 a62, 0
	v_accvgpr_write_b32 a61, 0
	v_accvgpr_write_b32 a60, 0
	v_accvgpr_write_b32 a59, 0
	v_accvgpr_write_b32 a58, 0
	v_accvgpr_write_b32 a57, 0
	v_accvgpr_write_b32 a56, 0
	v_accvgpr_write_b32 a55, 0
	v_accvgpr_write_b32 a54, 0
	v_accvgpr_write_b32 a53, 0
	v_accvgpr_write_b32 a52, 0
	v_accvgpr_write_b32 a51, 0
	v_accvgpr_write_b32 a50, 0
	v_accvgpr_write_b32 a49, 0
	v_accvgpr_write_b32 a48, 0
	v_accvgpr_write_b32 a95, 0
	v_accvgpr_write_b32 a94, 0
	v_accvgpr_write_b32 a93, 0
	v_accvgpr_write_b32 a92, 0
	v_accvgpr_write_b32 a91, 0
	v_accvgpr_write_b32 a90, 0
	v_accvgpr_write_b32 a89, 0
	v_accvgpr_write_b32 a88, 0
	v_accvgpr_write_b32 a87, 0
	v_accvgpr_write_b32 a86, 0
	v_accvgpr_write_b32 a85, 0
	v_accvgpr_write_b32 a84, 0
	v_accvgpr_write_b32 a83, 0
	v_accvgpr_write_b32 a82, 0
	v_accvgpr_write_b32 a81, 0
	v_accvgpr_write_b32 a80, 0
	v_accvgpr_write_b32 a47, 0
	v_accvgpr_write_b32 a46, 0
	v_accvgpr_write_b32 a45, 0
	v_accvgpr_write_b32 a44, 0
	v_accvgpr_write_b32 a43, 0
	v_accvgpr_write_b32 a42, 0
	v_accvgpr_write_b32 a41, 0
	v_accvgpr_write_b32 a40, 0
	v_accvgpr_write_b32 a39, 0
	v_accvgpr_write_b32 a38, 0
	v_accvgpr_write_b32 a37, 0
	v_accvgpr_write_b32 a36, 0
	v_accvgpr_write_b32 a35, 0
	v_accvgpr_write_b32 a34, 0
	v_accvgpr_write_b32 a33, 0
	v_accvgpr_write_b32 a32, 0
	v_accvgpr_write_b32 a127, 0
	v_accvgpr_write_b32 a126, 0
	v_accvgpr_write_b32 a125, 0
	v_accvgpr_write_b32 a124, 0
	v_accvgpr_write_b32 a123, 0
	v_accvgpr_write_b32 a122, 0
	v_accvgpr_write_b32 a121, 0
	v_accvgpr_write_b32 a120, 0
	v_accvgpr_write_b32 a119, 0
	v_accvgpr_write_b32 a118, 0
	v_accvgpr_write_b32 a117, 0
	v_accvgpr_write_b32 a116, 0
	v_accvgpr_write_b32 a115, 0
	v_accvgpr_write_b32 a114, 0
	v_accvgpr_write_b32 a113, 0
	v_accvgpr_write_b32 a112, 0
	v_accvgpr_write_b32 a79, 0
	v_accvgpr_write_b32 a78, 0
	v_accvgpr_write_b32 a77, 0
	v_accvgpr_write_b32 a76, 0
	v_accvgpr_write_b32 a75, 0
	v_accvgpr_write_b32 a74, 0
	v_accvgpr_write_b32 a73, 0
	v_accvgpr_write_b32 a72, 0
	v_accvgpr_write_b32 a71, 0
	v_accvgpr_write_b32 a70, 0
	v_accvgpr_write_b32 a69, 0
	v_accvgpr_write_b32 a68, 0
	v_accvgpr_write_b32 a67, 0
	v_accvgpr_write_b32 a66, 0
	v_accvgpr_write_b32 a65, 0
	v_accvgpr_write_b32 a64, 0
	s_mov_b32 s60, 0
	v_mov_b32_e32 v81, v80
	s_waitcnt vmcnt(15)
	ds_write_b128 v129, v[32:35]
	s_waitcnt vmcnt(14)
	ds_write_b128 v135, v[36:39]
	s_waitcnt vmcnt(13)
	ds_write_b128 v129, v[40:43] offset:9216
	s_waitcnt vmcnt(12)
	ds_write_b128 v135, v[44:47] offset:9216
	s_waitcnt vmcnt(11)
	ds_write_b128 v129, v[48:51] offset:36864
	s_waitcnt vmcnt(10)
	ds_write_b128 v135, v[52:55] offset:36864
	s_waitcnt vmcnt(9)
	ds_write_b128 v161, v[56:59] offset:36864
	s_waitcnt vmcnt(8)
	ds_write_b128 v162, v[60:63] offset:36864
	v_accvgpr_write_b32 a160, 0
	v_mov_b32_e32 v48, 0
	v_accvgpr_write_b32 a161, 0
	v_mov_b32_e32 v49, 0
	v_accvgpr_write_b32 a162, 0
	v_mov_b32_e32 v50, 0
	v_accvgpr_write_b32 a163, 0
	v_mov_b32_e32 v51, 0
	v_accvgpr_write_b32 a164, 0
	v_mov_b32_e32 v52, 0
	v_accvgpr_write_b32 a165, 0
	v_mov_b32_e32 v53, 0
	v_accvgpr_write_b32 a166, 0
	v_mov_b32_e32 v54, 0
	v_accvgpr_write_b32 a167, 0
	v_mov_b32_e32 v55, 0
	v_accvgpr_write_b32 a168, 0
	v_mov_b32_e32 v56, 0
	v_accvgpr_write_b32 a169, 0
	v_mov_b32_e32 v57, 0
	v_accvgpr_write_b32 a170, 0
	v_mov_b32_e32 v58, 0
	v_accvgpr_write_b32 a171, 0
	v_mov_b32_e32 v59, 0
	v_accvgpr_write_b32 a172, 0
	v_mov_b32_e32 v60, 0
	v_accvgpr_write_b32 a173, 0
	v_mov_b32_e32 v61, 0
	v_accvgpr_write_b32 a174, 0
	v_mov_b32_e32 v62, 0
	v_accvgpr_write_b32 a175, 0
	v_mov_b32_e32 v63, 0
	v_accvgpr_write_b32 a176, 0
	v_mov_b32_e32 v116, 0
	v_accvgpr_write_b32 a177, 0
	v_mov_b32_e32 v117, 0
	v_accvgpr_write_b32 a178, 0
	v_mov_b32_e32 v118, 0
	v_accvgpr_write_b32 a179, 0
	v_mov_b32_e32 v119, 0
	v_accvgpr_write_b32 a180, 0
	v_mov_b32_e32 v120, 0
	v_accvgpr_write_b32 a181, 0
	v_mov_b32_e32 v121, 0
	v_accvgpr_write_b32 a182, 0
	v_mov_b32_e32 v122, 0
	v_accvgpr_write_b32 a183, 0
	v_mov_b32_e32 v123, 0
	v_accvgpr_write_b32 a184, 0
	v_mov_b32_e32 v124, 0
	v_accvgpr_write_b32 a185, 0
	v_mov_b32_e32 v125, 0
	v_accvgpr_write_b32 a186, 0
	v_mov_b32_e32 v126, 0
	v_accvgpr_write_b32 a187, 0
	v_mov_b32_e32 v127, 0
	v_accvgpr_write_b32 a188, 0
	v_mov_b32_e32 v130, 0
	v_accvgpr_write_b32 a189, 0
	v_mov_b32_e32 v131, 0
	v_accvgpr_write_b32 a190, 0
	v_mov_b32_e32 v132, 0
	v_accvgpr_write_b32 a191, 0
	v_mov_b32_e32 v133, 0
	v_accvgpr_read_b32 v32, a0
	v_accvgpr_read_b32 v33, a0
	v_accvgpr_read_b32 v34, a0
	v_accvgpr_read_b32 v35, a0
	v_accvgpr_read_b32 v36, a0
	v_accvgpr_read_b32 v37, a0
	v_accvgpr_read_b32 v38, a0
	v_accvgpr_read_b32 v39, a0
	v_accvgpr_read_b32 v40, a0
	v_accvgpr_read_b32 v41, a0
	v_accvgpr_read_b32 v42, a0
	v_accvgpr_read_b32 v43, a0
	v_accvgpr_read_b32 v44, a0
	v_accvgpr_read_b32 v45, a0
	v_accvgpr_read_b32 v46, a0
	v_accvgpr_read_b32 v47, a0
	v_mbcnt_lo_u32_b32 v235, -1, 0
	v_mbcnt_hi_u32_b32 v235, -1, v235
	v_lshlrev_b32_e32 v235, 4, v235
	v_add_u32_e32 v235, 0xd800, v235
	s_waitcnt lgkmcnt(0)
	ds_write_b128 v235, a[160:163]
	ds_write_b128 v235, a[160:163] offset:1024
	ds_write_b128 v235, a[160:163] offset:2048
	ds_write_b128 v235, a[160:163] offset:3072
	ds_write_b128 v235, a[160:163] offset:4096
	ds_write_b128 v235, a[160:163] offset:5120
	ds_write_b128 v235, a[160:163] offset:6144
	ds_write_b128 v235, a[160:163] offset:7168
	ds_write_b128 v235, a[160:163] offset:8192
	s_waitcnt lgkmcnt(0)
	ds_write_b128 v235, a[160:163] offset:9216
	ds_write_b128 v235, a[160:163] offset:10240
	ds_write_b128 v235, a[160:163] offset:11264
	ds_write_b128 v235, a[160:163] offset:12288
	ds_write_b128 v235, a[160:163] offset:13312
	ds_write_b128 v235, a[160:163] offset:14336
	ds_write_b128 v235, a[160:163] offset:15360
	ds_write_b128 v235, a[160:163] offset:16384
	ds_write_b128 v235, a[160:163] offset:17408
	.p2align 6

.LBB0_2448:
	s_lshr_b32 s48, s47, 3
	s_lshl_b32 s42, s48, 18
	s_add_i32 s42, s69, s42
	v_lshl_add_u64 v[10:11], s[42:43], 1, v[8:9]
	s_and_b32 s42, s46, 7
	s_lshl_b32 s42, s42, 18
	s_add_i32 s48, s48, s66
	v_lshl_add_u64 v[12:13], v[8:9], 0, s[42:43]
	s_lshl_b32 s42, s48, 19
	v_lshl_add_u64 v[14:15], v[2:3], 0, s[42:43]
	v_add_co_u32_e32 v16, vcc, s70, v14
	s_and_b32 s49, s47, 7
	s_nop 0
	v_addc_co_u32_e32 v17, vcc, 0, v15, vcc
	v_add_co_u32_e32 v18, vcc, s71, v14
	s_lshl_b32 s42, s49, 18
	s_nop 0
	v_addc_co_u32_e32 v19, vcc, 0, v15, vcc
	v_add_co_u32_e32 v76, vcc, s72, v14
	v_lshl_add_u64 v[90:91], v[4:5], 0, s[42:43]
	s_nop 0
	v_addc_co_u32_e32 v77, vcc, 0, v15, vcc
	v_add_co_u32_e32 v78, vcc, s73, v14
	global_load_dwordx4 v[108:111], v[14:15], off
	global_load_dwordx4 v[112:115], v[16:17], off
	v_addc_co_u32_e32 v79, vcc, 0, v15, vcc
	v_add_co_u32_e32 v80, vcc, s74, v14
	global_load_dwordx4 v[116:119], v[18:19], off
	global_load_dwordx4 v[120:123], v[76:77], off
	v_addc_co_u32_e32 v81, vcc, 0, v15, vcc
	v_add_co_u32_e32 v82, vcc, s75, v14
	global_load_dwordx4 v[124:127], v[78:79], off
	global_load_dwordx4 v[128:131], v[80:81], off
	v_addc_co_u32_e32 v83, vcc, 0, v15, vcc
	v_add_co_u32_e32 v88, vcc, s77, v14
	global_load_dwordx4 v[132:135], v[82:83], off
	s_nop 0
	v_addc_co_u32_e32 v89, vcc, 0, v15, vcc
	v_add_co_u32_e32 v92, vcc, s70, v90
	global_load_dwordx4 v[140:143], v[88:89], off
	s_nop 0
	v_addc_co_u32_e32 v93, vcc, 0, v91, vcc
	v_add_co_u32_e32 v104, vcc, s71, v90
	global_load_dwordx4 v[144:147], v[90:91], off
	global_load_dwordx4 v[148:151], v[92:93], off
	v_addc_co_u32_e32 v105, vcc, 0, v91, vcc
	v_add_co_u32_e32 v106, vcc, s72, v90
	global_load_dwordx4 v[152:155], v[104:105], off
	s_nop 0
	v_addc_co_u32_e32 v107, vcc, 0, v91, vcc
	global_load_dwordx4 v[156:159], v[106:107], off
	global_load_dwordx4 v[250:253], v[14:15], off offset:128
	global_load_dwordx4 v[246:249], v[16:17], off offset:128
	global_load_dwordx4 v[242:245], v[18:19], off offset:128
	s_nop 0
	global_load_dwordx4 v[238:241], v[76:77], off offset:128
	global_load_dwordx4 v[234:237], v[78:79], off offset:128
	global_load_dwordx4 v[230:233], v[80:81], off offset:128
	s_nop 0
	global_load_dwordx4 v[226:229], v[82:83], off offset:128
	s_nop 0
	global_load_dwordx4 v[222:225], v[88:89], off offset:128
	global_load_dwordx4 v[218:221], v[90:91], off offset:128
	s_nop 0
	global_load_dwordx4 v[214:217], v[92:93], off offset:128
	s_nop 0
	global_load_dwordx4 v[210:213], v[104:105], off offset:128
	s_nop 0
	global_load_dwordx4 v[206:209], v[106:107], off offset:128
	s_mov_b32 s42, 0
	v_accvgpr_write_b32 a47, 0
	v_accvgpr_write_b32 a46, 0
	v_accvgpr_write_b32 a45, 0
	v_accvgpr_write_b32 a44, 0
	v_accvgpr_write_b32 a43, 0
	v_accvgpr_write_b32 a42, 0
	v_accvgpr_write_b32 a41, 0
	v_accvgpr_write_b32 a40, 0
	v_accvgpr_write_b32 a39, 0
	v_accvgpr_write_b32 a38, 0
	v_accvgpr_write_b32 a37, 0
	v_accvgpr_write_b32 a36, 0
	v_accvgpr_write_b32 a35, 0
	v_accvgpr_write_b32 a34, 0
	v_accvgpr_write_b32 a33, 0
	v_accvgpr_write_b32 a32, 0
	v_accvgpr_write_b32 a63, 0
	v_accvgpr_write_b32 a62, 0
	v_accvgpr_write_b32 a61, 0
	v_accvgpr_write_b32 a60, 0
	v_accvgpr_write_b32 a59, 0
	v_accvgpr_write_b32 a58, 0
	v_accvgpr_write_b32 a57, 0
	v_accvgpr_write_b32 a56, 0
	v_accvgpr_write_b32 a55, 0
	v_accvgpr_write_b32 a54, 0
	v_accvgpr_write_b32 a53, 0
	v_accvgpr_write_b32 a52, 0
	v_accvgpr_write_b32 a51, 0
	v_accvgpr_write_b32 a50, 0
	v_accvgpr_write_b32 a49, 0
	v_accvgpr_write_b32 a48, 0
	v_accvgpr_write_b32 a79, 0
	v_accvgpr_write_b32 a78, 0
	v_accvgpr_write_b32 a77, 0
	v_accvgpr_write_b32 a76, 0
	v_accvgpr_write_b32 a75, 0
	v_accvgpr_write_b32 a74, 0
	v_accvgpr_write_b32 a73, 0
	v_accvgpr_write_b32 a72, 0
	v_accvgpr_write_b32 a71, 0
	v_accvgpr_write_b32 a70, 0
	v_accvgpr_write_b32 a69, 0
	v_accvgpr_write_b32 a68, 0
	v_accvgpr_write_b32 a67, 0
	v_accvgpr_write_b32 a66, 0
	v_accvgpr_write_b32 a65, 0
	v_accvgpr_write_b32 a64, 0
	v_accvgpr_write_b32 a111, 0
	v_accvgpr_write_b32 a110, 0
	v_accvgpr_write_b32 a109, 0
	v_accvgpr_write_b32 a108, 0
	v_accvgpr_write_b32 a107, 0
	v_accvgpr_write_b32 a106, 0
	v_accvgpr_write_b32 a105, 0
	v_accvgpr_write_b32 a104, 0
	v_accvgpr_write_b32 a103, 0
	v_accvgpr_write_b32 a102, 0
	v_accvgpr_write_b32 a101, 0
	v_accvgpr_write_b32 a100, 0
	v_accvgpr_write_b32 a99, 0
	v_accvgpr_write_b32 a98, 0
	v_accvgpr_write_b32 a97, 0
	v_accvgpr_write_b32 a96, 0
	v_accvgpr_write_b32 a95, 0
	v_accvgpr_write_b32 a94, 0
	v_accvgpr_write_b32 a93, 0
	v_accvgpr_write_b32 a92, 0
	v_accvgpr_write_b32 a91, 0
	v_accvgpr_write_b32 a90, 0
	v_accvgpr_write_b32 a89, 0
	v_accvgpr_write_b32 a88, 0
	v_accvgpr_write_b32 a87, 0
	v_accvgpr_write_b32 a86, 0
	v_accvgpr_write_b32 a85, 0
	v_accvgpr_write_b32 a84, 0
	v_accvgpr_write_b32 a83, 0
	v_accvgpr_write_b32 a82, 0
	v_accvgpr_write_b32 a81, 0
	v_accvgpr_write_b32 a80, 0
	v_accvgpr_write_b32 a127, 0
	v_accvgpr_write_b32 a126, 0
	v_accvgpr_write_b32 a125, 0
	v_accvgpr_write_b32 a124, 0
	v_accvgpr_write_b32 a123, 0
	v_accvgpr_write_b32 a122, 0
	v_accvgpr_write_b32 a121, 0
	v_accvgpr_write_b32 a120, 0
	v_accvgpr_write_b32 a119, 0
	v_accvgpr_write_b32 a118, 0
	v_accvgpr_write_b32 a117, 0
	v_accvgpr_write_b32 a116, 0
	v_accvgpr_write_b32 a115, 0
	v_accvgpr_write_b32 a114, 0
	v_accvgpr_write_b32 a113, 0
	v_accvgpr_write_b32 a112, 0
	v_accvgpr_write_b32 a31, 0
	v_accvgpr_write_b32 a30, 0
	v_accvgpr_write_b32 a29, 0
	v_accvgpr_write_b32 a28, 0
	v_accvgpr_write_b32 a27, 0
	v_accvgpr_write_b32 a26, 0
	v_accvgpr_write_b32 a25, 0
	v_accvgpr_write_b32 a24, 0
	v_accvgpr_write_b32 a23, 0
	v_accvgpr_write_b32 a22, 0
	v_accvgpr_write_b32 a21, 0
	v_accvgpr_write_b32 a20, 0
	v_accvgpr_write_b32 a19, 0
	v_accvgpr_write_b32 a18, 0
	v_accvgpr_write_b32 a17, 0
	v_accvgpr_write_b32 a16, 0
	v_accvgpr_write_b32 a15, 0
	v_accvgpr_write_b32 a14, 0
	v_accvgpr_write_b32 a13, 0
	v_accvgpr_write_b32 a12, 0
	v_accvgpr_write_b32 a11, 0
	v_accvgpr_write_b32 a10, 0
	v_accvgpr_write_b32 a9, 0
	v_accvgpr_write_b32 a8, 0
	v_accvgpr_write_b32 a7, 0
	v_accvgpr_write_b32 a6, 0
	v_accvgpr_write_b32 a5, 0
	v_accvgpr_write_b32 a4, 0
	v_accvgpr_write_b32 a3, 0
	v_accvgpr_write_b32 a2, 0
	v_accvgpr_write_b32 a1, 0
	v_accvgpr_write_b32 a0, 0
	s_mov_b64 s[44:45], 0
	s_waitcnt vmcnt(23)
	ds_write_b128 v45, v[108:111]
	s_waitcnt vmcnt(22)
	ds_write_b128 v45, v[112:115] offset:4608
	s_waitcnt vmcnt(21)
	ds_write_b128 v45, v[116:119] offset:9216
	s_waitcnt vmcnt(20)
	ds_write_b128 v45, v[120:123] offset:13824
	s_waitcnt vmcnt(19)
	ds_write_b128 v45, v[124:127] offset:18432
	s_waitcnt vmcnt(18)
	ds_write_b128 v45, v[128:131] offset:23040
	s_waitcnt vmcnt(17)
	ds_write_b128 v45, v[132:135] offset:27648
	s_waitcnt vmcnt(16)
	ds_write_b128 v45, v[140:143] offset:32256
	s_waitcnt vmcnt(15)
	ds_write_b128 v45, v[144:147] offset:36864
	s_waitcnt vmcnt(14)
	ds_write_b128 v45, v[148:151] offset:41472
	s_waitcnt vmcnt(13)
	ds_write_b128 v45, v[152:155] offset:46080
	s_waitcnt vmcnt(12)
	ds_write_b128 v45, v[156:159] offset:50688
	s_waitcnt lgkmcnt(0)
	s_barrier
	s_waitcnt vmcnt(0)
	v_readfirstlane_b32 s100, v10
	v_readfirstlane_b32 s101, v11
	v_readfirstlane_b32 s98, v12
	v_readfirstlane_b32 s99, v13
	s_nop 1
	v_subrev_u32_e32 v194, s100, v10
	v_subrev_u32_e32 v193, s98, v12
	v_add_u32_e32 v254, s78, v194
	v_add_u32_e32 v205, s79, v194
	v_add_u32_e32 v204, s80, v194
	v_add_u32_e32 v203, s81, v194
	v_add_u32_e32 v202, s82, v194
	v_add_u32_e32 v201, s83, v194
	v_add_u32_e32 v200, s84, v194
	v_add_u32_e32 v199, s85, v194
	v_add_u32_e32 v198, s86, v193
	v_add_u32_e32 v197, s87, v193
	v_add_u32_e32 v196, s88, v193
	v_add_u32_e32 v195, s89, v193
	s_add_u32 s100, s100, s44
	s_addc_u32 s101, s101, s45
	s_add_u32 s98, s98, s44
	s_addc_u32 s99, s99, s45
	v_add_u32_e32 v192, v20, v46
	v_add_u32_e32 v191, v20, v47
	v_add_u32_e32 v190, v20, v48
	s_and_b32 s50, s42, 1
	s_mul_i32 s51, s50, 0xd800
	v_add_u32_e32 v189, s51, v192
	v_add_u32_e32 v188, s51, v191
	v_add_u32_e32 v187, s51, v190
	ds_read_b128 v[108:111], v189
	ds_read_b128 v[14:17], v187 offset:36864
	ds_read_b128 v[112:115], v189 offset:4608
	ds_read_b128 v[64:67], v187 offset:41472
	ds_read_b128 v[116:119], v189 offset:9216
	ds_read_b128 v[120:123], v188
	s_getreg_b32 s50, hwreg(HW_REG_HW_ID, 4, 1)
	s_cmp_lg_u32 s50, 0
	s_cbranch_scc1 xg5_varB_8
	.p2align 6
.LBB0_2449:
	s_and_b32 s50, s42, 1
	s_mul_i32 s51, s50, 0xd800
	s_xor_b32 s50, s50, 1
	s_mul_i32 s50, s50, 0xd800
	s_add_i32 s42, s42, 1
	v_add_u32_e32 v186, s50, v45
	ds_read_b128 v[68:71], v189 offset:32
	ds_read_b128 v[80:83], v187 offset:36896
	ds_read_b128 v[72:75], v189 offset:4640
	ds_read_b128 v[84:87], v187 offset:41504
	ds_read_b128 v[76:79], v189 offset:9248
	ds_read_b128 v[104:107], v188 offset:32
	s_waitcnt lgkmcnt(10)
	v_mfma_f32_32x32x16_bf16 a[32:47], v[108:111], v[14:17], a[32:47]
	s_waitcnt vmcnt(11)
	ds_write_b128 v186, v[250:253]
	s_waitcnt lgkmcnt(9)
	v_mfma_f32_32x32x16_bf16 a[48:63], v[108:111], v[64:67], a[48:63]
	s_waitcnt vmcnt(10)
	ds_write_b128 v186, v[246:249] offset:4608
	global_load_dwordx4 v[250:253], v254, s[100:101] offset:512
	v_mfma_f32_32x32x16_bf16 a[64:79], v[112:115], v[14:17], a[64:79]
	s_waitcnt vmcnt(10)
	ds_write_b128 v186, v[242:245] offset:9216
	global_load_dwordx4 v[246:249], v205, s[100:101] offset:512
	v_mfma_f32_32x32x16_bf16 a[96:111], v[112:115], v[64:67], a[96:111]
	s_waitcnt vmcnt(10)
	ds_write_b128 v186, v[238:241] offset:13824
	global_load_dwordx4 v[242:245], v204, s[100:101] offset:512
	s_waitcnt lgkmcnt(11)
	v_mfma_f32_32x32x16_bf16 a[80:95], v[116:119], v[14:17], a[80:95]
	s_waitcnt vmcnt(10)
	ds_write_b128 v186, v[234:237] offset:18432
	global_load_dwordx4 v[238:241], v203, s[100:101] offset:512
	v_mfma_f32_32x32x16_bf16 a[112:127], v[116:119], v[64:67], a[112:127]
	s_waitcnt vmcnt(10)
	ds_write_b128 v186, v[230:233] offset:23040
	global_load_dwordx4 v[234:237], v202, s[100:101] offset:512
	s_waitcnt lgkmcnt(12)
	v_mfma_f32_32x32x16_bf16 a[16:31], v[120:123], v[14:17], a[16:31]
	s_waitcnt vmcnt(10)
	ds_write_b128 v186, v[226:229] offset:27648
	global_load_dwordx4 v[230:233], v201, s[100:101] offset:512
	v_mfma_f32_32x32x16_bf16 a[0:15], v[120:123], v[64:67], a[0:15]
	s_waitcnt vmcnt(10)
	ds_write_b128 v186, v[222:225] offset:32256
	global_load_dwordx4 v[226:229], v200, s[100:101] offset:512
	ds_read_b128 v[108:111], v189 offset:64
	ds_read_b128 v[14:17], v187 offset:36928
	ds_read_b128 v[112:115], v189 offset:4672
	ds_read_b128 v[64:67], v187 offset:41536
	ds_read_b128 v[116:119], v189 offset:9280
	ds_read_b128 v[120:123], v188 offset:64
	s_waitcnt lgkmcnt(15)
	v_mfma_f32_32x32x16_bf16 a[32:47], v[68:71], v[80:83], a[32:47]
	s_waitcnt vmcnt(10)
	ds_write_b128 v186, v[218:221] offset:36864
	global_load_dwordx4 v[222:225], v199, s[100:101] offset:512
	v_mfma_f32_32x32x16_bf16 a[48:63], v[68:71], v[84:87], a[48:63]
	s_waitcnt vmcnt(10)
	ds_write_b128 v186, v[214:217] offset:41472
	global_load_dwordx4 v[218:221], v198, s[98:99] offset:256
	v_mfma_f32_32x32x16_bf16 a[64:79], v[72:75], v[80:83], a[64:79]
	s_waitcnt vmcnt(10)
	ds_write_b128 v186, v[210:213] offset:46080
	global_load_dwordx4 v[214:217], v197, s[98:99] offset:256
	v_mfma_f32_32x32x16_bf16 a[96:111], v[72:75], v[84:87], a[96:111]
	s_waitcnt vmcnt(10)
	ds_write_b128 v186, v[206:209] offset:50688
	global_load_dwordx4 v[210:213], v196, s[98:99] offset:256
	v_mfma_f32_32x32x16_bf16 a[80:95], v[76:79], v[80:83], a[80:95]
	global_load_dwordx4 v[206:209], v195, s[98:99] offset:256
	s_add_u32 s100, s100, 0x80
	s_addc_u32 s101, s101, 0
	s_add_u32 s98, s98, 0x80
	s_addc_u32 s99, s99, 0
	v_mfma_f32_32x32x16_bf16 a[112:127], v[76:79], v[84:87], a[112:127]
	s_waitcnt lgkmcnt(15)
	v_mfma_f32_32x32x16_bf16 a[16:31], v[104:107], v[80:83], a[16:31]
	v_mfma_f32_32x32x16_bf16 a[0:15], v[104:107], v[84:87], a[0:15]
	ds_read_b128 v[68:71], v189 offset:96
	ds_read_b128 v[80:83], v187 offset:36960
	ds_read_b128 v[72:75], v189 offset:4704
	ds_read_b128 v[84:87], v187 offset:41568
	ds_read_b128 v[76:79], v189 offset:9312
	ds_read_b128 v[104:107], v188 offset:96
	s_waitcnt lgkmcnt(14)
	v_mfma_f32_32x32x16_bf16 a[32:47], v[108:111], v[14:17], a[32:47]
	s_waitcnt lgkmcnt(12)
	v_mfma_f32_32x32x16_bf16 a[48:63], v[108:111], v[64:67], a[48:63]
	v_mfma_f32_32x32x16_bf16 a[64:79], v[112:115], v[14:17], a[64:79]
	v_mfma_f32_32x32x16_bf16 a[96:111], v[112:115], v[64:67], a[96:111]
	s_waitcnt lgkmcnt(11)
	v_mfma_f32_32x32x16_bf16 a[80:95], v[116:119], v[14:17], a[80:95]
	v_mfma_f32_32x32x16_bf16 a[112:127], v[116:119], v[64:67], a[112:127]
	s_waitcnt lgkmcnt(10)
	v_mfma_f32_32x32x16_bf16 a[16:31], v[120:123], v[14:17], a[16:31]
	v_mfma_f32_32x32x16_bf16 a[0:15], v[120:123], v[64:67], a[0:15]
	s_waitcnt lgkmcnt(0)
	v_mfma_f32_32x32x16_bf16 a[32:47], v[68:71], v[80:83], a[32:47]
	v_mfma_f32_32x32x16_bf16 a[48:63], v[68:71], v[84:87], a[48:63]
	v_mfma_f32_32x32x16_bf16 a[64:79], v[72:75], v[80:83], a[64:79]
	v_mfma_f32_32x32x16_bf16 a[96:111], v[72:75], v[84:87], a[96:111]
	s_barrier
	v_add_u32_e32 v189, s50, v192
	v_add_u32_e32 v188, s50, v191
	v_add_u32_e32 v187, s50, v190
	ds_read_b128 v[108:111], v189
	ds_read_b128 v[14:17], v187 offset:36864
	ds_read_b128 v[112:115], v189 offset:4608
	ds_read_b128 v[64:67], v187 offset:41472
	ds_read_b128 v[116:119], v189 offset:9216
	ds_read_b128 v[120:123], v188
	v_mfma_f32_32x32x16_bf16 a[80:95], v[76:79], v[80:83], a[80:95]
	v_mfma_f32_32x32x16_bf16 a[112:127], v[76:79], v[84:87], a[112:127]
	v_mfma_f32_32x32x16_bf16 a[16:31], v[104:107], v[80:83], a[16:31]
	v_mfma_f32_32x32x16_bf16 a[0:15], v[104:107], v[84:87], a[0:15]
	s_add_u32 s44, s44, 0x80
	s_addc_u32 s45, s45, 0
	s_cmpk_lg_i32 s44, 0x700
	s_cbranch_scc1 .LBB0_2449
	s_branch xg5_tail_8
	.p2align 6

.LBB0_2571:
	s_add_i32 s48, s18, 16
	s_cmpk_gt_u32 s18, 0x6f
	s_cselect_b64 s[8:9], -1, 0
	s_cmpk_lt_u32 s18, 0x70
	s_cselect_b64 vcc, -1, 0
	s_bitcmp0_b32 s48, 6
	s_cselect_b64 s[6:7], -1, 0
	v_cndmask_b32_e64 v104, v102, v100, s[6:7]
	v_cndmask_b32_e32 v104, v114, v104, vcc
	s_nop 0
	v_readlane_b32 s20, v104, s48
	s_nop 1
	v_mad_i64_i32 v[202:203], s[6:7], s20, v194, v[96:97]
	global_load_dwordx4 a[8:11], v[202:203], off
	v_mad_i64_i32 v[202:203], s[6:7], s20, v194, v[98:99]
	s_add_i32 s6, s18, 17
	global_load_dwordx2 a[28:29], v[202:203], off
	s_nop 1
	v_readlane_b32 s20, v104, s6
	s_nop 1
	v_mad_i64_i32 v[202:203], s[6:7], s20, v194, v[96:97]
	global_load_dwordx4 v[250:253], v[202:203], off
	v_mad_i64_i32 v[202:203], s[6:7], s20, v194, v[98:99]
	s_add_i32 s6, s18, 18
	global_load_dwordx2 a[30:31], v[202:203], off
	s_nop 1
	v_readlane_b32 s20, v104, s6
	s_nop 1
	v_mad_i64_i32 v[202:203], s[6:7], s20, v194, v[96:97]
	global_load_dwordx4 a[0:3], v[202:203], off
	v_mad_i64_i32 v[202:203], s[6:7], s20, v194, v[98:99]
	s_add_i32 s6, s18, 19
	global_load_dwordx2 a[32:33], v[202:203], off
	s_nop 1
	v_readlane_b32 s20, v104, s6
	s_nop 1
	v_mad_i64_i32 v[202:203], s[6:7], s20, v194, v[96:97]
	global_load_dwordx4 a[4:7], v[202:203], off
	v_mad_i64_i32 v[202:203], s[6:7], s20, v194, v[98:99]
	s_add_i32 s6, s18, 20
	global_load_dwordx2 a[34:35], v[202:203], off
	s_nop 1
	v_readlane_b32 s20, v104, s6
	s_nop 1
	v_mad_i64_i32 v[202:203], s[6:7], s20, v194, v[96:97]
	global_load_dwordx4 v[214:217], v[202:203], off
	v_mad_i64_i32 v[202:203], s[6:7], s20, v194, v[98:99]
	s_add_i32 s6, s18, 21
	global_load_dwordx2 a[36:37], v[202:203], off
	s_nop 1
	v_readlane_b32 s20, v104, s6
	s_nop 1
	v_mad_i64_i32 v[202:203], s[6:7], s20, v194, v[96:97]
	global_load_dwordx4 v[218:221], v[202:203], off
	v_mad_i64_i32 v[202:203], s[6:7], s20, v194, v[98:99]
	s_add_i32 s6, s18, 22
	global_load_dwordx2 a[38:39], v[202:203], off
	s_nop 1
	v_readlane_b32 s20, v104, s6
	s_nop 1
	v_mad_i64_i32 v[202:203], s[6:7], s20, v194, v[96:97]
	global_load_dwordx4 v[222:225], v[202:203], off
	v_mad_i64_i32 v[202:203], s[6:7], s20, v194, v[98:99]
	s_add_i32 s6, s18, 23
	global_load_dwordx2 a[40:41], v[202:203], off
	s_nop 1
	v_readlane_b32 s20, v104, s6
	s_nop 1
	v_mad_i64_i32 v[202:203], s[6:7], s20, v194, v[96:97]
	global_load_dwordx4 v[226:229], v[202:203], off
	v_mad_i64_i32 v[202:203], s[6:7], s20, v194, v[98:99]
	s_add_i32 s6, s18, 24
	global_load_dwordx2 a[42:43], v[202:203], off
	s_nop 1
	v_readlane_b32 s20, v104, s6
	s_nop 1
	v_mad_i64_i32 v[202:203], s[6:7], s20, v194, v[96:97]
	global_load_dwordx4 v[230:233], v[202:203], off
	v_mad_i64_i32 v[202:203], s[6:7], s20, v194, v[98:99]
	s_add_i32 s6, s18, 25
	global_load_dwordx2 a[44:45], v[202:203], off
	s_nop 1
	v_readlane_b32 s20, v104, s6
	s_nop 1
	v_mad_i64_i32 v[202:203], s[6:7], s20, v194, v[96:97]
	global_load_dwordx4 v[234:237], v[202:203], off
	v_mad_i64_i32 v[202:203], s[6:7], s20, v194, v[98:99]
	s_add_i32 s6, s18, 26
	global_load_dwordx2 a[46:47], v[202:203], off
	s_nop 1
	v_readlane_b32 s20, v104, s6
	s_nop 1
	v_mad_i64_i32 v[202:203], s[6:7], s20, v194, v[96:97]
	global_load_dwordx4 v[238:241], v[202:203], off
	v_mad_i64_i32 v[202:203], s[6:7], s20, v194, v[98:99]
	s_add_i32 s6, s18, 27
	global_load_dwordx2 a[48:49], v[202:203], off
	s_nop 1
	v_readlane_b32 s20, v104, s6
	s_nop 1
	v_mad_i64_i32 v[202:203], s[6:7], s20, v194, v[96:97]
	global_load_dwordx4 v[242:245], v[202:203], off
	v_mad_i64_i32 v[202:203], s[6:7], s20, v194, v[98:99]
	s_add_i32 s6, s18, 28
	global_load_dwordx2 a[50:51], v[202:203], off
	s_nop 1
	v_readlane_b32 s20, v104, s6
	s_nop 1
	v_mad_i64_i32 v[202:203], s[6:7], s20, v194, v[96:97]
	global_load_dwordx4 v[246:249], v[202:203], off
	v_mad_i64_i32 v[202:203], s[6:7], s20, v194, v[98:99]
	s_add_i32 s6, s18, 29
	global_load_dwordx2 a[24:25], v[202:203], off
	s_nop 1
	v_readlane_b32 s20, v104, s6
	s_nop 1
	v_mad_i64_i32 v[202:203], s[6:7], s20, v194, v[96:97]
	global_load_dwordx4 v[210:213], v[202:203], off
	v_mad_i64_i32 v[202:203], s[6:7], s20, v194, v[98:99]
	s_add_i32 s6, s18, 30
	global_load_dwordx2 a[22:23], v[202:203], off
	s_nop 1
	v_readlane_b32 s20, v104, s6
	s_nop 1
	v_mad_i64_i32 v[202:203], s[6:7], s20, v194, v[96:97]
	global_load_dwordx4 v[206:209], v[202:203], off
	v_mad_i64_i32 v[202:203], s[6:7], s20, v194, v[98:99]
	s_add_i32 s6, s18, 31
	global_load_dwordx2 a[20:21], v[202:203], off
	s_cmp_lg_u32 s18, 64
	s_nop 0
	v_readlane_b32 s20, v104, s6
	s_nop 1
	v_mad_i64_i32 v[104:105], s[6:7], s20, v194, v[98:99]
	global_load_dwordx2 a[26:27], v[104:105], off
	v_mad_i64_i32 v[202:203], s[6:7], s20, v194, v[96:97]
	global_load_dwordx4 v[202:205], v[202:203], off
	s_cbranch_scc1 .LBB0_2573
	global_load_dword a53, v[144:145], off
	global_load_dword a54, v[142:143], off
	global_load_dword v103, v[140:141], off
	global_load_dword v101, v[138:139], off
	.p2align 6
